# diff-attention KV loop: kpmm/key-position loads hoisted with counted vmcnt (K/V prefetch stays in flight), QK and PV LDS fragment reads pipelined; scan y-reduction as DPP reduce-scatter; prep part (a)
# speedup vs baseline: 1.0701x; 1.0352x over previous
; #define SC_STORE(R, B)                                                \
;   _Pragma("unroll") for (int i = 0; i < 6; ++i) *(f32x4*)(buf + (B) * SC_CH * SC_STEPF + pf[i]) = R[i];
; __device__ __forceinline__ void scan_unit(const Params p, int u, char* smem) {
;     ...
; #pragma unroll
;   for (int i = 0; i < 6; ++i) {
;     int f = min(tid + i * 256, SC_CH * 84 - 1);
;     int st = f / 84, q = f % 84;
;     int a = q >> 4;
;     const float* base = a == 0 ? a0 : a == 1 ? a1 : a == 2 ? a2 : a == 3 ? a3 : a == 4 ? a4 : vsrc;
;     pb[i] = base + (a < 5 ? (q & 15) * 4 : (q - 80) * 4);
;     pst[i] = st;
;     pf[i] = f * 4;
;   }
;   const int sdir = n ? -1 : 1, sbase = n ? (S_ - 1) : 0;
;   const int nch = S_ / SC_CH;
;   unsigned po[6];
; #pragma unroll
;   for (int i = 0; i < 6; ++i)
;     po[i] = (unsigned)((const char*)(pb[i] + (size_t)(sbase + sdir * pst[i]) * 512) - (const char*)ws);
;   const unsigned yo = (unsigned)((const char*)(ydst + (size_t)(sbase + sdir * jg) * 512) - (const char*)ws);
;   const int cstep = sdir * SC_CH * 512 * 4;
;   f32x4 lregA[6], lregB[6];
;     ...
;   f32x2 sA = {0.f, 0.f}, sB = {0.f, 0.f};
;   const int jg4 = jg * 4, vi = w * 4 + rw;
;     ...
;   __syncthreads();
;   __builtin_amdgcn_s_setprio(3);
;   SC_LOAD(lregA, 0);
;   SC_STORE(lregA, 0);
;   SC_LOAD(lregB, 1);
;   __syncthreads();
.LBB0_98:
	s_or_b64 exec, exec, s[24:25]
	v_lshlrev_b32_e32 v11, 2, v27
	v_cmp_gt_i32_e32 vcc, 5, v28
	v_and_b32_e32 v27, 60, v11
	v_add_u32_e32 v11, 0xfffffec0, v11
	v_lshlrev_b32_e32 v24, 2, v24
	v_cndmask_b32_e32 v11, v11, v27, vcc
	v_cmp_gt_i32_e32 vcc, 5, v25
	v_and_b32_e32 v25, 60, v24
	v_add_u32_e32 v24, 0xfffffec0, v24
	v_lshlrev_b32_e32 v21, 2, v21
	v_cndmask_b32_e32 v24, v24, v25, vcc
	v_cmp_gt_i32_e32 vcc, 5, v22
	v_and_b32_e32 v22, 60, v21
	v_add_u32_e32 v21, 0xfffffec0, v21
	v_lshlrev_b32_e32 v18, 2, v18
	s_and_b32 s2, s72, 0x7c0
	v_cndmask_b32_e32 v21, v21, v22, vcc
	v_cmp_gt_i32_e32 vcc, 5, v19
	v_and_b32_e32 v19, 60, v18
	v_add_u32_e32 v18, 0xfffffec0, v18
	v_lshlrev_b32_e32 v15, 2, v15
	s_cmp_lt_u32 s70, 32
	v_cndmask_b32_e32 v18, v18, v19, vcc
	v_cmp_gt_i32_e32 vcc, 5, v16
	v_and_b32_e32 v16, 60, v15
	v_add_u32_e32 v15, 0xfffffec0, v15
	s_cselect_b32 s1, 1, -1
	v_cndmask_b32_e32 v15, v15, v16, vcc
	s_cselect_b32 s3, 0, 0x1fff
	v_mul_lo_u32 v14, v14, s1
	v_lshlrev_b32_e32 v15, 2, v15
	v_add_lshl_u32 v14, v14, s3, 11
	v_add3_u32 v0, v0, v15, v14
	v_subrev_u32_e32 v168, s96, v0
	v_mul_lo_u32 v0, v17, s1
	v_lshlrev_b32_e32 v18, 2, v18
	v_add_lshl_u32 v0, v0, s3, 11
	v_add3_u32 v0, v2, v18, v0
	v_subrev_u32_e32 v116, s96, v0
	v_mul_lo_u32 v0, v20, s1
	v_lshlrev_b32_e32 v21, 2, v21
	v_add_lshl_u32 v0, v0, s3, 11
	v_add3_u32 v0, v4, v21, v0
	v_subrev_u32_e32 v118, s96, v0
	v_mul_lo_u32 v0, v23, s1
	v_lshlrev_b32_e32 v24, 2, v24
	v_add_lshl_u32 v0, v0, s3, 11
	v_add3_u32 v0, v6, v24, v0
	v_subrev_u32_e32 v120, s96, v0
	v_mul_lo_u32 v0, v26, s1
	v_lshlrev_b32_e32 v11, 2, v11
	v_lshlrev_b32_e32 v16, 2, v30
	v_add_lshl_u32 v0, v0, s3, 11
	v_cmp_gt_i32_e32 vcc, 5, v31
	v_and_b32_e32 v19, 60, v16
	v_add_u32_e32 v16, 0xfffffec0, v16
	v_add3_u32 v0, v8, v11, v0
	v_cndmask_b32_e32 v16, v16, v19, vcc
	v_subrev_u32_e32 v122, s96, v0
	v_mul_lo_u32 v0, v29, s1
	v_lshlrev_b32_e32 v16, 2, v16
	v_add_lshl_u32 v0, v0, s3, 11
	v_add3_u32 v0, v10, v16, v0
	v_ashrrev_i32_e32 v38, 4, v13
	v_bfe_u32 v39, v13, 4, 2
	v_subrev_u32_e32 v124, s96, v0
	v_and_b32_e32 v40, 15, v13
	v_mov_b32_e32 v0, s3
	s_lshl_b32 s3, s0, 24
	s_mov_b32 s0, 0x3ffffffc
	v_mad_i32_i24 v41, v40, s1, v0
	v_and_or_b32 v42, v38, s0, v39
	s_barrier
	s_setprio 3
	v_lshl_add_u64 v[10:11], s[96:97], 0, v[168:169]
	v_mov_b32_e32 v117, v169
	global_load_dwordx4 v[14:17], v[10:11], off
	v_lshl_add_u64 v[10:11], s[96:97], 0, v[116:117]
	v_mov_b32_e32 v119, v169
	global_load_dwordx4 v[18:21], v[10:11], off
	v_lshl_add_u64 v[10:11], s[96:97], 0, v[118:119]
	global_load_dwordx4 v[22:25], v[10:11], off
	v_mov_b32_e32 v121, v169
	v_lshl_add_u64 v[10:11], s[96:97], 0, v[120:121]
	v_mov_b32_e32 v123, v169
	global_load_dwordx4 v[26:29], v[10:11], off
	v_lshl_add_u64 v[10:11], s[96:97], 0, v[122:123]
	v_mov_b32_e32 v125, v169
	s_lshl_b32 s0, s1, 15
	v_lshlrev_b32_e32 v117, 4, v12
	v_lshlrev_b32_e32 v119, 4, v1
	global_load_dwordx4 v[30:33], v[10:11], off
	v_lshl_add_u64 v[10:11], s[96:97], 0, v[124:125]
	v_lshlrev_b32_e32 v121, 4, v3
	v_add_u32_e32 v0, s0, v168
	v_add_u32_e32 v4, s0, v116
	v_add_u32_e32 v8, s0, v118
	v_add_u32_e32 v12, s0, v120
	global_load_dwordx4 v[34:37], v[10:11], off
	v_lshlrev_b32_e32 v123, 4, v5
	v_lshlrev_b32_e32 v125, 4, v7
	v_lshlrev_b32_e32 v127, 4, v9
	global_load_dwordx4 v[0:3], v0, s[96:97]
	s_add_i32 s3, s3, 0x31480000
	global_load_dwordx4 v[4:7], v4, s[96:97]
	v_mov_b32_e32 v52, 0
	global_load_dwordx4 v[8:11], v8, s[96:97]
	v_lshlrev_b32_e32 v129, 4, v40
	v_lshlrev_b32_e32 v131, 2, v42
	v_cmp_eq_u32_e32 vcc, 0, v40
	v_cmp_eq_u32_e64 s[38:39], 1, v40
	v_cmp_eq_u32_e64 s[40:41], 2, v40
	v_cmp_eq_u32_e64 s[42:43], 3, v40
	v_cmp_eq_u32_e64 s[44:45], 4, v40
	v_cmp_eq_u32_e64 s[46:47], 5, v40
	v_cmp_eq_u32_e64 s[48:49], 6, v40
	v_cmp_eq_u32_e64 s[50:51], 7, v40
	v_cmp_eq_u32_e64 s[52:53], 8, v40
	v_cmp_eq_u32_e64 s[54:55], 9, v40
	v_cmp_eq_u32_e64 s[56:57], 10, v40
	v_cmp_eq_u32_e64 s[58:59], 11, v40
	v_cmp_eq_u32_e64 s[60:61], 12, v40
	v_cmp_eq_u32_e64 s[62:63], 13, v40
	v_cmp_eq_u32_e64 s[64:65], 14, v40
	v_cmp_eq_u32_e64 s[66:67], 15, v40
	s_lshl_b32 s1, s1, 16
	v_mov_b32_e32 v53, v52
	v_mov_b32_e32 v54, v52
	v_mov_b32_e32 v55, v52
	s_waitcnt vmcnt(8)
	ds_write_b128 v117, v[14:17]
	v_add_u32_e32 v16, s0, v122
	global_load_dwordx4 v[12:15], v12, s[96:97]
	s_waitcnt vmcnt(8)
	ds_write_b128 v119, v[18:21]
	v_add_u32_e32 v20, s0, v124
	s_waitcnt vmcnt(7)
	ds_write_b128 v121, v[22:25]
	global_load_dwordx4 v[16:19], v16, s[96:97]
	v_lshl_add_u32 v24, v41, 11, s3
	global_load_dwordx4 v[20:23], v20, s[96:97]
	v_lshlrev_b32_e32 v25, 2, v38
	v_or_b32_e32 v24, s2, v24
	v_and_b32_e32 v25, -16, v25
	v_add_u32_e32 v24, v24, v25
	v_lshl_or_b32 v132, v39, 2, v24
	s_mov_b32 s3, -2
	s_waitcnt vmcnt(8)
	ds_write_b128 v123, v[26:29]
	s_waitcnt vmcnt(7)
	ds_write_b128 v125, v[30:33]
	s_waitcnt vmcnt(6)
	ds_write_b128 v127, v[34:37]
	s_waitcnt lgkmcnt(0)
	s_barrier
	v_and_b32_e32 v184, 2, v40
	v_cmp_ne_u32_e64 s[38:39], 0, v184
	v_and_b32_e32 v185, 1, v40
	v_cmp_ne_u32_e64 s[40:41], 0, v185
; #define LBAR() asm volatile("s_waitcnt lgkmcnt(0)\n\ts_barrier" ::: "memory")
; #define SC_STORE(R, B)                                                \
;   _Pragma("unroll") for (int i = 0; i < 6; ++i) *(f32x4*)(buf + (B) * SC_CH * SC_STEPF + pf[i]) = R[i];
; __device__ __forceinline__ void scan_unit(const Params p, int u, char* smem) {
;     ...
;   __syncthreads();
;   __builtin_amdgcn_s_setprio(3);
;   SC_LOAD(lregA, 0);
;   SC_STORE(lregA, 0);
;   SC_LOAD(lregB, 1);
;   __syncthreads();
;   for (int c = 0; c < nch; c += 2) {
;     SC_LOAD(lregA, c + 2);
;     SC_COMPUTE(c, 0);
;     SC_STORE(lregB, 1);
;     LBAR();
;     SC_LOAD(lregB, c + 3);
;     SC_COMPUTE(c + 1, 1);
;     SC_STORE(lregA, 0);
;     LBAR();
.LBB0_99:
	ds_read_b128 v[56:59], v129
	ds_read_b128 v[60:63], v129 offset:256
	ds_read_b128 v[64:67], v129 offset:512
	ds_read_b128 v[68:71], v129 offset:768
	ds_read_b128 v[72:75], v129 offset:1024
	ds_read_b32 v76, v131 offset:1280
	ds_read_b128 v[80:83], v129 offset:1344
	ds_read_b128 v[84:87], v129 offset:1600
	ds_read_b128 v[88:91], v129 offset:1856
	ds_read_b128 v[92:95], v129 offset:2112
	ds_read_b128 v[96:99], v129 offset:2368
	ds_read_b32 v100, v131 offset:2624
	s_add_i32 s2, s3, 2
	s_add_i32 s3, s3, 4
	s_min_u32 s3, s3, 0x1ff
	s_mul_i32 s3, s3, s0
	v_add_u32_e32 v112, s3, v168
	v_add_u32_e32 v113, s3, v116
	v_add_u32_e32 v114, s3, v118
	v_add_u32_e32 v115, s3, v120
	v_add_u32_e32 v128, s3, v122
	v_add_u32_e32 v130, s3, v124
	v_pk_mul_f32 v[108:109], v[162:163], v[54:55]
	v_pk_fma_f32 v[108:109], v[160:161], v[52:53], v[108:109]
	v_add_f32_e32 v229, v108, v109
	v_add_f32_dpp v178, v220, v220 row_mirror row_mask:0xf bank_mask:0x3
	v_add_f32_dpp v178, v228, v228 row_mirror row_mask:0xf bank_mask:0xc
	v_add_f32_dpp v179, v221, v221 row_mirror row_mask:0xf bank_mask:0x3
	v_add_f32_dpp v179, v229, v229 row_mirror row_mask:0xf bank_mask:0xc
	v_add_f32_dpp v181, v173, v173 row_half_mirror row_mask:0xf bank_mask:0x5
	v_add_f32_dpp v181, v177, v177 row_half_mirror row_mask:0xf bank_mask:0xa
	v_add_f32_dpp v182, v174, v174 row_half_mirror row_mask:0xf bank_mask:0x5
	v_add_f32_dpp v182, v178, v178 row_half_mirror row_mask:0xf bank_mask:0xa
	v_add_f32_dpp v183, v175, v175 row_half_mirror row_mask:0xf bank_mask:0x5
	v_add_f32_dpp v183, v179, v179 row_half_mirror row_mask:0xf bank_mask:0xa
	v_cndmask_b32_e64 v184, v180, v182, s[38:39]
	v_cndmask_b32_e64 v185, v182, v180, s[38:39]
	global_load_dwordx4 v[28:31], v112, s[96:97]
	global_load_dwordx4 v[32:35], v113, s[96:97]
	v_add_f32_dpp v186, v185, v184 quad_perm:[2,3,0,1] row_mask:0xf bank_mask:0xf bound_ctrl:1
	v_cndmask_b32_e64 v184, v181, v183, s[38:39]
	v_cndmask_b32_e64 v185, v183, v181, s[38:39]
	global_load_dwordx4 v[36:39], v114, s[96:97]
	global_load_dwordx4 v[40:43], v115, s[96:97]
	v_add_f32_dpp v187, v185, v184 quad_perm:[2,3,0,1] row_mask:0xf bank_mask:0xf bound_ctrl:1
	v_cndmask_b32_e64 v184, v186, v187, s[40:41]
	v_cndmask_b32_e64 v185, v187, v186, s[40:41]
	global_load_dwordx4 v[44:47], v128, s[96:97]
	global_load_dwordx4 v[24:27], v130, s[96:97]
	v_add_f32_dpp v110, v185, v184 quad_perm:[1,0,3,2] row_mask:0xf bank_mask:0xf bound_ctrl:1
	s_cmp_eq_u32 s2, 0
	s_cbranch_scc1 .Lscan_skip_first
	global_store_dword v111, v110, s[96:97]
.Lscan_skip_first:
	s_waitcnt lgkmcnt(6)
	v_pk_mul_f32 v[102:103], v[52:53], v[56:57]
	v_pk_fma_f32 v[102:103], v[54:55], v[58:59], v[102:103]
	v_pk_mul_f32 v[104:105], v[68:69], v[76:77] op_sel_hi:[1,0]
	v_add_f32_e32 v102, v102, v103
	v_pk_mul_f32 v[106:107], v[70:71], v[76:77] op_sel_hi:[1,0]
	ds_read_b128 v[136:139], v129 offset:2688
	v_add_f32_dpp v102, v102, v102 quad_perm:[1,0,3,2] row_mask:0xf bank_mask:0xf bound_ctrl:1
	v_pk_fma_f32 v[104:105], v[52:53], v[60:61], v[104:105]
	ds_read_b128 v[140:143], v129 offset:2944
	v_add_f32_dpp v102, v102, v102 quad_perm:[2,3,0,1] row_mask:0xf bank_mask:0xf bound_ctrl:1
	v_pk_fma_f32 v[106:107], v[54:55], v[62:63], v[106:107]
	ds_read_b128 v[144:147], v129 offset:3200
	v_add_f32_dpp v102, v102, v102 row_half_mirror row_mask:0xf bank_mask:0xf bound_ctrl:1
	ds_read_b128 v[148:151], v129 offset:3456
	ds_read_b128 v[152:155], v129 offset:3712
	v_add_f32_dpp v102, v102, v102 row_mirror row_mask:0xf bank_mask:0xf bound_ctrl:1
	v_pk_fma_f32 v[52:53], v[64:65], v[102:103], v[104:105] op_sel_hi:[1,0,1] neg_lo:[0,1,0] neg_hi:[0,1,0]
	v_pk_fma_f32 v[54:55], v[66:67], v[102:103], v[106:107] op_sel_hi:[1,0,1] neg_lo:[0,1,0] neg_hi:[0,1,0]
	ds_read_b32 v156, v131 offset:3968
	s_waitcnt lgkmcnt(6)
	v_pk_mul_f32 v[102:103], v[52:53], v[80:81]
	v_pk_mul_f32 v[108:109], v[74:75], v[54:55]
	v_pk_fma_f32 v[102:103], v[54:55], v[82:83], v[102:103]
	v_pk_fma_f32 v[108:109], v[72:73], v[52:53], v[108:109]
	v_pk_mul_f32 v[104:105], v[92:93], v[100:101] op_sel_hi:[1,0]
	v_add_f32_e32 v102, v102, v103
	v_add_f32_e32 v214, v108, v109
	v_pk_mul_f32 v[106:107], v[94:95], v[100:101] op_sel_hi:[1,0]
	v_add_f32_dpp v102, v102, v102 quad_perm:[1,0,3,2] row_mask:0xf bank_mask:0xf bound_ctrl:1
	v_pk_fma_f32 v[104:105], v[52:53], v[84:85], v[104:105]
	ds_read_b128 v[56:59], v129 offset:4032
	v_add_f32_dpp v102, v102, v102 quad_perm:[2,3,0,1] row_mask:0xf bank_mask:0xf bound_ctrl:1
	v_pk_fma_f32 v[106:107], v[54:55], v[86:87], v[106:107]
	ds_read_b128 v[60:63], v129 offset:4288
	v_add_f32_dpp v102, v102, v102 row_half_mirror row_mask:0xf bank_mask:0xf bound_ctrl:1
	ds_read_b128 v[64:67], v129 offset:4544
	ds_read_b128 v[68:71], v129 offset:4800
	v_add_f32_dpp v102, v102, v102 row_mirror row_mask:0xf bank_mask:0xf bound_ctrl:1
	v_pk_fma_f32 v[52:53], v[88:89], v[102:103], v[104:105] op_sel_hi:[1,0,1] neg_lo:[0,1,0] neg_hi:[0,1,0]
	v_pk_fma_f32 v[54:55], v[90:91], v[102:103], v[106:107] op_sel_hi:[1,0,1] neg_lo:[0,1,0] neg_hi:[0,1,0]
	ds_read_b128 v[72:75], v129 offset:5056
	ds_read_b32 v76, v131 offset:5312
	s_waitcnt lgkmcnt(6)
	v_pk_mul_f32 v[102:103], v[52:53], v[136:137]
	v_pk_mul_f32 v[108:109], v[98:99], v[54:55]
	v_pk_fma_f32 v[102:103], v[54:55], v[138:139], v[102:103]
	v_pk_fma_f32 v[108:109], v[96:97], v[52:53], v[108:109]
	v_pk_mul_f32 v[104:105], v[148:149], v[156:157] op_sel_hi:[1,0]
	v_add_f32_e32 v102, v102, v103
	v_add_f32_e32 v215, v108, v109
	v_pk_mul_f32 v[106:107], v[150:151], v[156:157] op_sel_hi:[1,0]
	v_add_f32_dpp v102, v102, v102 quad_perm:[1,0,3,2] row_mask:0xf bank_mask:0xf bound_ctrl:1
	v_pk_fma_f32 v[104:105], v[52:53], v[140:141], v[104:105]
	ds_read_b128 v[80:83], v129 offset:5376
	v_add_f32_dpp v102, v102, v102 quad_perm:[2,3,0,1] row_mask:0xf bank_mask:0xf bound_ctrl:1
	v_pk_fma_f32 v[106:107], v[54:55], v[142:143], v[106:107]
	ds_read_b128 v[84:87], v129 offset:5632
	v_add_f32_dpp v102, v102, v102 row_half_mirror row_mask:0xf bank_mask:0xf bound_ctrl:1
	ds_read_b128 v[88:91], v129 offset:5888
	ds_read_b128 v[92:95], v129 offset:6144
	v_add_f32_dpp v102, v102, v102 row_mirror row_mask:0xf bank_mask:0xf bound_ctrl:1
	v_pk_fma_f32 v[52:53], v[144:145], v[102:103], v[104:105] op_sel_hi:[1,0,1] neg_lo:[0,1,0] neg_hi:[0,1,0]
	v_pk_fma_f32 v[54:55], v[146:147], v[102:103], v[106:107] op_sel_hi:[1,0,1] neg_lo:[0,1,0] neg_hi:[0,1,0]
	ds_read_b128 v[96:99], v129 offset:6400
	ds_read_b32 v100, v131 offset:6656
	s_waitcnt lgkmcnt(6)
	v_pk_mul_f32 v[102:103], v[52:53], v[56:57]
	v_pk_mul_f32 v[108:109], v[154:155], v[54:55]
	v_pk_fma_f32 v[102:103], v[54:55], v[58:59], v[102:103]
	v_pk_fma_f32 v[108:109], v[152:153], v[52:53], v[108:109]
	v_pk_mul_f32 v[104:105], v[68:69], v[76:77] op_sel_hi:[1,0]
	v_add_f32_e32 v102, v102, v103
	v_add_f32_e32 v216, v108, v109
	v_pk_mul_f32 v[106:107], v[70:71], v[76:77] op_sel_hi:[1,0]
	v_add_f32_dpp v102, v102, v102 quad_perm:[1,0,3,2] row_mask:0xf bank_mask:0xf bound_ctrl:1
	v_pk_fma_f32 v[104:105], v[52:53], v[60:61], v[104:105]
	ds_read_b128 v[136:139], v129 offset:6720
	v_add_f32_dpp v102, v102, v102 quad_perm:[2,3,0,1] row_mask:0xf bank_mask:0xf bound_ctrl:1
	v_pk_fma_f32 v[106:107], v[54:55], v[62:63], v[106:107]
	ds_read_b128 v[140:143], v129 offset:6976
	v_add_f32_dpp v102, v102, v102 row_half_mirror row_mask:0xf bank_mask:0xf bound_ctrl:1
	ds_read_b128 v[144:147], v129 offset:7232
	ds_read_b128 v[148:151], v129 offset:7488
	v_add_f32_dpp v102, v102, v102 row_mirror row_mask:0xf bank_mask:0xf bound_ctrl:1
	v_pk_fma_f32 v[52:53], v[64:65], v[102:103], v[104:105] op_sel_hi:[1,0,1] neg_lo:[0,1,0] neg_hi:[0,1,0]
	v_pk_fma_f32 v[54:55], v[66:67], v[102:103], v[106:107] op_sel_hi:[1,0,1] neg_lo:[0,1,0] neg_hi:[0,1,0]
	ds_read_b128 v[152:155], v129 offset:7744
	ds_read_b32 v156, v131 offset:8000
	s_waitcnt lgkmcnt(6)
	v_pk_mul_f32 v[102:103], v[52:53], v[80:81]
	v_pk_mul_f32 v[108:109], v[74:75], v[54:55]
	v_pk_fma_f32 v[102:103], v[54:55], v[82:83], v[102:103]
	v_pk_fma_f32 v[108:109], v[72:73], v[52:53], v[108:109]
	v_pk_mul_f32 v[104:105], v[92:93], v[100:101] op_sel_hi:[1,0]
	v_add_f32_e32 v102, v102, v103
	v_add_f32_e32 v217, v108, v109
	v_pk_mul_f32 v[106:107], v[94:95], v[100:101] op_sel_hi:[1,0]
	v_add_f32_dpp v102, v102, v102 quad_perm:[1,0,3,2] row_mask:0xf bank_mask:0xf bound_ctrl:1
	v_pk_fma_f32 v[104:105], v[52:53], v[84:85], v[104:105]
	ds_read_b128 v[56:59], v129 offset:8064
	v_add_f32_dpp v102, v102, v102 quad_perm:[2,3,0,1] row_mask:0xf bank_mask:0xf bound_ctrl:1
	v_pk_fma_f32 v[106:107], v[54:55], v[86:87], v[106:107]
	ds_read_b128 v[60:63], v129 offset:8320
	v_add_f32_dpp v102, v102, v102 row_half_mirror row_mask:0xf bank_mask:0xf bound_ctrl:1
	ds_read_b128 v[64:67], v129 offset:8576
	ds_read_b128 v[68:71], v129 offset:8832
	v_add_f32_dpp v102, v102, v102 row_mirror row_mask:0xf bank_mask:0xf bound_ctrl:1
	v_pk_fma_f32 v[52:53], v[88:89], v[102:103], v[104:105] op_sel_hi:[1,0,1] neg_lo:[0,1,0] neg_hi:[0,1,0]
	v_pk_fma_f32 v[54:55], v[90:91], v[102:103], v[106:107] op_sel_hi:[1,0,1] neg_lo:[0,1,0] neg_hi:[0,1,0]
	ds_read_b128 v[72:75], v129 offset:9088
	ds_read_b32 v76, v131 offset:9344
	s_waitcnt lgkmcnt(6)
	v_pk_mul_f32 v[102:103], v[52:53], v[136:137]
	v_pk_mul_f32 v[108:109], v[98:99], v[54:55]
	v_pk_fma_f32 v[102:103], v[54:55], v[138:139], v[102:103]
	v_pk_fma_f32 v[108:109], v[96:97], v[52:53], v[108:109]
	v_pk_mul_f32 v[104:105], v[148:149], v[156:157] op_sel_hi:[1,0]
	v_add_f32_e32 v102, v102, v103
	v_add_f32_e32 v218, v108, v109
	v_pk_mul_f32 v[106:107], v[150:151], v[156:157] op_sel_hi:[1,0]
	v_add_f32_dpp v102, v102, v102 quad_perm:[1,0,3,2] row_mask:0xf bank_mask:0xf bound_ctrl:1
	v_pk_fma_f32 v[104:105], v[52:53], v[140:141], v[104:105]
	ds_read_b128 v[80:83], v129 offset:9408
	v_add_f32_dpp v102, v102, v102 quad_perm:[2,3,0,1] row_mask:0xf bank_mask:0xf bound_ctrl:1
	v_pk_fma_f32 v[106:107], v[54:55], v[142:143], v[106:107]
	ds_read_b128 v[84:87], v129 offset:9664
	v_add_f32_dpp v102, v102, v102 row_half_mirror row_mask:0xf bank_mask:0xf bound_ctrl:1
	ds_read_b128 v[88:91], v129 offset:9920
	ds_read_b128 v[92:95], v129 offset:10176
	v_add_f32_dpp v102, v102, v102 row_mirror row_mask:0xf bank_mask:0xf bound_ctrl:1
	v_pk_fma_f32 v[52:53], v[144:145], v[102:103], v[104:105] op_sel_hi:[1,0,1] neg_lo:[0,1,0] neg_hi:[0,1,0]
	v_pk_fma_f32 v[54:55], v[146:147], v[102:103], v[106:107] op_sel_hi:[1,0,1] neg_lo:[0,1,0] neg_hi:[0,1,0]
	ds_read_b128 v[96:99], v129 offset:10432
	ds_read_b32 v100, v131 offset:10688
	s_waitcnt lgkmcnt(6)
	v_pk_mul_f32 v[102:103], v[52:53], v[56:57]
	v_pk_mul_f32 v[108:109], v[154:155], v[54:55]
	v_pk_fma_f32 v[102:103], v[54:55], v[58:59], v[102:103]
	v_pk_fma_f32 v[108:109], v[152:153], v[52:53], v[108:109]
	v_pk_mul_f32 v[104:105], v[68:69], v[76:77] op_sel_hi:[1,0]
	v_add_f32_e32 v102, v102, v103
	v_add_f32_e32 v219, v108, v109
	v_pk_mul_f32 v[106:107], v[70:71], v[76:77] op_sel_hi:[1,0]
	v_add_f32_dpp v102, v102, v102 quad_perm:[1,0,3,2] row_mask:0xf bank_mask:0xf bound_ctrl:1
	v_pk_fma_f32 v[104:105], v[52:53], v[60:61], v[104:105]
	ds_read_b128 v[136:139], v129 offset:10752
	v_add_f32_dpp v102, v102, v102 quad_perm:[2,3,0,1] row_mask:0xf bank_mask:0xf bound_ctrl:1
	v_pk_fma_f32 v[106:107], v[54:55], v[62:63], v[106:107]
	ds_read_b128 v[140:143], v129 offset:11008
	v_add_f32_dpp v102, v102, v102 row_half_mirror row_mask:0xf bank_mask:0xf bound_ctrl:1
	ds_read_b128 v[144:147], v129 offset:11264
	ds_read_b128 v[148:151], v129 offset:11520
	v_add_f32_dpp v102, v102, v102 row_mirror row_mask:0xf bank_mask:0xf bound_ctrl:1
	v_pk_fma_f32 v[52:53], v[64:65], v[102:103], v[104:105] op_sel_hi:[1,0,1] neg_lo:[0,1,0] neg_hi:[0,1,0]
	v_pk_fma_f32 v[54:55], v[66:67], v[102:103], v[106:107] op_sel_hi:[1,0,1] neg_lo:[0,1,0] neg_hi:[0,1,0]
	ds_read_b128 v[152:155], v129 offset:11776
	ds_read_b32 v156, v131 offset:12032
	s_waitcnt lgkmcnt(6)
	v_pk_mul_f32 v[102:103], v[52:53], v[80:81]
	v_pk_mul_f32 v[108:109], v[74:75], v[54:55]
	v_pk_fma_f32 v[102:103], v[54:55], v[82:83], v[102:103]
	v_pk_fma_f32 v[108:109], v[72:73], v[52:53], v[108:109]
	v_pk_mul_f32 v[104:105], v[92:93], v[100:101] op_sel_hi:[1,0]
	v_add_f32_e32 v102, v102, v103
	v_add_f32_e32 v220, v108, v109
	v_pk_mul_f32 v[106:107], v[94:95], v[100:101] op_sel_hi:[1,0]
	v_add_f32_dpp v102, v102, v102 quad_perm:[1,0,3,2] row_mask:0xf bank_mask:0xf bound_ctrl:1
	v_pk_fma_f32 v[104:105], v[52:53], v[84:85], v[104:105]
	ds_read_b128 v[56:59], v129 offset:12096
	v_add_f32_dpp v102, v102, v102 quad_perm:[2,3,0,1] row_mask:0xf bank_mask:0xf bound_ctrl:1
	v_pk_fma_f32 v[106:107], v[54:55], v[86:87], v[106:107]
	ds_read_b128 v[60:63], v129 offset:12352
	v_add_f32_dpp v102, v102, v102 row_half_mirror row_mask:0xf bank_mask:0xf bound_ctrl:1
	ds_read_b128 v[64:67], v129 offset:12608
	ds_read_b128 v[68:71], v129 offset:12864
	v_add_f32_dpp v102, v102, v102 row_mirror row_mask:0xf bank_mask:0xf bound_ctrl:1
	v_pk_fma_f32 v[52:53], v[88:89], v[102:103], v[104:105] op_sel_hi:[1,0,1] neg_lo:[0,1,0] neg_hi:[0,1,0]
	v_pk_fma_f32 v[54:55], v[90:91], v[102:103], v[106:107] op_sel_hi:[1,0,1] neg_lo:[0,1,0] neg_hi:[0,1,0]
	ds_read_b128 v[72:75], v129 offset:13120
	ds_read_b32 v76, v131 offset:13376
	s_waitcnt lgkmcnt(6)
	v_pk_mul_f32 v[102:103], v[52:53], v[136:137]
	v_pk_mul_f32 v[108:109], v[98:99], v[54:55]
	v_pk_fma_f32 v[102:103], v[54:55], v[138:139], v[102:103]
	v_pk_fma_f32 v[108:109], v[96:97], v[52:53], v[108:109]
	v_pk_mul_f32 v[104:105], v[148:149], v[156:157] op_sel_hi:[1,0]
	v_add_f32_e32 v102, v102, v103
	v_add_f32_e32 v221, v108, v109
	v_pk_mul_f32 v[106:107], v[150:151], v[156:157] op_sel_hi:[1,0]
	v_add_f32_dpp v102, v102, v102 quad_perm:[1,0,3,2] row_mask:0xf bank_mask:0xf bound_ctrl:1
	v_pk_fma_f32 v[104:105], v[52:53], v[140:141], v[104:105]
	ds_read_b128 v[80:83], v129 offset:13440
	v_add_f32_dpp v102, v102, v102 quad_perm:[2,3,0,1] row_mask:0xf bank_mask:0xf bound_ctrl:1
	v_pk_fma_f32 v[106:107], v[54:55], v[142:143], v[106:107]
	ds_read_b128 v[84:87], v129 offset:13696
	v_add_f32_dpp v102, v102, v102 row_half_mirror row_mask:0xf bank_mask:0xf bound_ctrl:1
	ds_read_b128 v[88:91], v129 offset:13952
	ds_read_b128 v[92:95], v129 offset:14208
	v_add_f32_dpp v102, v102, v102 row_mirror row_mask:0xf bank_mask:0xf bound_ctrl:1
	v_pk_fma_f32 v[52:53], v[144:145], v[102:103], v[104:105] op_sel_hi:[1,0,1] neg_lo:[0,1,0] neg_hi:[0,1,0]
	v_pk_fma_f32 v[54:55], v[146:147], v[102:103], v[106:107] op_sel_hi:[1,0,1] neg_lo:[0,1,0] neg_hi:[0,1,0]
	ds_read_b128 v[96:99], v129 offset:14464
	ds_read_b32 v100, v131 offset:14720
	s_waitcnt vmcnt(11)
	ds_write_b128 v117, v[0:3] offset:21504
	s_waitcnt lgkmcnt(7)
	v_pk_mul_f32 v[102:103], v[52:53], v[56:57]
	v_pk_mul_f32 v[108:109], v[154:155], v[54:55]
	v_pk_fma_f32 v[102:103], v[54:55], v[58:59], v[102:103]
	v_pk_fma_f32 v[108:109], v[152:153], v[52:53], v[108:109]
	v_pk_mul_f32 v[104:105], v[68:69], v[76:77] op_sel_hi:[1,0]
	v_add_f32_e32 v102, v102, v103
	v_add_f32_e32 v222, v108, v109
	v_pk_mul_f32 v[106:107], v[70:71], v[76:77] op_sel_hi:[1,0]
	v_add_f32_dpp v102, v102, v102 quad_perm:[1,0,3,2] row_mask:0xf bank_mask:0xf bound_ctrl:1
	v_pk_fma_f32 v[104:105], v[52:53], v[60:61], v[104:105]
	ds_read_b128 v[136:139], v129 offset:14784
	v_add_f32_dpp v102, v102, v102 quad_perm:[2,3,0,1] row_mask:0xf bank_mask:0xf bound_ctrl:1
	v_pk_fma_f32 v[106:107], v[54:55], v[62:63], v[106:107]
	ds_read_b128 v[140:143], v129 offset:15040
	v_add_f32_dpp v102, v102, v102 row_half_mirror row_mask:0xf bank_mask:0xf bound_ctrl:1
	ds_read_b128 v[144:147], v129 offset:15296
	ds_read_b128 v[148:151], v129 offset:15552
	v_add_f32_dpp v102, v102, v102 row_mirror row_mask:0xf bank_mask:0xf bound_ctrl:1
	v_pk_fma_f32 v[52:53], v[64:65], v[102:103], v[104:105] op_sel_hi:[1,0,1] neg_lo:[0,1,0] neg_hi:[0,1,0]
	v_pk_fma_f32 v[54:55], v[66:67], v[102:103], v[106:107] op_sel_hi:[1,0,1] neg_lo:[0,1,0] neg_hi:[0,1,0]
	ds_read_b128 v[152:155], v129 offset:15808
	ds_read_b32 v156, v131 offset:16064
	s_waitcnt vmcnt(10)
	ds_write_b128 v119, v[4:7] offset:21504
	s_waitcnt lgkmcnt(8)
; #define SC_STORE(R, B)                                                \
;   _Pragma("unroll") for (int i = 0; i < 6; ++i) *(f32x4*)(buf + (B) * SC_CH * SC_STEPF + pf[i]) = R[i];
; __device__ __forceinline__ void scan_unit(const Params p, int u, char* smem) {
;     ...
;   __syncthreads();
;   __builtin_amdgcn_s_setprio(3);
;   SC_LOAD(lregA, 0);
;   SC_STORE(lregA, 0);
;   SC_LOAD(lregB, 1);
;   __syncthreads();
;   for (int c = 0; c < nch; c += 2) {
;     SC_LOAD(lregA, c + 2);
;     SC_COMPUTE(c, 0);
;     SC_STORE(lregB, 1);
	v_pk_mul_f32 v[102:103], v[52:53], v[80:81]
	v_pk_mul_f32 v[108:109], v[74:75], v[54:55]
	v_pk_fma_f32 v[102:103], v[54:55], v[82:83], v[102:103]
	v_pk_fma_f32 v[108:109], v[72:73], v[52:53], v[108:109]
	v_pk_mul_f32 v[104:105], v[92:93], v[100:101] op_sel_hi:[1,0]
	v_add_f32_e32 v102, v102, v103
	v_add_f32_e32 v223, v108, v109
	v_pk_mul_f32 v[106:107], v[94:95], v[100:101] op_sel_hi:[1,0]
	v_add_f32_dpp v102, v102, v102 quad_perm:[1,0,3,2] row_mask:0xf bank_mask:0xf bound_ctrl:1
	v_pk_fma_f32 v[104:105], v[52:53], v[84:85], v[104:105]
	v_add_f32_dpp v172, v214, v214 row_mirror row_mask:0xf bank_mask:0x3
	v_add_f32_dpp v102, v102, v102 quad_perm:[2,3,0,1] row_mask:0xf bank_mask:0xf bound_ctrl:1
	v_pk_fma_f32 v[106:107], v[54:55], v[86:87], v[106:107]
	v_add_f32_dpp v172, v222, v222 row_mirror row_mask:0xf bank_mask:0xc
	v_add_f32_dpp v102, v102, v102 row_half_mirror row_mask:0xf bank_mask:0xf bound_ctrl:1
	ds_read_b128 v[56:59], v129 offset:16128
	ds_read_b128 v[60:63], v129 offset:16384
	v_add_f32_dpp v102, v102, v102 row_mirror row_mask:0xf bank_mask:0xf bound_ctrl:1
	v_pk_fma_f32 v[52:53], v[88:89], v[102:103], v[104:105] op_sel_hi:[1,0,1] neg_lo:[0,1,0] neg_hi:[0,1,0]
	v_pk_fma_f32 v[54:55], v[90:91], v[102:103], v[106:107] op_sel_hi:[1,0,1] neg_lo:[0,1,0] neg_hi:[0,1,0]
	ds_read_b128 v[64:67], v129 offset:16640
	ds_read_b128 v[68:71], v129 offset:16896
	ds_read_b128 v[72:75], v129 offset:17152
	ds_read_b32 v76, v131 offset:17408
	s_waitcnt vmcnt(9)
	ds_write_b128 v121, v[8:11] offset:21504
	s_waitcnt lgkmcnt(8)
	v_pk_mul_f32 v[102:103], v[52:53], v[136:137]
	v_pk_mul_f32 v[108:109], v[98:99], v[54:55]
	v_pk_fma_f32 v[102:103], v[54:55], v[138:139], v[102:103]
	v_pk_fma_f32 v[108:109], v[96:97], v[52:53], v[108:109]
	v_pk_mul_f32 v[104:105], v[148:149], v[156:157] op_sel_hi:[1,0]
	v_add_f32_e32 v102, v102, v103
	v_add_f32_e32 v224, v108, v109
	v_pk_mul_f32 v[106:107], v[150:151], v[156:157] op_sel_hi:[1,0]
	v_add_f32_dpp v102, v102, v102 quad_perm:[1,0,3,2] row_mask:0xf bank_mask:0xf bound_ctrl:1
	v_pk_fma_f32 v[104:105], v[52:53], v[140:141], v[104:105]
	v_add_f32_dpp v173, v215, v215 row_mirror row_mask:0xf bank_mask:0x3
	v_add_f32_dpp v102, v102, v102 quad_perm:[2,3,0,1] row_mask:0xf bank_mask:0xf bound_ctrl:1
	v_pk_fma_f32 v[106:107], v[54:55], v[142:143], v[106:107]
	v_add_f32_dpp v173, v223, v223 row_mirror row_mask:0xf bank_mask:0xc
	v_add_f32_dpp v102, v102, v102 row_half_mirror row_mask:0xf bank_mask:0xf bound_ctrl:1
	ds_read_b128 v[80:83], v129 offset:17472
	ds_read_b128 v[84:87], v129 offset:17728
	v_add_f32_dpp v102, v102, v102 row_mirror row_mask:0xf bank_mask:0xf bound_ctrl:1
	v_pk_fma_f32 v[52:53], v[144:145], v[102:103], v[104:105] op_sel_hi:[1,0,1] neg_lo:[0,1,0] neg_hi:[0,1,0]
	v_pk_fma_f32 v[54:55], v[146:147], v[102:103], v[106:107] op_sel_hi:[1,0,1] neg_lo:[0,1,0] neg_hi:[0,1,0]
	ds_read_b128 v[88:91], v129 offset:17984
	ds_read_b128 v[92:95], v129 offset:18240
	ds_read_b128 v[96:99], v129 offset:18496
	ds_read_b32 v100, v131 offset:18752
	s_waitcnt vmcnt(8)
	ds_write_b128 v123, v[12:15] offset:21504
	s_waitcnt lgkmcnt(8)
	v_pk_mul_f32 v[102:103], v[52:53], v[56:57]
	v_pk_mul_f32 v[108:109], v[154:155], v[54:55]
	v_pk_fma_f32 v[102:103], v[54:55], v[58:59], v[102:103]
	v_pk_fma_f32 v[108:109], v[152:153], v[52:53], v[108:109]
	v_pk_mul_f32 v[104:105], v[68:69], v[76:77] op_sel_hi:[1,0]
	v_add_f32_e32 v102, v102, v103
	v_add_f32_e32 v225, v108, v109
	v_pk_mul_f32 v[106:107], v[70:71], v[76:77] op_sel_hi:[1,0]
	v_add_f32_dpp v102, v102, v102 quad_perm:[1,0,3,2] row_mask:0xf bank_mask:0xf bound_ctrl:1
	v_pk_fma_f32 v[104:105], v[52:53], v[60:61], v[104:105]
	v_add_f32_dpp v174, v216, v216 row_mirror row_mask:0xf bank_mask:0x3
	v_add_f32_dpp v102, v102, v102 quad_perm:[2,3,0,1] row_mask:0xf bank_mask:0xf bound_ctrl:1
	v_pk_fma_f32 v[106:107], v[54:55], v[62:63], v[106:107]
	v_add_f32_dpp v174, v224, v224 row_mirror row_mask:0xf bank_mask:0xc
	v_add_f32_dpp v102, v102, v102 row_half_mirror row_mask:0xf bank_mask:0xf bound_ctrl:1
	ds_read_b128 v[136:139], v129 offset:18816
	ds_read_b128 v[140:143], v129 offset:19072
	v_add_f32_dpp v102, v102, v102 row_mirror row_mask:0xf bank_mask:0xf bound_ctrl:1
	v_pk_fma_f32 v[52:53], v[64:65], v[102:103], v[104:105] op_sel_hi:[1,0,1] neg_lo:[0,1,0] neg_hi:[0,1,0]
	v_pk_fma_f32 v[54:55], v[66:67], v[102:103], v[106:107] op_sel_hi:[1,0,1] neg_lo:[0,1,0] neg_hi:[0,1,0]
	ds_read_b128 v[144:147], v129 offset:19328
	ds_read_b128 v[148:151], v129 offset:19584
	ds_read_b128 v[152:155], v129 offset:19840
	ds_read_b32 v156, v131 offset:20096
	s_waitcnt vmcnt(7)
	ds_write_b128 v125, v[16:19] offset:21504
	s_waitcnt lgkmcnt(8)
	v_pk_mul_f32 v[102:103], v[52:53], v[80:81]
	v_pk_mul_f32 v[108:109], v[74:75], v[54:55]
	v_pk_fma_f32 v[102:103], v[54:55], v[82:83], v[102:103]
	v_pk_fma_f32 v[108:109], v[72:73], v[52:53], v[108:109]
	v_pk_mul_f32 v[104:105], v[92:93], v[100:101] op_sel_hi:[1,0]
	v_add_f32_e32 v102, v102, v103
	v_add_f32_e32 v226, v108, v109
	v_pk_mul_f32 v[106:107], v[94:95], v[100:101] op_sel_hi:[1,0]
	v_add_f32_dpp v102, v102, v102 quad_perm:[1,0,3,2] row_mask:0xf bank_mask:0xf bound_ctrl:1
	v_pk_fma_f32 v[104:105], v[52:53], v[84:85], v[104:105]
	v_add_f32_dpp v175, v217, v217 row_mirror row_mask:0xf bank_mask:0x3
	v_add_f32_dpp v102, v102, v102 quad_perm:[2,3,0,1] row_mask:0xf bank_mask:0xf bound_ctrl:1
	v_pk_fma_f32 v[106:107], v[54:55], v[86:87], v[106:107]
	v_add_f32_dpp v175, v225, v225 row_mirror row_mask:0xf bank_mask:0xc
	v_add_f32_dpp v102, v102, v102 row_half_mirror row_mask:0xf bank_mask:0xf bound_ctrl:1
	ds_read_b128 v[56:59], v129 offset:20160
	ds_read_b128 v[60:63], v129 offset:20416
	v_add_f32_dpp v102, v102, v102 row_mirror row_mask:0xf bank_mask:0xf bound_ctrl:1
	v_pk_fma_f32 v[52:53], v[88:89], v[102:103], v[104:105] op_sel_hi:[1,0,1] neg_lo:[0,1,0] neg_hi:[0,1,0]
	v_pk_fma_f32 v[54:55], v[90:91], v[102:103], v[106:107] op_sel_hi:[1,0,1] neg_lo:[0,1,0] neg_hi:[0,1,0]
	ds_read_b128 v[64:67], v129 offset:20672
	ds_read_b128 v[68:71], v129 offset:20928
	ds_read_b128 v[160:163], v129 offset:21184
	ds_read_b32 v76, v131 offset:21440
	s_waitcnt vmcnt(6)
; #define LBAR() asm volatile("s_waitcnt lgkmcnt(0)\n\ts_barrier" ::: "memory")
; #define SC_STORE(R, B)                                                \
;   _Pragma("unroll") for (int i = 0; i < 6; ++i) *(f32x4*)(buf + (B) * SC_CH * SC_STEPF + pf[i]) = R[i];
; __device__ __forceinline__ void scan_unit(const Params p, int u, char* smem) {
;     ...
;   __syncthreads();
;   __builtin_amdgcn_s_setprio(3);
;   SC_LOAD(lregA, 0);
;   SC_STORE(lregA, 0);
;   SC_LOAD(lregB, 1);
;   __syncthreads();
;   for (int c = 0; c < nch; c += 2) {
;     SC_LOAD(lregA, c + 2);
;     SC_COMPUTE(c, 0);
;     SC_STORE(lregB, 1);
;     LBAR();
;     SC_LOAD(lregB, c + 3);
;     SC_COMPUTE(c + 1, 1);
;     SC_STORE(lregA, 0);
;     LBAR();
	ds_write_b128 v127, v[20:23] offset:21504
	s_waitcnt lgkmcnt(8)
	v_pk_mul_f32 v[102:103], v[52:53], v[136:137]
	v_pk_mul_f32 v[108:109], v[98:99], v[54:55]
	v_pk_fma_f32 v[102:103], v[54:55], v[138:139], v[102:103]
	v_pk_fma_f32 v[108:109], v[96:97], v[52:53], v[108:109]
	v_pk_mul_f32 v[104:105], v[148:149], v[156:157] op_sel_hi:[1,0]
	v_add_f32_e32 v102, v102, v103
	v_add_f32_e32 v227, v108, v109
	v_pk_mul_f32 v[106:107], v[150:151], v[156:157] op_sel_hi:[1,0]
	v_add_f32_dpp v102, v102, v102 quad_perm:[1,0,3,2] row_mask:0xf bank_mask:0xf bound_ctrl:1
	v_pk_fma_f32 v[104:105], v[52:53], v[140:141], v[104:105]
	v_add_f32_dpp v176, v218, v218 row_mirror row_mask:0xf bank_mask:0x3
	v_add_f32_dpp v102, v102, v102 quad_perm:[2,3,0,1] row_mask:0xf bank_mask:0xf bound_ctrl:1
	v_pk_fma_f32 v[106:107], v[54:55], v[142:143], v[106:107]
	v_add_f32_dpp v176, v226, v226 row_mirror row_mask:0xf bank_mask:0xc
	v_add_f32_dpp v102, v102, v102 row_half_mirror row_mask:0xf bank_mask:0xf bound_ctrl:1
	s_nop 0
	s_nop 0
	v_add_f32_dpp v102, v102, v102 row_mirror row_mask:0xf bank_mask:0xf bound_ctrl:1
	v_pk_fma_f32 v[52:53], v[144:145], v[102:103], v[104:105] op_sel_hi:[1,0,1] neg_lo:[0,1,0] neg_hi:[0,1,0]
	v_pk_fma_f32 v[54:55], v[146:147], v[102:103], v[106:107] op_sel_hi:[1,0,1] neg_lo:[0,1,0] neg_hi:[0,1,0]
	s_waitcnt lgkmcnt(1)
	v_pk_mul_f32 v[102:103], v[52:53], v[56:57]
	v_pk_mul_f32 v[108:109], v[154:155], v[54:55]
	v_pk_fma_f32 v[102:103], v[54:55], v[58:59], v[102:103]
	v_pk_fma_f32 v[108:109], v[152:153], v[52:53], v[108:109]
	v_pk_mul_f32 v[104:105], v[68:69], v[76:77] op_sel_hi:[1,0]
	v_add_f32_e32 v102, v102, v103
	v_add_f32_e32 v228, v108, v109
	v_pk_mul_f32 v[106:107], v[70:71], v[76:77] op_sel_hi:[1,0]
	v_add_f32_dpp v102, v102, v102 quad_perm:[1,0,3,2] row_mask:0xf bank_mask:0xf bound_ctrl:1
	v_pk_fma_f32 v[104:105], v[52:53], v[60:61], v[104:105]
	v_add_f32_dpp v177, v219, v219 row_mirror row_mask:0xf bank_mask:0x3
	v_add_f32_dpp v102, v102, v102 quad_perm:[2,3,0,1] row_mask:0xf bank_mask:0xf bound_ctrl:1
	v_pk_fma_f32 v[106:107], v[54:55], v[62:63], v[106:107]
	v_add_f32_dpp v177, v227, v227 row_mirror row_mask:0xf bank_mask:0xc
	v_add_f32_dpp v102, v102, v102 row_half_mirror row_mask:0xf bank_mask:0xf bound_ctrl:1
	v_add_f32_dpp v180, v172, v172 row_half_mirror row_mask:0xf bank_mask:0x5
	s_nop 0
	v_add_f32_dpp v102, v102, v102 row_mirror row_mask:0xf bank_mask:0xf bound_ctrl:1
	v_add_f32_dpp v180, v176, v176 row_half_mirror row_mask:0xf bank_mask:0xa
	v_pk_fma_f32 v[52:53], v[64:65], v[102:103], v[104:105] op_sel_hi:[1,0,1] neg_lo:[0,1,0] neg_hi:[0,1,0]
	v_pk_fma_f32 v[54:55], v[66:67], v[102:103], v[106:107] op_sel_hi:[1,0,1] neg_lo:[0,1,0] neg_hi:[0,1,0]
	s_waitcnt lgkmcnt(0)
	s_barrier
	ds_read_b128 v[56:59], v129 offset:21504
	ds_read_b128 v[60:63], v129 offset:21760
	ds_read_b128 v[64:67], v129 offset:22016
	ds_read_b128 v[68:71], v129 offset:22272
	ds_read_b128 v[72:75], v129 offset:22528
	ds_read_b32 v76, v131 offset:22784
	ds_read_b128 v[80:83], v129 offset:22848
	ds_read_b128 v[84:87], v129 offset:23104
	ds_read_b128 v[88:91], v129 offset:23360
	ds_read_b128 v[92:95], v129 offset:23616
	ds_read_b128 v[96:99], v129 offset:23872
	ds_read_b32 v100, v131 offset:24128
	s_min_u32 s3, s2, 0x1fc
	s_add_i32 s3, s3, 3
	s_mul_i32 s3, s3, s0
	v_add_u32_e32 v112, s3, v168
	v_add_u32_e32 v113, s3, v116
	v_add_u32_e32 v114, s3, v118
	v_add_u32_e32 v115, s3, v120
	v_add_u32_e32 v128, s3, v122
	v_add_u32_e32 v130, s3, v124
	v_pk_mul_f32 v[108:109], v[162:163], v[54:55]
	v_pk_fma_f32 v[108:109], v[160:161], v[52:53], v[108:109]
	v_add_f32_e32 v229, v108, v109
	v_add_f32_dpp v178, v220, v220 row_mirror row_mask:0xf bank_mask:0x3
	v_add_f32_dpp v178, v228, v228 row_mirror row_mask:0xf bank_mask:0xc
	v_add_f32_dpp v179, v221, v221 row_mirror row_mask:0xf bank_mask:0x3
	v_add_f32_dpp v179, v229, v229 row_mirror row_mask:0xf bank_mask:0xc
	v_add_f32_dpp v181, v173, v173 row_half_mirror row_mask:0xf bank_mask:0x5
	v_add_f32_dpp v181, v177, v177 row_half_mirror row_mask:0xf bank_mask:0xa
	v_add_f32_dpp v182, v174, v174 row_half_mirror row_mask:0xf bank_mask:0x5
	v_add_f32_dpp v182, v178, v178 row_half_mirror row_mask:0xf bank_mask:0xa
	v_add_f32_dpp v183, v175, v175 row_half_mirror row_mask:0xf bank_mask:0x5
	v_add_f32_dpp v183, v179, v179 row_half_mirror row_mask:0xf bank_mask:0xa
	v_cndmask_b32_e64 v184, v180, v182, s[38:39]
	v_cndmask_b32_e64 v185, v182, v180, s[38:39]
	global_load_dwordx4 v[0:3], v112, s[96:97]
	global_load_dwordx4 v[4:7], v113, s[96:97]
	v_add_f32_dpp v186, v185, v184 quad_perm:[2,3,0,1] row_mask:0xf bank_mask:0xf bound_ctrl:1
	v_cndmask_b32_e64 v184, v181, v183, s[38:39]
	v_cndmask_b32_e64 v185, v183, v181, s[38:39]
	global_load_dwordx4 v[8:11], v114, s[96:97]
	global_load_dwordx4 v[12:15], v115, s[96:97]
	v_add_f32_dpp v187, v185, v184 quad_perm:[2,3,0,1] row_mask:0xf bank_mask:0xf bound_ctrl:1
	v_cndmask_b32_e64 v184, v186, v187, s[40:41]
	v_cndmask_b32_e64 v185, v187, v186, s[40:41]
	global_load_dwordx4 v[16:19], v128, s[96:97]
	global_load_dwordx4 v[20:23], v130, s[96:97]
	v_add_f32_dpp v110, v185, v184 quad_perm:[1,0,3,2] row_mask:0xf bank_mask:0xf bound_ctrl:1
	global_store_dword v132, v110, s[96:97]
	s_waitcnt lgkmcnt(6)
	v_pk_mul_f32 v[102:103], v[52:53], v[56:57]
	v_pk_fma_f32 v[102:103], v[54:55], v[58:59], v[102:103]
	v_pk_mul_f32 v[104:105], v[68:69], v[76:77] op_sel_hi:[1,0]
	v_add_f32_e32 v102, v102, v103
	v_pk_mul_f32 v[106:107], v[70:71], v[76:77] op_sel_hi:[1,0]
	ds_read_b128 v[136:139], v129 offset:24192
	v_add_f32_dpp v102, v102, v102 quad_perm:[1,0,3,2] row_mask:0xf bank_mask:0xf bound_ctrl:1
	v_pk_fma_f32 v[104:105], v[52:53], v[60:61], v[104:105]
	ds_read_b128 v[140:143], v129 offset:24448
	v_add_f32_dpp v102, v102, v102 quad_perm:[2,3,0,1] row_mask:0xf bank_mask:0xf bound_ctrl:1
	v_pk_fma_f32 v[106:107], v[54:55], v[62:63], v[106:107]
	ds_read_b128 v[144:147], v129 offset:24704
	v_add_f32_dpp v102, v102, v102 row_half_mirror row_mask:0xf bank_mask:0xf bound_ctrl:1
	ds_read_b128 v[148:151], v129 offset:24960
	ds_read_b128 v[152:155], v129 offset:25216
	v_add_f32_dpp v102, v102, v102 row_mirror row_mask:0xf bank_mask:0xf bound_ctrl:1
	v_pk_fma_f32 v[52:53], v[64:65], v[102:103], v[104:105] op_sel_hi:[1,0,1] neg_lo:[0,1,0] neg_hi:[0,1,0]
	v_pk_fma_f32 v[54:55], v[66:67], v[102:103], v[106:107] op_sel_hi:[1,0,1] neg_lo:[0,1,0] neg_hi:[0,1,0]
	ds_read_b32 v156, v131 offset:25472
	s_waitcnt lgkmcnt(6)
	v_pk_mul_f32 v[102:103], v[52:53], v[80:81]
	v_pk_mul_f32 v[108:109], v[74:75], v[54:55]
	v_pk_fma_f32 v[102:103], v[54:55], v[82:83], v[102:103]
	v_pk_fma_f32 v[108:109], v[72:73], v[52:53], v[108:109]
	v_pk_mul_f32 v[104:105], v[92:93], v[100:101] op_sel_hi:[1,0]
	v_add_f32_e32 v102, v102, v103
	v_add_f32_e32 v214, v108, v109
	v_pk_mul_f32 v[106:107], v[94:95], v[100:101] op_sel_hi:[1,0]
	v_add_f32_dpp v102, v102, v102 quad_perm:[1,0,3,2] row_mask:0xf bank_mask:0xf bound_ctrl:1
	v_pk_fma_f32 v[104:105], v[52:53], v[84:85], v[104:105]
	ds_read_b128 v[56:59], v129 offset:25536
	v_add_f32_dpp v102, v102, v102 quad_perm:[2,3,0,1] row_mask:0xf bank_mask:0xf bound_ctrl:1
	v_pk_fma_f32 v[106:107], v[54:55], v[86:87], v[106:107]
	ds_read_b128 v[60:63], v129 offset:25792
	v_add_f32_dpp v102, v102, v102 row_half_mirror row_mask:0xf bank_mask:0xf bound_ctrl:1
	ds_read_b128 v[64:67], v129 offset:26048
	ds_read_b128 v[68:71], v129 offset:26304
	v_add_f32_dpp v102, v102, v102 row_mirror row_mask:0xf bank_mask:0xf bound_ctrl:1
	v_pk_fma_f32 v[52:53], v[88:89], v[102:103], v[104:105] op_sel_hi:[1,0,1] neg_lo:[0,1,0] neg_hi:[0,1,0]
	v_pk_fma_f32 v[54:55], v[90:91], v[102:103], v[106:107] op_sel_hi:[1,0,1] neg_lo:[0,1,0] neg_hi:[0,1,0]
	ds_read_b128 v[72:75], v129 offset:26560
	ds_read_b32 v76, v131 offset:26816
	s_waitcnt lgkmcnt(6)
	v_pk_mul_f32 v[102:103], v[52:53], v[136:137]
	v_pk_mul_f32 v[108:109], v[98:99], v[54:55]
	v_pk_fma_f32 v[102:103], v[54:55], v[138:139], v[102:103]
	v_pk_fma_f32 v[108:109], v[96:97], v[52:53], v[108:109]
	v_pk_mul_f32 v[104:105], v[148:149], v[156:157] op_sel_hi:[1,0]
	v_add_f32_e32 v102, v102, v103
	v_add_f32_e32 v215, v108, v109
	v_pk_mul_f32 v[106:107], v[150:151], v[156:157] op_sel_hi:[1,0]
	v_add_f32_dpp v102, v102, v102 quad_perm:[1,0,3,2] row_mask:0xf bank_mask:0xf bound_ctrl:1
	v_pk_fma_f32 v[104:105], v[52:53], v[140:141], v[104:105]
	ds_read_b128 v[80:83], v129 offset:26880
	v_add_f32_dpp v102, v102, v102 quad_perm:[2,3,0,1] row_mask:0xf bank_mask:0xf bound_ctrl:1
	v_pk_fma_f32 v[106:107], v[54:55], v[142:143], v[106:107]
	ds_read_b128 v[84:87], v129 offset:27136
	v_add_f32_dpp v102, v102, v102 row_half_mirror row_mask:0xf bank_mask:0xf bound_ctrl:1
	ds_read_b128 v[88:91], v129 offset:27392
	ds_read_b128 v[92:95], v129 offset:27648
	v_add_f32_dpp v102, v102, v102 row_mirror row_mask:0xf bank_mask:0xf bound_ctrl:1
	v_pk_fma_f32 v[52:53], v[144:145], v[102:103], v[104:105] op_sel_hi:[1,0,1] neg_lo:[0,1,0] neg_hi:[0,1,0]
	v_pk_fma_f32 v[54:55], v[146:147], v[102:103], v[106:107] op_sel_hi:[1,0,1] neg_lo:[0,1,0] neg_hi:[0,1,0]
	ds_read_b128 v[96:99], v129 offset:27904
	ds_read_b32 v100, v131 offset:28160
	s_waitcnt lgkmcnt(6)
	v_pk_mul_f32 v[102:103], v[52:53], v[56:57]
	v_pk_mul_f32 v[108:109], v[154:155], v[54:55]
	v_pk_fma_f32 v[102:103], v[54:55], v[58:59], v[102:103]
	v_pk_fma_f32 v[108:109], v[152:153], v[52:53], v[108:109]
	v_pk_mul_f32 v[104:105], v[68:69], v[76:77] op_sel_hi:[1,0]
	v_add_f32_e32 v102, v102, v103
	v_add_f32_e32 v216, v108, v109
	v_pk_mul_f32 v[106:107], v[70:71], v[76:77] op_sel_hi:[1,0]
	v_add_f32_dpp v102, v102, v102 quad_perm:[1,0,3,2] row_mask:0xf bank_mask:0xf bound_ctrl:1
	v_pk_fma_f32 v[104:105], v[52:53], v[60:61], v[104:105]
	ds_read_b128 v[136:139], v129 offset:28224
	v_add_f32_dpp v102, v102, v102 quad_perm:[2,3,0,1] row_mask:0xf bank_mask:0xf bound_ctrl:1
	v_pk_fma_f32 v[106:107], v[54:55], v[62:63], v[106:107]
	ds_read_b128 v[140:143], v129 offset:28480
	v_add_f32_dpp v102, v102, v102 row_half_mirror row_mask:0xf bank_mask:0xf bound_ctrl:1
	ds_read_b128 v[144:147], v129 offset:28736
	ds_read_b128 v[148:151], v129 offset:28992
	v_add_f32_dpp v102, v102, v102 row_mirror row_mask:0xf bank_mask:0xf bound_ctrl:1
	v_pk_fma_f32 v[52:53], v[64:65], v[102:103], v[104:105] op_sel_hi:[1,0,1] neg_lo:[0,1,0] neg_hi:[0,1,0]
	v_pk_fma_f32 v[54:55], v[66:67], v[102:103], v[106:107] op_sel_hi:[1,0,1] neg_lo:[0,1,0] neg_hi:[0,1,0]
	ds_read_b128 v[152:155], v129 offset:29248
	ds_read_b32 v156, v131 offset:29504
	s_waitcnt lgkmcnt(6)
	v_pk_mul_f32 v[102:103], v[52:53], v[80:81]
	v_pk_mul_f32 v[108:109], v[74:75], v[54:55]
	v_pk_fma_f32 v[102:103], v[54:55], v[82:83], v[102:103]
	v_pk_fma_f32 v[108:109], v[72:73], v[52:53], v[108:109]
	v_pk_mul_f32 v[104:105], v[92:93], v[100:101] op_sel_hi:[1,0]
	v_add_f32_e32 v102, v102, v103
	v_add_f32_e32 v217, v108, v109
	v_pk_mul_f32 v[106:107], v[94:95], v[100:101] op_sel_hi:[1,0]
	v_add_f32_dpp v102, v102, v102 quad_perm:[1,0,3,2] row_mask:0xf bank_mask:0xf bound_ctrl:1
	v_pk_fma_f32 v[104:105], v[52:53], v[84:85], v[104:105]
	ds_read_b128 v[56:59], v129 offset:29568
	v_add_f32_dpp v102, v102, v102 quad_perm:[2,3,0,1] row_mask:0xf bank_mask:0xf bound_ctrl:1
	v_pk_fma_f32 v[106:107], v[54:55], v[86:87], v[106:107]
	ds_read_b128 v[60:63], v129 offset:29824
	v_add_f32_dpp v102, v102, v102 row_half_mirror row_mask:0xf bank_mask:0xf bound_ctrl:1
	ds_read_b128 v[64:67], v129 offset:30080
	ds_read_b128 v[68:71], v129 offset:30336
	v_add_f32_dpp v102, v102, v102 row_mirror row_mask:0xf bank_mask:0xf bound_ctrl:1
	v_pk_fma_f32 v[52:53], v[88:89], v[102:103], v[104:105] op_sel_hi:[1,0,1] neg_lo:[0,1,0] neg_hi:[0,1,0]
	v_pk_fma_f32 v[54:55], v[90:91], v[102:103], v[106:107] op_sel_hi:[1,0,1] neg_lo:[0,1,0] neg_hi:[0,1,0]
	ds_read_b128 v[72:75], v129 offset:30592
	ds_read_b32 v76, v131 offset:30848
	s_waitcnt lgkmcnt(6)
	v_pk_mul_f32 v[102:103], v[52:53], v[136:137]
	v_pk_mul_f32 v[108:109], v[98:99], v[54:55]
	v_pk_fma_f32 v[102:103], v[54:55], v[138:139], v[102:103]
	v_pk_fma_f32 v[108:109], v[96:97], v[52:53], v[108:109]
	v_pk_mul_f32 v[104:105], v[148:149], v[156:157] op_sel_hi:[1,0]
	v_add_f32_e32 v102, v102, v103
	v_add_f32_e32 v218, v108, v109
	v_pk_mul_f32 v[106:107], v[150:151], v[156:157] op_sel_hi:[1,0]
	v_add_f32_dpp v102, v102, v102 quad_perm:[1,0,3,2] row_mask:0xf bank_mask:0xf bound_ctrl:1
	v_pk_fma_f32 v[104:105], v[52:53], v[140:141], v[104:105]
	ds_read_b128 v[80:83], v129 offset:30912
	v_add_f32_dpp v102, v102, v102 quad_perm:[2,3,0,1] row_mask:0xf bank_mask:0xf bound_ctrl:1
	v_pk_fma_f32 v[106:107], v[54:55], v[142:143], v[106:107]
	ds_read_b128 v[84:87], v129 offset:31168
	v_add_f32_dpp v102, v102, v102 row_half_mirror row_mask:0xf bank_mask:0xf bound_ctrl:1
	ds_read_b128 v[88:91], v129 offset:31424
	ds_read_b128 v[92:95], v129 offset:31680
	v_add_f32_dpp v102, v102, v102 row_mirror row_mask:0xf bank_mask:0xf bound_ctrl:1
	v_pk_fma_f32 v[52:53], v[144:145], v[102:103], v[104:105] op_sel_hi:[1,0,1] neg_lo:[0,1,0] neg_hi:[0,1,0]
	v_pk_fma_f32 v[54:55], v[146:147], v[102:103], v[106:107] op_sel_hi:[1,0,1] neg_lo:[0,1,0] neg_hi:[0,1,0]
	ds_read_b128 v[96:99], v129 offset:31936
	ds_read_b32 v100, v131 offset:32192
	s_waitcnt lgkmcnt(6)
	v_pk_mul_f32 v[102:103], v[52:53], v[56:57]
	v_pk_mul_f32 v[108:109], v[154:155], v[54:55]
	v_pk_fma_f32 v[102:103], v[54:55], v[58:59], v[102:103]
	v_pk_fma_f32 v[108:109], v[152:153], v[52:53], v[108:109]
	v_pk_mul_f32 v[104:105], v[68:69], v[76:77] op_sel_hi:[1,0]
	v_add_f32_e32 v102, v102, v103
	v_add_f32_e32 v219, v108, v109
	v_pk_mul_f32 v[106:107], v[70:71], v[76:77] op_sel_hi:[1,0]
	v_add_f32_dpp v102, v102, v102 quad_perm:[1,0,3,2] row_mask:0xf bank_mask:0xf bound_ctrl:1
	v_pk_fma_f32 v[104:105], v[52:53], v[60:61], v[104:105]
	ds_read_b128 v[136:139], v129 offset:32256
	v_add_f32_dpp v102, v102, v102 quad_perm:[2,3,0,1] row_mask:0xf bank_mask:0xf bound_ctrl:1
	v_pk_fma_f32 v[106:107], v[54:55], v[62:63], v[106:107]
	ds_read_b128 v[140:143], v129 offset:32512
	v_add_f32_dpp v102, v102, v102 row_half_mirror row_mask:0xf bank_mask:0xf bound_ctrl:1
	ds_read_b128 v[144:147], v129 offset:32768
	ds_read_b128 v[148:151], v129 offset:33024
	v_add_f32_dpp v102, v102, v102 row_mirror row_mask:0xf bank_mask:0xf bound_ctrl:1
	v_pk_fma_f32 v[52:53], v[64:65], v[102:103], v[104:105] op_sel_hi:[1,0,1] neg_lo:[0,1,0] neg_hi:[0,1,0]
	v_pk_fma_f32 v[54:55], v[66:67], v[102:103], v[106:107] op_sel_hi:[1,0,1] neg_lo:[0,1,0] neg_hi:[0,1,0]
	ds_read_b128 v[152:155], v129 offset:33280
	ds_read_b32 v156, v131 offset:33536
	s_waitcnt lgkmcnt(6)
	v_pk_mul_f32 v[102:103], v[52:53], v[80:81]
	v_pk_mul_f32 v[108:109], v[74:75], v[54:55]
	v_pk_fma_f32 v[102:103], v[54:55], v[82:83], v[102:103]
	v_pk_fma_f32 v[108:109], v[72:73], v[52:53], v[108:109]
	v_pk_mul_f32 v[104:105], v[92:93], v[100:101] op_sel_hi:[1,0]
	v_add_f32_e32 v102, v102, v103
	v_add_f32_e32 v220, v108, v109
	v_pk_mul_f32 v[106:107], v[94:95], v[100:101] op_sel_hi:[1,0]
	v_add_f32_dpp v102, v102, v102 quad_perm:[1,0,3,2] row_mask:0xf bank_mask:0xf bound_ctrl:1
	v_pk_fma_f32 v[104:105], v[52:53], v[84:85], v[104:105]
	ds_read_b128 v[56:59], v129 offset:33600
	v_add_f32_dpp v102, v102, v102 quad_perm:[2,3,0,1] row_mask:0xf bank_mask:0xf bound_ctrl:1
	v_pk_fma_f32 v[106:107], v[54:55], v[86:87], v[106:107]
	ds_read_b128 v[60:63], v129 offset:33856
	v_add_f32_dpp v102, v102, v102 row_half_mirror row_mask:0xf bank_mask:0xf bound_ctrl:1
	ds_read_b128 v[64:67], v129 offset:34112
	ds_read_b128 v[68:71], v129 offset:34368
	v_add_f32_dpp v102, v102, v102 row_mirror row_mask:0xf bank_mask:0xf bound_ctrl:1
	v_pk_fma_f32 v[52:53], v[88:89], v[102:103], v[104:105] op_sel_hi:[1,0,1] neg_lo:[0,1,0] neg_hi:[0,1,0]
	v_pk_fma_f32 v[54:55], v[90:91], v[102:103], v[106:107] op_sel_hi:[1,0,1] neg_lo:[0,1,0] neg_hi:[0,1,0]
	ds_read_b128 v[72:75], v129 offset:34624
	ds_read_b32 v76, v131 offset:34880
	s_waitcnt lgkmcnt(6)
; #define SC_STORE(R, B)                                                \
;   _Pragma("unroll") for (int i = 0; i < 6; ++i) *(f32x4*)(buf + (B) * SC_CH * SC_STEPF + pf[i]) = R[i];
; __device__ __forceinline__ void scan_unit(const Params p, int u, char* smem) {
;     ...
;   __syncthreads();
;   __builtin_amdgcn_s_setprio(3);
;   SC_LOAD(lregA, 0);
;   SC_STORE(lregA, 0);
;   SC_LOAD(lregB, 1);
;   __syncthreads();
;   for (int c = 0; c < nch; c += 2) {
;     SC_LOAD(lregA, c + 2);
;     SC_COMPUTE(c, 0);
;     SC_STORE(lregB, 1);
	v_pk_mul_f32 v[102:103], v[52:53], v[136:137]
	v_pk_mul_f32 v[108:109], v[98:99], v[54:55]
	v_pk_fma_f32 v[102:103], v[54:55], v[138:139], v[102:103]
	v_pk_fma_f32 v[108:109], v[96:97], v[52:53], v[108:109]
	v_pk_mul_f32 v[104:105], v[148:149], v[156:157] op_sel_hi:[1,0]
	v_add_f32_e32 v102, v102, v103
	v_add_f32_e32 v221, v108, v109
	v_pk_mul_f32 v[106:107], v[150:151], v[156:157] op_sel_hi:[1,0]
	v_add_f32_dpp v102, v102, v102 quad_perm:[1,0,3,2] row_mask:0xf bank_mask:0xf bound_ctrl:1
	v_pk_fma_f32 v[104:105], v[52:53], v[140:141], v[104:105]
	ds_read_b128 v[80:83], v129 offset:34944
	v_add_f32_dpp v102, v102, v102 quad_perm:[2,3,0,1] row_mask:0xf bank_mask:0xf bound_ctrl:1
	v_pk_fma_f32 v[106:107], v[54:55], v[142:143], v[106:107]
	ds_read_b128 v[84:87], v129 offset:35200
	v_add_f32_dpp v102, v102, v102 row_half_mirror row_mask:0xf bank_mask:0xf bound_ctrl:1
	ds_read_b128 v[88:91], v129 offset:35456
	ds_read_b128 v[92:95], v129 offset:35712
	v_add_f32_dpp v102, v102, v102 row_mirror row_mask:0xf bank_mask:0xf bound_ctrl:1
	v_pk_fma_f32 v[52:53], v[144:145], v[102:103], v[104:105] op_sel_hi:[1,0,1] neg_lo:[0,1,0] neg_hi:[0,1,0]
	v_pk_fma_f32 v[54:55], v[146:147], v[102:103], v[106:107] op_sel_hi:[1,0,1] neg_lo:[0,1,0] neg_hi:[0,1,0]
	ds_read_b128 v[96:99], v129 offset:35968
	ds_read_b32 v100, v131 offset:36224
	s_waitcnt vmcnt(11)
	ds_write_b128 v117, v[28:31]
	s_waitcnt lgkmcnt(7)
	v_pk_mul_f32 v[102:103], v[52:53], v[56:57]
	v_pk_mul_f32 v[108:109], v[154:155], v[54:55]
	v_pk_fma_f32 v[102:103], v[54:55], v[58:59], v[102:103]
	v_pk_fma_f32 v[108:109], v[152:153], v[52:53], v[108:109]
	v_pk_mul_f32 v[104:105], v[68:69], v[76:77] op_sel_hi:[1,0]
	v_add_f32_e32 v102, v102, v103
	v_add_f32_e32 v222, v108, v109
	v_pk_mul_f32 v[106:107], v[70:71], v[76:77] op_sel_hi:[1,0]
	v_add_f32_dpp v102, v102, v102 quad_perm:[1,0,3,2] row_mask:0xf bank_mask:0xf bound_ctrl:1
	v_pk_fma_f32 v[104:105], v[52:53], v[60:61], v[104:105]
	ds_read_b128 v[136:139], v129 offset:36288
	v_add_f32_dpp v102, v102, v102 quad_perm:[2,3,0,1] row_mask:0xf bank_mask:0xf bound_ctrl:1
	v_pk_fma_f32 v[106:107], v[54:55], v[62:63], v[106:107]
	ds_read_b128 v[140:143], v129 offset:36544
	v_add_f32_dpp v102, v102, v102 row_half_mirror row_mask:0xf bank_mask:0xf bound_ctrl:1
	ds_read_b128 v[144:147], v129 offset:36800
	ds_read_b128 v[148:151], v129 offset:37056
	v_add_f32_dpp v102, v102, v102 row_mirror row_mask:0xf bank_mask:0xf bound_ctrl:1
	v_pk_fma_f32 v[52:53], v[64:65], v[102:103], v[104:105] op_sel_hi:[1,0,1] neg_lo:[0,1,0] neg_hi:[0,1,0]
	v_pk_fma_f32 v[54:55], v[66:67], v[102:103], v[106:107] op_sel_hi:[1,0,1] neg_lo:[0,1,0] neg_hi:[0,1,0]
	ds_read_b128 v[152:155], v129 offset:37312
	ds_read_b32 v156, v131 offset:37568
	s_waitcnt vmcnt(10)
	ds_write_b128 v119, v[32:35]
	s_waitcnt lgkmcnt(8)
	v_pk_mul_f32 v[102:103], v[52:53], v[80:81]
	v_pk_mul_f32 v[108:109], v[74:75], v[54:55]
	v_pk_fma_f32 v[102:103], v[54:55], v[82:83], v[102:103]
	v_pk_fma_f32 v[108:109], v[72:73], v[52:53], v[108:109]
	v_pk_mul_f32 v[104:105], v[92:93], v[100:101] op_sel_hi:[1,0]
	v_add_f32_e32 v102, v102, v103
	v_add_f32_e32 v223, v108, v109
	v_pk_mul_f32 v[106:107], v[94:95], v[100:101] op_sel_hi:[1,0]
	v_add_f32_dpp v102, v102, v102 quad_perm:[1,0,3,2] row_mask:0xf bank_mask:0xf bound_ctrl:1
	v_pk_fma_f32 v[104:105], v[52:53], v[84:85], v[104:105]
	v_add_f32_dpp v172, v214, v214 row_mirror row_mask:0xf bank_mask:0x3
	v_add_f32_dpp v102, v102, v102 quad_perm:[2,3,0,1] row_mask:0xf bank_mask:0xf bound_ctrl:1
	v_pk_fma_f32 v[106:107], v[54:55], v[86:87], v[106:107]
	v_add_f32_dpp v172, v222, v222 row_mirror row_mask:0xf bank_mask:0xc
	v_add_f32_dpp v102, v102, v102 row_half_mirror row_mask:0xf bank_mask:0xf bound_ctrl:1
	ds_read_b128 v[56:59], v129 offset:37632
	ds_read_b128 v[60:63], v129 offset:37888
	v_add_f32_dpp v102, v102, v102 row_mirror row_mask:0xf bank_mask:0xf bound_ctrl:1
	v_pk_fma_f32 v[52:53], v[88:89], v[102:103], v[104:105] op_sel_hi:[1,0,1] neg_lo:[0,1,0] neg_hi:[0,1,0]
	v_pk_fma_f32 v[54:55], v[90:91], v[102:103], v[106:107] op_sel_hi:[1,0,1] neg_lo:[0,1,0] neg_hi:[0,1,0]
	ds_read_b128 v[64:67], v129 offset:38144
	ds_read_b128 v[68:71], v129 offset:38400
	ds_read_b128 v[72:75], v129 offset:38656
	ds_read_b32 v76, v131 offset:38912
	s_waitcnt vmcnt(9)
	ds_write_b128 v121, v[36:39]
	s_waitcnt lgkmcnt(8)
	v_pk_mul_f32 v[102:103], v[52:53], v[136:137]
	v_pk_mul_f32 v[108:109], v[98:99], v[54:55]
	v_pk_fma_f32 v[102:103], v[54:55], v[138:139], v[102:103]
	v_pk_fma_f32 v[108:109], v[96:97], v[52:53], v[108:109]
	v_pk_mul_f32 v[104:105], v[148:149], v[156:157] op_sel_hi:[1,0]
	v_add_f32_e32 v102, v102, v103
	v_add_f32_e32 v224, v108, v109
	v_pk_mul_f32 v[106:107], v[150:151], v[156:157] op_sel_hi:[1,0]
	v_add_f32_dpp v102, v102, v102 quad_perm:[1,0,3,2] row_mask:0xf bank_mask:0xf bound_ctrl:1
	v_pk_fma_f32 v[104:105], v[52:53], v[140:141], v[104:105]
	v_add_f32_dpp v173, v215, v215 row_mirror row_mask:0xf bank_mask:0x3
	v_add_f32_dpp v102, v102, v102 quad_perm:[2,3,0,1] row_mask:0xf bank_mask:0xf bound_ctrl:1
	v_pk_fma_f32 v[106:107], v[54:55], v[142:143], v[106:107]
	v_add_f32_dpp v173, v223, v223 row_mirror row_mask:0xf bank_mask:0xc
	v_add_f32_dpp v102, v102, v102 row_half_mirror row_mask:0xf bank_mask:0xf bound_ctrl:1
	ds_read_b128 v[80:83], v129 offset:38976
	ds_read_b128 v[84:87], v129 offset:39232
	v_add_f32_dpp v102, v102, v102 row_mirror row_mask:0xf bank_mask:0xf bound_ctrl:1
	v_pk_fma_f32 v[52:53], v[144:145], v[102:103], v[104:105] op_sel_hi:[1,0,1] neg_lo:[0,1,0] neg_hi:[0,1,0]
	v_pk_fma_f32 v[54:55], v[146:147], v[102:103], v[106:107] op_sel_hi:[1,0,1] neg_lo:[0,1,0] neg_hi:[0,1,0]
	ds_read_b128 v[88:91], v129 offset:39488
	ds_read_b128 v[92:95], v129 offset:39744
	ds_read_b128 v[96:99], v129 offset:40000
	ds_read_b32 v100, v131 offset:40256
	s_waitcnt vmcnt(8)
; #define LBAR() asm volatile("s_waitcnt lgkmcnt(0)\n\ts_barrier" ::: "memory")
; #define SC_STORE(R, B)                                                \
;   _Pragma("unroll") for (int i = 0; i < 6; ++i) *(f32x4*)(buf + (B) * SC_CH * SC_STEPF + pf[i]) = R[i];
; __device__ __forceinline__ void scan_unit(const Params p, int u, char* smem) {
;     ...
;   __syncthreads();
;   __builtin_amdgcn_s_setprio(3);
;   SC_LOAD(lregA, 0);
;   SC_STORE(lregA, 0);
;   SC_LOAD(lregB, 1);
;   __syncthreads();
;   for (int c = 0; c < nch; c += 2) {
;     SC_LOAD(lregA, c + 2);
;     SC_COMPUTE(c, 0);
;     SC_STORE(lregB, 1);
;     LBAR();
;     SC_LOAD(lregB, c + 3);
;     SC_COMPUTE(c + 1, 1);
;     SC_STORE(lregA, 0);
;     LBAR();
;   }
	ds_write_b128 v123, v[40:43]
	s_waitcnt lgkmcnt(8)
	v_pk_mul_f32 v[102:103], v[52:53], v[56:57]
	v_pk_mul_f32 v[108:109], v[154:155], v[54:55]
	v_pk_fma_f32 v[102:103], v[54:55], v[58:59], v[102:103]
	v_pk_fma_f32 v[108:109], v[152:153], v[52:53], v[108:109]
	v_pk_mul_f32 v[104:105], v[68:69], v[76:77] op_sel_hi:[1,0]
	v_add_f32_e32 v102, v102, v103
	v_add_f32_e32 v225, v108, v109
	v_pk_mul_f32 v[106:107], v[70:71], v[76:77] op_sel_hi:[1,0]
	v_add_f32_dpp v102, v102, v102 quad_perm:[1,0,3,2] row_mask:0xf bank_mask:0xf bound_ctrl:1
	v_pk_fma_f32 v[104:105], v[52:53], v[60:61], v[104:105]
	v_add_f32_dpp v174, v216, v216 row_mirror row_mask:0xf bank_mask:0x3
	v_add_f32_dpp v102, v102, v102 quad_perm:[2,3,0,1] row_mask:0xf bank_mask:0xf bound_ctrl:1
	v_pk_fma_f32 v[106:107], v[54:55], v[62:63], v[106:107]
	v_add_f32_dpp v174, v224, v224 row_mirror row_mask:0xf bank_mask:0xc
	v_add_f32_dpp v102, v102, v102 row_half_mirror row_mask:0xf bank_mask:0xf bound_ctrl:1
	ds_read_b128 v[136:139], v129 offset:40320
	ds_read_b128 v[140:143], v129 offset:40576
	v_add_f32_dpp v102, v102, v102 row_mirror row_mask:0xf bank_mask:0xf bound_ctrl:1
	v_pk_fma_f32 v[52:53], v[64:65], v[102:103], v[104:105] op_sel_hi:[1,0,1] neg_lo:[0,1,0] neg_hi:[0,1,0]
	v_pk_fma_f32 v[54:55], v[66:67], v[102:103], v[106:107] op_sel_hi:[1,0,1] neg_lo:[0,1,0] neg_hi:[0,1,0]
	ds_read_b128 v[144:147], v129 offset:40832
	ds_read_b128 v[148:151], v129 offset:41088
	ds_read_b128 v[152:155], v129 offset:41344
	ds_read_b32 v156, v131 offset:41600
	s_waitcnt vmcnt(7)
	ds_write_b128 v125, v[44:47]
	s_waitcnt lgkmcnt(8)
	v_pk_mul_f32 v[102:103], v[52:53], v[80:81]
	v_pk_mul_f32 v[108:109], v[74:75], v[54:55]
	v_pk_fma_f32 v[102:103], v[54:55], v[82:83], v[102:103]
	v_pk_fma_f32 v[108:109], v[72:73], v[52:53], v[108:109]
	v_pk_mul_f32 v[104:105], v[92:93], v[100:101] op_sel_hi:[1,0]
	v_add_f32_e32 v102, v102, v103
	v_add_f32_e32 v226, v108, v109
	v_pk_mul_f32 v[106:107], v[94:95], v[100:101] op_sel_hi:[1,0]
	v_add_f32_dpp v102, v102, v102 quad_perm:[1,0,3,2] row_mask:0xf bank_mask:0xf bound_ctrl:1
	v_pk_fma_f32 v[104:105], v[52:53], v[84:85], v[104:105]
	v_add_f32_dpp v175, v217, v217 row_mirror row_mask:0xf bank_mask:0x3
	v_add_f32_dpp v102, v102, v102 quad_perm:[2,3,0,1] row_mask:0xf bank_mask:0xf bound_ctrl:1
	v_pk_fma_f32 v[106:107], v[54:55], v[86:87], v[106:107]
	v_add_f32_dpp v175, v225, v225 row_mirror row_mask:0xf bank_mask:0xc
	v_add_f32_dpp v102, v102, v102 row_half_mirror row_mask:0xf bank_mask:0xf bound_ctrl:1
	ds_read_b128 v[56:59], v129 offset:41664
	ds_read_b128 v[60:63], v129 offset:41920
	v_add_f32_dpp v102, v102, v102 row_mirror row_mask:0xf bank_mask:0xf bound_ctrl:1
	v_pk_fma_f32 v[52:53], v[88:89], v[102:103], v[104:105] op_sel_hi:[1,0,1] neg_lo:[0,1,0] neg_hi:[0,1,0]
	v_pk_fma_f32 v[54:55], v[90:91], v[102:103], v[106:107] op_sel_hi:[1,0,1] neg_lo:[0,1,0] neg_hi:[0,1,0]
	ds_read_b128 v[64:67], v129 offset:42176
	ds_read_b128 v[68:71], v129 offset:42432
	ds_read_b128 v[160:163], v129 offset:42688
	ds_read_b32 v76, v131 offset:42944
	s_waitcnt vmcnt(6)
	ds_write_b128 v127, v[24:27]
	s_waitcnt lgkmcnt(8)
	v_pk_mul_f32 v[102:103], v[52:53], v[136:137]
	v_pk_mul_f32 v[108:109], v[98:99], v[54:55]
	v_pk_fma_f32 v[102:103], v[54:55], v[138:139], v[102:103]
	v_pk_fma_f32 v[108:109], v[96:97], v[52:53], v[108:109]
	v_pk_mul_f32 v[104:105], v[148:149], v[156:157] op_sel_hi:[1,0]
	v_add_f32_e32 v102, v102, v103
	v_add_f32_e32 v227, v108, v109
	v_pk_mul_f32 v[106:107], v[150:151], v[156:157] op_sel_hi:[1,0]
	v_add_f32_dpp v102, v102, v102 quad_perm:[1,0,3,2] row_mask:0xf bank_mask:0xf bound_ctrl:1
	v_pk_fma_f32 v[104:105], v[52:53], v[140:141], v[104:105]
	v_add_f32_dpp v176, v218, v218 row_mirror row_mask:0xf bank_mask:0x3
	v_add_f32_dpp v102, v102, v102 quad_perm:[2,3,0,1] row_mask:0xf bank_mask:0xf bound_ctrl:1
	v_pk_fma_f32 v[106:107], v[54:55], v[142:143], v[106:107]
	v_add_f32_dpp v176, v226, v226 row_mirror row_mask:0xf bank_mask:0xc
	v_add_f32_dpp v102, v102, v102 row_half_mirror row_mask:0xf bank_mask:0xf bound_ctrl:1
	s_nop 0
	s_nop 0
	v_add_f32_dpp v102, v102, v102 row_mirror row_mask:0xf bank_mask:0xf bound_ctrl:1
	v_pk_fma_f32 v[52:53], v[144:145], v[102:103], v[104:105] op_sel_hi:[1,0,1] neg_lo:[0,1,0] neg_hi:[0,1,0]
	v_pk_fma_f32 v[54:55], v[146:147], v[102:103], v[106:107] op_sel_hi:[1,0,1] neg_lo:[0,1,0] neg_hi:[0,1,0]
	s_waitcnt lgkmcnt(1)
	v_pk_mul_f32 v[102:103], v[52:53], v[56:57]
	v_pk_mul_f32 v[108:109], v[154:155], v[54:55]
	v_pk_fma_f32 v[102:103], v[54:55], v[58:59], v[102:103]
	v_pk_fma_f32 v[108:109], v[152:153], v[52:53], v[108:109]
	v_pk_mul_f32 v[104:105], v[68:69], v[76:77] op_sel_hi:[1,0]
	v_add_f32_e32 v102, v102, v103
	v_add_f32_e32 v228, v108, v109
	v_pk_mul_f32 v[106:107], v[70:71], v[76:77] op_sel_hi:[1,0]
	v_add_f32_dpp v102, v102, v102 quad_perm:[1,0,3,2] row_mask:0xf bank_mask:0xf bound_ctrl:1
	v_pk_fma_f32 v[104:105], v[52:53], v[60:61], v[104:105]
	v_add_f32_dpp v177, v219, v219 row_mirror row_mask:0xf bank_mask:0x3
	v_add_f32_dpp v102, v102, v102 quad_perm:[2,3,0,1] row_mask:0xf bank_mask:0xf bound_ctrl:1
	v_pk_fma_f32 v[106:107], v[54:55], v[62:63], v[106:107]
	v_add_f32_dpp v177, v227, v227 row_mirror row_mask:0xf bank_mask:0xc
	v_add_f32_dpp v102, v102, v102 row_half_mirror row_mask:0xf bank_mask:0xf bound_ctrl:1
	v_add_f32_dpp v180, v172, v172 row_half_mirror row_mask:0xf bank_mask:0x5
	s_nop 0
	v_add_f32_dpp v102, v102, v102 row_mirror row_mask:0xf bank_mask:0xf bound_ctrl:1
	v_add_f32_dpp v180, v176, v176 row_half_mirror row_mask:0xf bank_mask:0xa
	v_pk_fma_f32 v[52:53], v[64:65], v[102:103], v[104:105] op_sel_hi:[1,0,1] neg_lo:[0,1,0] neg_hi:[0,1,0]
	v_pk_fma_f32 v[54:55], v[66:67], v[102:103], v[106:107] op_sel_hi:[1,0,1] neg_lo:[0,1,0] neg_hi:[0,1,0]
	v_add_u32_e32 v111, s0, v132
	v_add_u32_e32 v132, s1, v132
	s_mov_b32 s3, s2
	s_cmpk_lt_u32 s2, 0x1fe
	s_waitcnt lgkmcnt(0)
	s_barrier
; #define LBAR() asm volatile("s_waitcnt lgkmcnt(0)\n\ts_barrier" ::: "memory")
; #define SC_STORE(R, B)                                                \
;   _Pragma("unroll") for (int i = 0; i < 6; ++i) *(f32x4*)(buf + (B) * SC_CH * SC_STEPF + pf[i]) = R[i];
; __device__ __forceinline__ void scan_unit(const Params p, int u, char* smem) {
;     ...
;   __syncthreads();
;   __builtin_amdgcn_s_setprio(3);
;   SC_LOAD(lregA, 0);
;   SC_STORE(lregA, 0);
;   SC_LOAD(lregB, 1);
;   __syncthreads();
;   for (int c = 0; c < nch; c += 2) {
;     SC_LOAD(lregA, c + 2);
;     SC_COMPUTE(c, 0);
;     SC_STORE(lregB, 1);
;     LBAR();
;     SC_LOAD(lregB, c + 3);
;     SC_COMPUTE(c + 1, 1);
;     SC_STORE(lregA, 0);
;     LBAR();
;   }
;   __builtin_amdgcn_s_setprio(0);
; }
; template <int ATM>
; __device__ __forceinline__ void phase_attn_scan(const Params p, int l, char* smem) {
;   char* ws = p.ws;
;   __shared__ int s_item;
;   if (ATM & 8) for (int u = lbid(); u < 64; u += gridDim.x) scan_unit(p, u, smem);
	s_cbranch_scc1 .LBB0_99
	v_pk_mul_f32 v[108:109], v[162:163], v[54:55]
	v_pk_fma_f32 v[108:109], v[160:161], v[52:53], v[108:109]
	v_add_f32_e32 v229, v108, v109
	v_add_f32_dpp v178, v220, v220 row_mirror row_mask:0xf bank_mask:0x3
	v_add_f32_dpp v178, v228, v228 row_mirror row_mask:0xf bank_mask:0xc
	v_add_f32_dpp v179, v221, v221 row_mirror row_mask:0xf bank_mask:0x3
	v_add_f32_dpp v179, v229, v229 row_mirror row_mask:0xf bank_mask:0xc
	v_add_f32_dpp v181, v173, v173 row_half_mirror row_mask:0xf bank_mask:0x5
	v_add_f32_dpp v181, v177, v177 row_half_mirror row_mask:0xf bank_mask:0xa
	v_add_f32_dpp v182, v174, v174 row_half_mirror row_mask:0xf bank_mask:0x5
	v_add_f32_dpp v182, v178, v178 row_half_mirror row_mask:0xf bank_mask:0xa
	v_add_f32_dpp v183, v175, v175 row_half_mirror row_mask:0xf bank_mask:0x5
	v_add_f32_dpp v183, v179, v179 row_half_mirror row_mask:0xf bank_mask:0xa
	v_cndmask_b32_e64 v184, v180, v182, s[38:39]
	v_cndmask_b32_e64 v185, v182, v180, s[38:39]
	s_nop 0
	s_nop 0
	v_add_f32_dpp v186, v185, v184 quad_perm:[2,3,0,1] row_mask:0xf bank_mask:0xf bound_ctrl:1
	v_cndmask_b32_e64 v184, v181, v183, s[38:39]
	v_cndmask_b32_e64 v185, v183, v181, s[38:39]
	s_nop 0
	s_nop 0
	v_add_f32_dpp v187, v185, v184 quad_perm:[2,3,0,1] row_mask:0xf bank_mask:0xf bound_ctrl:1
	v_cndmask_b32_e64 v184, v186, v187, s[40:41]
	v_cndmask_b32_e64 v185, v187, v186, s[40:41]
	s_nop 0
	s_nop 0
	v_add_f32_dpp v110, v185, v184 quad_perm:[1,0,3,2] row_mask:0xf bank_mask:0xf bound_ctrl:1
	global_store_dword v111, v110, s[96:97]
	s_waitcnt vmcnt(0)
	s_setprio 0
	v_readlane_b32 s52, v244, 4
	v_readlane_b32 s0, v245, 54
	v_readlane_b32 s56, v244, 8
	v_readlane_b32 s57, v244, 9
	v_readlane_b32 s58, v244, 10
	v_readlane_b32 s59, v244, 11
	v_readlane_b32 s60, v244, 12
	v_readlane_b32 s61, v244, 13
	v_readlane_b32 s62, v244, 14
	v_readlane_b32 s63, v244, 15
	v_readlane_b32 s64, v244, 16
	v_readlane_b32 s65, v244, 17
	s_add_i32 s70, s70, s86
	s_add_i32 s72, s72, s0
	v_readlane_b32 s66, v244, 18
	v_readlane_b32 s67, v244, 19
	v_readlane_b32 s56, v244, 21
	v_readlane_b32 s58, v244, 23
	v_readlane_b32 s60, v244, 25
	v_readlane_b32 s62, v244, 27
	v_readlane_b32 s64, v244, 29
	s_cmp_gt_i32 s70, 63
	v_readlane_b32 s53, v244, 5
	v_readlane_b32 s54, v244, 6
	v_readlane_b32 s55, v244, 7
	v_readlane_b32 s57, v244, 22
	v_readlane_b32 s59, v244, 24
	v_readlane_b32 s61, v244, 26
	v_readlane_b32 s63, v244, 28
	v_readlane_b32 s65, v244, 30
	v_readlane_b32 s66, v244, 31
	v_readlane_b32 s67, v244, 32
	v_readlane_b32 s50, v244, 33
	s_movk_i32 s51, 0x3ff
	v_readlane_b32 s48, v244, 34
	s_cbranch_scc0 .LBB0_62
	s_branch .LBB0_149

; template <int DQK, int NSUB> ...
;     ...
;   for (int t = 0; t < ntiles; ++t) {
;     const bool more = (t + 1 < ntiles);
;     const int k1 = (t + 1) * 64;
;     constexpr bool EARLY = (DQK != 128);
;     if (EARLY && more) {
;       if (!KDMA) {
; #pragma unroll
;         for (int i = 0; i < NKC; ++i) {
;           int c = tid + i * 256, r = c / (DQK / 8), kc = c % (DQK / 8);
;           kreg[i] = *(const u32x4*)(K + (size_t)(k1 + r) * ldk + kc * 8);
;         }
;       }
; #pragma unroll
;       for (int i = 0; i < 4; ++i) {
;         int c = tid + i * 256, r = c >> 3, kc = c & 7;
;         vreg[i] = *(const u32x4*)(Vt + (size_t)r * ldv + k1 + kc * 8);
;       }
;     }
;     f32x4 sacc[4][NSUB];
; #pragma unroll
;     for (int kt = 0; kt < 4; ++kt)
; #pragma unroll
;       for (int sub = 0; sub < NSUB; ++sub) sacc[kt][sub] = (f32x4){0.f, 0.f, 0.f, 0.f};
;     __builtin_amdgcn_s_setprio(1);
; #pragma unroll
;     for (int ks = 0; ks < NKS; ++ks) {
; #pragma unroll
;       for (int kt = 0; kt < 4; ++kt) {
;         bf16x8 kf = *(const bf16x8*)(Ks + (kt * 16 + l15) * LDK + (((ks * 4 + quad) ^ (l15 & SW)) * 8));
; #pragma unroll
;         for (int sub = 0; sub < NSUB; ++sub)
;           sacc[kt][sub] = __builtin_amdgcn_mfma_f32_16x16x32_bf16(kf, qf[sub][ks], sacc[kt][sub], 0, 0, 0);
;       }
;       __builtin_amdgcn_sched_barrier(0);
;     }
;     __builtin_amdgcn_s_setprio(0);
;     float cb = 0.f;
;     if (hasBias) {
;       int kmn = kpmm[t * 2], kmx = kpmm[t * 2 + 1];
;       if (kmn - qpmax >= 128 || kmx - qpmin <= -128) {
;         cb = (kmn - qpmax >= 128) ? bt[256] : bt[0];
;       } else {
.LBB0_179:
	s_add_u32 s42, s96, s30
	s_addc_u32 s43, s97, s31
	global_load_dwordx2 v[160:161], v194, s[42:43] offset:256
	s_and_saveexec_b64 s[36:37], s[38:39]
	s_cbranch_execz .Ldiff_nokp
	v_add_u32_e32 v254, s25, v178
	v_ashrrev_i32_e32 v255, 31, v254
	v_lshl_add_u64 v[254:255], v[254:255], 2, s[0:1]
	global_load_dword v252, v[254:255], off
.Ldiff_nokp:
	s_or_b64 exec, exec, s[36:37]
	v_lshl_add_u64 v[80:81], s[96:97], 0, v[190:191]
	v_lshl_add_u64 v[84:85], s[96:97], 0, v[188:189]
	v_lshl_add_u64 v[88:89], s[96:97], 0, v[180:181]
	v_lshl_add_u64 v[92:93], s[96:97], 0, v[182:183]
	v_lshl_add_u64 v[96:97], s[96:97], 0, v[184:185]
	v_lshl_add_u64 v[100:101], s[96:97], 0, v[186:187]
	global_load_dwordx4 v[80:83], v[80:81], off
	s_nop 0
	global_load_dwordx4 v[84:87], v[84:85], off
	s_nop 0
	global_load_dwordx4 v[88:91], v[88:89], off
	s_nop 0
	global_load_dwordx4 v[92:95], v[92:93], off
	s_nop 0
	global_load_dwordx4 v[96:99], v[96:97], off
	s_nop 0
	global_load_dwordx4 v[100:103], v[100:101], off
	s_setprio 1
	ds_read_b128 v[104:107], v227
	ds_read_b128 v[108:111], v227 offset:2048
	ds_read_b128 v[112:115], v227 offset:4096
	ds_read_b128 v[116:119], v227 offset:6144
	ds_read_b128 v[120:123], v226
	ds_read_b128 v[124:127], v226 offset:2048
	ds_read_b128 v[248:251], v226 offset:4096
	s_waitcnt lgkmcnt(6)
	v_mfma_f32_16x16x32_bf16 v[128:131], v[104:107], v[72:75], 0
	v_mfma_f32_16x16x32_bf16 v[132:135], v[104:107], v[76:79], 0
	ds_read_b128 v[104:107], v226 offset:6144
	s_waitcnt lgkmcnt(6)
	v_mfma_f32_16x16x32_bf16 v[136:139], v[108:111], v[72:75], 0
	v_mfma_f32_16x16x32_bf16 v[140:143], v[108:111], v[76:79], 0
	s_waitcnt lgkmcnt(5)
	v_mfma_f32_16x16x32_bf16 v[144:147], v[112:115], v[72:75], 0
	v_mfma_f32_16x16x32_bf16 v[148:151], v[112:115], v[76:79], 0
	s_waitcnt lgkmcnt(4)
	v_mfma_f32_16x16x32_bf16 v[152:155], v[116:119], v[72:75], 0
	v_mfma_f32_16x16x32_bf16 v[156:159], v[116:119], v[76:79], 0
	s_waitcnt lgkmcnt(3)
	v_mfma_f32_16x16x32_bf16 v[128:131], v[120:123], v[48:51], v[128:131]
	v_mfma_f32_16x16x32_bf16 v[132:135], v[120:123], v[52:55], v[132:135]
	s_waitcnt lgkmcnt(2)
	v_mfma_f32_16x16x32_bf16 v[136:139], v[124:127], v[48:51], v[136:139]
	v_mfma_f32_16x16x32_bf16 v[140:143], v[124:127], v[52:55], v[140:143]
	s_waitcnt lgkmcnt(1)
	v_mfma_f32_16x16x32_bf16 v[144:147], v[248:251], v[48:51], v[144:147]
	v_mfma_f32_16x16x32_bf16 v[148:151], v[248:251], v[52:55], v[148:151]
	s_waitcnt lgkmcnt(0)
	v_mfma_f32_16x16x32_bf16 v[152:155], v[104:107], v[48:51], v[152:155]
	v_mfma_f32_16x16x32_bf16 v[156:159], v[104:107], v[52:55], v[156:159]
	s_setprio 0
	v_mov_b32_e32 v234, 0xb000
	s_waitcnt vmcnt(6)
	v_sub_u32_e32 v104, v160, v218
	v_cmp_lt_i32_e64 s[36:37], s26, v104
	v_cmp_gt_i32_e32 vcc, s35, v104
	s_and_saveexec_b64 s[40:41], vcc
	s_cbranch_execz .LBB0_183
	s_mov_b64 s[44:45], -1
	v_sub_u32_e32 v104, v161, v217
	v_cmp_lt_i32_e32 vcc, s95, v104
	s_and_saveexec_b64 s[42:43], vcc
	s_cbranch_execz .LBB0_182
; template <int DQK, int NSUB> ...
;     ...
; #pragma unroll
;         for (int kt = 0; kt < 4; ++kt) {
; #pragma unroll
;           for (int j = 0; j < 4; ++j) {
;             int kpos = kp[kt * 16 + quad * 4 + j];
; #pragma unroll
;             for (int sub = 0; sub < NSUB; ++sub) {
;               int rel = kpos - qp[sub];
;               rel = max(-128, min(128, rel));
;               sacc[kt][sub][j] += bt[rel + 128];
;             }
;           }
;         }
;       }
	ds_read_b128 v[104:107], v176 offset:45072
	ds_read_b128 v[108:111], v176 offset:45136
	s_xor_b64 s[44:45], exec, -1
	s_waitcnt lgkmcnt(1)
	v_sub_u32_e32 v112, v104, v216
	v_sub_u32_e32 v104, v104, v215
	v_med3_i32 v104, v104, s95, v210
	v_lshlrev_b32_e32 v114, 2, v104
	v_sub_u32_e32 v104, v105, v216
	v_med3_i32 v104, v104, s95, v210
	v_lshlrev_b32_e32 v113, 2, v104
	v_sub_u32_e32 v104, v105, v215
	v_med3_i32 v104, v104, s95, v210
	v_lshlrev_b32_e32 v115, 2, v104
	v_sub_u32_e32 v104, v106, v216
	v_med3_i32 v104, v104, s95, v210
	v_lshlrev_b32_e32 v105, 2, v104
	v_sub_u32_e32 v104, v106, v215
	v_med3_i32 v104, v104, s95, v210
	v_lshlrev_b32_e32 v116, 2, v104
	v_sub_u32_e32 v104, v107, v216
	v_med3_i32 v104, v104, s95, v210
	v_med3_i32 v112, v112, s95, v210
	v_lshlrev_b32_e32 v117, 2, v104
	v_sub_u32_e32 v104, v107, v215
	v_lshlrev_b32_e32 v112, 2, v112
	v_med3_i32 v104, v104, s95, v210
	v_lshlrev_b32_e32 v118, 2, v104
	ds_read_b32 v104, v112 offset:44544
	ds_read_b32 v106, v105 offset:44544
	ds_read_b32 v112, v116 offset:44544
	ds_read_b32 v107, v117 offset:44544
	ds_read_b32 v105, v113 offset:44544
	ds_read_b32 v113, v118 offset:44544
	ds_read_b32 v117, v115 offset:44544
	ds_read_b32 v116, v114 offset:44544
	s_waitcnt lgkmcnt(4)
	v_pk_add_f32 v[106:107], v[130:131], v[106:107]
	s_waitcnt lgkmcnt(3)
	v_pk_add_f32 v[104:105], v[128:129], v[104:105]
	s_waitcnt lgkmcnt(2)
	v_pk_add_f32 v[114:115], v[134:135], v[112:113]
	v_sub_u32_e32 v112, v108, v216
	v_sub_u32_e32 v108, v108, v215
	v_med3_i32 v108, v108, s95, v210
	v_lshlrev_b32_e32 v113, 2, v108
	v_sub_u32_e32 v108, v109, v216
	v_med3_i32 v108, v108, s95, v210
	v_lshlrev_b32_e32 v118, 2, v108
	v_sub_u32_e32 v108, v109, v215
	v_med3_i32 v108, v108, s95, v210
	v_lshlrev_b32_e32 v120, 2, v108
	v_sub_u32_e32 v108, v110, v216
	v_med3_i32 v108, v108, s95, v210
	v_lshlrev_b32_e32 v119, 2, v108
	v_sub_u32_e32 v108, v110, v215
	v_med3_i32 v108, v108, s95, v210
	v_lshlrev_b32_e32 v121, 2, v108
	v_sub_u32_e32 v108, v111, v216
	v_med3_i32 v108, v108, s95, v210
	v_lshlrev_b32_e32 v122, 2, v108
	v_sub_u32_e32 v108, v111, v215
	v_med3_i32 v112, v112, s95, v210
	v_med3_i32 v108, v108, s95, v210
	v_lshlrev_b32_e32 v112, 2, v112
	v_lshlrev_b32_e32 v123, 2, v108
	ds_read_b32 v108, v112 offset:44544
	ds_read_b32 v124, v113 offset:44544
	ds_read_b32 v109, v118 offset:44544
	ds_read_b32 v110, v119 offset:44544
	ds_read_b32 v111, v122 offset:44544
	ds_read_b32 v119, v123 offset:44544
	ds_read_b32 v118, v121 offset:44544
	ds_read_b32 v125, v120 offset:44544
	ds_read_b128 v[120:123], v176 offset:45200
	s_waitcnt lgkmcnt(9)
	v_pk_add_f32 v[112:113], v[132:133], v[116:117]
	s_waitcnt lgkmcnt(4)
	v_pk_add_f32 v[110:111], v[138:139], v[110:111]
	v_pk_add_f32 v[108:109], v[136:137], v[108:109]
	s_waitcnt lgkmcnt(1)
	v_pk_add_f32 v[116:117], v[140:141], v[124:125]
	ds_read_b128 v[124:127], v176 offset:45264
	s_waitcnt lgkmcnt(1)
	v_sub_u32_e32 v160, v120, v216
	v_sub_u32_e32 v120, v120, v215
	v_med3_i32 v120, v120, s95, v210
	v_lshlrev_b32_e32 v161, 2, v120
	v_sub_u32_e32 v120, v121, v216
	v_med3_i32 v120, v120, s95, v210
	v_lshlrev_b32_e32 v162, 2, v120
	v_sub_u32_e32 v120, v121, v215
	v_med3_i32 v120, v120, s95, v210
	v_lshlrev_b32_e32 v164, 2, v120
	v_sub_u32_e32 v120, v122, v216
	v_med3_i32 v120, v120, s95, v210
	v_lshlrev_b32_e32 v121, 2, v120
	v_sub_u32_e32 v120, v122, v215
	v_med3_i32 v120, v120, s95, v210
	v_lshlrev_b32_e32 v165, 2, v120
	v_sub_u32_e32 v120, v123, v216
	v_med3_i32 v120, v120, s95, v210
	v_med3_i32 v160, v160, s95, v210
	v_lshlrev_b32_e32 v163, 2, v120
	v_sub_u32_e32 v120, v123, v215
	v_lshlrev_b32_e32 v160, 2, v160
	v_med3_i32 v120, v120, s95, v210
	v_lshlrev_b32_e32 v166, 2, v120
	ds_read_b32 v120, v160 offset:44544
	ds_read_b32 v160, v161 offset:44544
	ds_read_b32 v122, v121 offset:44544
	ds_read_b32 v123, v163 offset:44544
	ds_read_b32 v121, v162 offset:44544
	ds_read_b32 v163, v166 offset:44544
	ds_read_b32 v162, v165 offset:44544
	ds_read_b32 v161, v164 offset:44544
	s_waitcnt lgkmcnt(8)
	v_sub_u32_e32 v164, v124, v216
	v_sub_u32_e32 v124, v124, v215
	v_med3_i32 v124, v124, s95, v210
	v_lshlrev_b32_e32 v165, 2, v124
	v_sub_u32_e32 v124, v125, v216
	v_med3_i32 v124, v124, s95, v210
	v_lshlrev_b32_e32 v166, 2, v124
	v_sub_u32_e32 v124, v125, v215
	v_med3_i32 v124, v124, s95, v210
	v_lshlrev_b32_e32 v167, 2, v124
	v_sub_u32_e32 v124, v126, v216
	v_med3_i32 v124, v124, s95, v210
	v_lshlrev_b32_e32 v233, 2, v124
	v_sub_u32_e32 v124, v126, v215
	v_med3_i32 v124, v124, s95, v210
	v_lshlrev_b32_e32 v240, 2, v124
	v_sub_u32_e32 v124, v127, v216
	v_med3_i32 v124, v124, s95, v210
	v_med3_i32 v164, v164, s95, v210
	v_lshlrev_b32_e32 v241, 2, v124
	v_sub_u32_e32 v124, v127, v215
	v_lshlrev_b32_e32 v164, 2, v164
	v_med3_i32 v124, v124, s95, v210
	v_lshlrev_b32_e32 v242, 2, v124
	ds_read_b32 v124, v164 offset:44544
	ds_read_b32 v234, v165 offset:44544
	ds_read_b32 v125, v166 offset:44544
	ds_read_b32 v235, v167 offset:44544
	ds_read_b32 v126, v233 offset:44544
	ds_read_b32 v127, v241 offset:44544
	ds_read_b32 v241, v242 offset:44544
	ds_read_b32 v240, v240 offset:44544
	v_pk_add_f32 v[118:119], v[142:143], v[118:119]
	s_waitcnt lgkmcnt(12)
	v_pk_add_f32 v[122:123], v[146:147], v[122:123]
	s_waitcnt lgkmcnt(11)
	v_pk_add_f32 v[120:121], v[144:145], v[120:121]
	s_waitcnt lgkmcnt(9)
	v_pk_add_f32 v[166:167], v[150:151], v[162:163]
	s_waitcnt lgkmcnt(8)
	v_pk_add_f32 v[164:165], v[148:149], v[160:161]
	s_waitcnt lgkmcnt(2)
	v_pk_add_f32 v[126:127], v[154:155], v[126:127]
	v_pk_add_f32 v[124:125], v[152:153], v[124:125]
	s_waitcnt lgkmcnt(0)
	v_pk_add_f32 v[162:163], v[158:159], v[240:241]
	v_pk_add_f32 v[160:161], v[156:157], v[234:235]

; #define LBAR() asm volatile("s_waitcnt lgkmcnt(0)\n\ts_barrier" ::: "memory")
; template <int DQK, int NSUB> ...
;     ...
;     LBAR();
;     if (more) {
;       if (!EARLY) {
; #pragma unroll
;         for (int i = 0; i < NKC; ++i) {
;           int c = tid + i * 256, r = c / (DQK / 8), kc = c % (DQK / 8);
;           kreg[i] = *(const u32x4*)(K + (size_t)(k1 + r) * ldk + kc * 8);
;         }
; #pragma unroll
;         for (int i = 0; i < 4; ++i) {
;           int c = tid + i * 256, r = c >> 3, kc = c & 7;
;           vreg[i] = *(const u32x4*)(Vt + (size_t)r * ldv + k1 + kc * 8);
;         }
;       }
;       if (hasBias && tid < 64) kp[tid] = kposp[k1 + tid];
.LBB0_185:
	s_or_b64 exec, exec, s[40:41]
	s_waitcnt lgkmcnt(0)
	s_barrier
	s_and_saveexec_b64 s[36:37], s[38:39]
	s_cbranch_execz .LBB0_187
	s_waitcnt vmcnt(6)
	ds_write_b32 v225, v252 offset:45072

; template <int DQK, int NSUB> ...
;     ...
;       float mnew = fmaxf(mrow[sub], mx + cb);
;       float alpha = __builtin_amdgcn_exp2f(mrow[sub] - mnew);
;       mrow[sub] = mnew;
;       const float off = cb - mnew;
;       float ps = 0.f;
;       float pv[4][4];
; #pragma unroll
;       for (int kt = 0; kt < 4; ++kt)
; #pragma unroll
;         for (int j = 0; j < 4; ++j) {
;           pv[kt][j] = __builtin_amdgcn_exp2f(sacc[kt][sub][j] + off);
;           ps += pv[kt][j];
;         }
;       lrow[sub] = lrow[sub] * alpha + ps;
; #pragma unroll
;       for (int kb = 0; kb < 2; ++kb) {
;         u32x4 pu = {pack2(pv[2 * kb][0], pv[2 * kb][1]), pack2(pv[2 * kb][2], pv[2 * kb][3]),
;                     pack2(pv[2 * kb + 1][0], pv[2 * kb + 1][1]), pack2(pv[2 * kb + 1][2], pv[2 * kb + 1][3])};
;         pf[sub][kb] = __builtin_bit_cast(bf16x8, pu);
;       }
;       if (__builtin_amdgcn_ballot_w64(alpha != 1.f) != 0) {
; #pragma unroll
;         for (int et = 0; et < 8; ++et) {
;           oacc[et][sub][0] *= alpha; oacc[et][sub][1] *= alpha;
;           oacc[et][sub][2] *= alpha; oacc[et][sub][3] *= alpha;
;         }
;       }
;     }
;     __builtin_amdgcn_s_setprio(1);
; #pragma unroll
;     for (int et = 0; et < 8; ++et) {
; #pragma unroll
;       for (int kb = 0; kb < 2; ++kb) {
;         const u16* vp = Vs + (et * 16 + l15) * 72 + kb * 32 + quad * 4;
;         u32x2 a0 = *(const u32x2*)vp;
;         u32x2 a1 = *(const u32x2*)(vp + 16);
;         u32x4 cu = {a0.x, a0.y, a1.x, a1.y};
;         bf16x8 vb = __builtin_bit_cast(bf16x8, cu);
; #pragma unroll
;         for (int sub = 0; sub < NSUB; ++sub)
;           oacc[et][sub] = __builtin_amdgcn_mfma_f32_16x16x32_bf16(vb, pf[sub][kb], oacc[et][sub], 0, 0, 0);
.LBB0_191:
	v_sub_f32_e32 v129, v233, v132
	v_add_f32_e32 v112, v112, v129
	v_exp_f32_e32 v112, v112
	v_add_f32_e32 v113, v113, v129
	v_exp_f32_e32 v113, v113
	v_add_f32_e32 v114, v114, v129
	v_exp_f32_e32 v114, v114
	v_add_f32_e32 v115, v115, v129
	v_exp_f32_e32 v115, v115
	v_add_f32_e32 v116, v116, v129
	v_add_f32_e32 v133, 0, v112
	v_exp_f32_e32 v116, v116
	v_add_f32_e32 v117, v117, v129
	v_add_f32_e32 v133, v113, v133
	v_exp_f32_e32 v117, v117
	v_add_f32_e32 v118, v118, v129
	v_add_f32_e32 v133, v114, v133
	v_exp_f32_e32 v118, v118
	v_add_f32_e32 v119, v119, v129
	v_add_f32_e32 v133, v115, v133
	v_exp_f32_e32 v119, v119
	v_add_f32_e32 v134, v164, v129
	v_add_f32_e32 v133, v116, v133
	v_exp_f32_e32 v134, v134
	v_add_f32_e32 v135, v165, v129
	v_add_f32_e32 v133, v117, v133
	v_exp_f32_e32 v135, v135
	v_add_f32_e32 v136, v166, v129
	v_add_f32_e32 v133, v118, v133
	v_exp_f32_e32 v136, v136
	v_add_f32_e32 v137, v167, v129
	v_add_f32_e32 v133, v119, v133
	v_exp_f32_e32 v137, v137
	v_add_f32_e32 v138, v160, v129
	v_add_f32_e32 v133, v134, v133
	v_exp_f32_e32 v138, v138
	v_add_f32_e32 v139, v161, v129
	v_add_f32_e32 v133, v135, v133
	v_exp_f32_e32 v139, v139
	v_add_f32_e32 v140, v162, v129
	v_add_f32_e32 v133, v136, v133
	v_exp_f32_e32 v140, v140
	v_add_f32_e32 v129, v163, v129
	v_add_f32_e32 v133, v137, v133
	v_exp_f32_e32 v141, v129
	v_add_f32_e32 v129, v138, v133
	v_add_f32_e32 v129, v139, v129
	v_add_f32_e32 v129, v140, v129
	v_add_f32_e32 v129, v141, v129
	v_fmac_f32_e32 v129, v230, v130
	v_sub_f32_e32 v130, v233, v131
	v_add_f32_e32 v104, v104, v130
	v_exp_f32_e32 v104, v104
	v_add_f32_e32 v105, v105, v130
	v_exp_f32_e32 v105, v105
	v_add_f32_e32 v106, v106, v130
	v_exp_f32_e32 v106, v106
	v_add_f32_e32 v107, v107, v130
	v_exp_f32_e32 v107, v107
	v_add_f32_e32 v108, v108, v130
	v_add_f32_e32 v133, 0, v104
	v_exp_f32_e32 v108, v108
	v_add_f32_e32 v109, v109, v130
	v_add_f32_e32 v133, v105, v133
	v_exp_f32_e32 v109, v109
	v_add_f32_e32 v110, v110, v130
	v_add_f32_e32 v133, v106, v133
	v_exp_f32_e32 v110, v110
	v_add_f32_e32 v111, v111, v130
	v_add_f32_e32 v133, v107, v133
	v_exp_f32_e32 v111, v111
	v_add_f32_e32 v120, v120, v130
	v_add_f32_e32 v133, v108, v133
	v_exp_f32_e32 v120, v120
	v_add_f32_e32 v121, v121, v130
	v_add_f32_e32 v133, v109, v133
	v_exp_f32_e32 v121, v121
	v_add_f32_e32 v122, v122, v130
	v_add_f32_e32 v133, v110, v133
	v_exp_f32_e32 v122, v122
	v_add_f32_e32 v123, v123, v130
	v_add_f32_e32 v133, v111, v133
	v_exp_f32_e32 v123, v123
	v_add_f32_e32 v124, v124, v130
	v_add_f32_e32 v133, v120, v133
	v_exp_f32_e32 v124, v124
	v_add_f32_e32 v125, v125, v130
	v_add_f32_e32 v133, v121, v133
	v_exp_f32_e32 v125, v125
	v_add_f32_e32 v126, v126, v130
	v_add_f32_e32 v133, v122, v133
	v_exp_f32_e32 v126, v126
	v_add_f32_e32 v127, v127, v130
	v_add_f32_e32 v133, v123, v133
	v_exp_f32_e32 v127, v127
	v_add_f32_e32 v130, v124, v133
	v_add_f32_e32 v130, v125, v130
	v_add_f32_e32 v130, v126, v130
	v_add_f32_e32 v130, v127, v130
	v_fmac_f32_e32 v130, v229, v128
	v_cvt_pk_bf16_f32 v112, v112, v113
	v_cvt_pk_bf16_f32 v113, v114, v115
	v_cvt_pk_bf16_f32 v114, v116, v117
	v_cvt_pk_bf16_f32 v115, v118, v119
	v_cvt_pk_bf16_f32 v116, v134, v135
	v_cvt_pk_bf16_f32 v117, v136, v137
	v_cvt_pk_bf16_f32 v118, v138, v139
	v_cvt_pk_bf16_f32 v119, v140, v141
	v_cvt_pk_bf16_f32 v104, v104, v105
	v_cvt_pk_bf16_f32 v105, v106, v107
	v_cvt_pk_bf16_f32 v106, v108, v109
	v_cvt_pk_bf16_f32 v107, v110, v111
	v_cvt_pk_bf16_f32 v108, v120, v121
	v_cvt_pk_bf16_f32 v109, v122, v123
	v_cvt_pk_bf16_f32 v110, v124, v125
	v_cvt_pk_bf16_f32 v111, v126, v127
	s_setprio 1
	v_add_u32_e32 v128, 0x6000, v228
	v_add_u32_e32 v133, 0x6800, v228
	v_add_u32_e32 v134, 0x7000, v228
	v_add_u32_e32 v135, 0x7800, v228
	v_add_u32_e32 v136, 0x8800, v228
	v_add_u32_e32 v137, 0x9000, v228
	v_add_u32_e32 v138, 0x9800, v228
	v_add_u32_e32 v139, 0xa000, v228
	ds_read2_b64 v[120:123], v128 offset0:128 offset1:132
	ds_read2_b64 v[124:127], v128 offset0:136 offset1:140
	ds_read2_b64 v[140:143], v133 offset0:160 offset1:164
	ds_read2_b64 v[144:147], v133 offset0:168 offset1:172
	s_waitcnt lgkmcnt(3)
; #define LBAR() asm volatile("s_waitcnt lgkmcnt(0)\n\ts_barrier" ::: "memory")
; template <int DQK, int NSUB> ...
;     ...
;     __builtin_amdgcn_s_setprio(1);
; #pragma unroll
;     for (int et = 0; et < 8; ++et) {
; #pragma unroll
;       for (int kb = 0; kb < 2; ++kb) {
;         const u16* vp = Vs + (et * 16 + l15) * 72 + kb * 32 + quad * 4;
;         u32x2 a0 = *(const u32x2*)vp;
;         u32x2 a1 = *(const u32x2*)(vp + 16);
;         u32x4 cu = {a0.x, a0.y, a1.x, a1.y};
;         bf16x8 vb = __builtin_bit_cast(bf16x8, cu);
; #pragma unroll
;         for (int sub = 0; sub < NSUB; ++sub)
;           oacc[et][sub] = __builtin_amdgcn_mfma_f32_16x16x32_bf16(vb, pf[sub][kb], oacc[et][sub], 0, 0, 0);
;       }
;       if (et & 1) __builtin_amdgcn_sched_barrier(0);
;     }
;     __builtin_amdgcn_s_setprio(0);
;     if (more) {
;       if (KDMA) {
;         asm volatile("s_waitcnt vmcnt(0)" ::: "memory");
;       } else {
; #pragma unroll
;         for (int i = 0; i < NKC; ++i) {
;           int c = tid + i * 256, r = c / (DQK / 8), kc = c % (DQK / 8);
;           *(u32x4*)(Ks + r * LDK + ((kc ^ (r & SW)) * 8)) = kreg[i];
;         }
;       }
;     }
;     LBAR();
;     if (more) {
; #pragma unroll
;       for (int i = 0; i < 4; ++i) {
;         int c = tid + i * 256, r = c >> 3, kc = c & 7;
;         *(u32x4*)(Vs + r * 72 + kc * 8) = vreg[i];
;       }
;     }
	v_mfma_f32_16x16x32_bf16 v[68:71], v[120:123], v[104:107], v[68:71]
	v_mfma_f32_16x16x32_bf16 v[64:67], v[120:123], v[112:115], v[64:67]
	ds_read2_b64 v[120:123], v134 offset0:192 offset1:196
	s_waitcnt lgkmcnt(3)
	v_mfma_f32_16x16x32_bf16 v[68:71], v[124:127], v[108:111], v[68:71]
	v_mfma_f32_16x16x32_bf16 v[64:67], v[124:127], v[116:119], v[64:67]
	ds_read2_b64 v[124:127], v134 offset0:200 offset1:204
	s_waitcnt lgkmcnt(3)
	v_mfma_f32_16x16x32_bf16 v[60:63], v[140:143], v[104:107], v[60:63]
	v_mfma_f32_16x16x32_bf16 v[56:59], v[140:143], v[112:115], v[56:59]
	ds_read2_b64 v[140:143], v135 offset0:224 offset1:228
	s_waitcnt lgkmcnt(3)
	v_mfma_f32_16x16x32_bf16 v[60:63], v[144:147], v[108:111], v[60:63]
	v_mfma_f32_16x16x32_bf16 v[56:59], v[144:147], v[116:119], v[56:59]
	ds_read2_b64 v[144:147], v135 offset0:232 offset1:236
	s_waitcnt lgkmcnt(3)
	v_mfma_f32_16x16x32_bf16 v[44:47], v[120:123], v[104:107], v[44:47]
	v_mfma_f32_16x16x32_bf16 v[40:43], v[120:123], v[112:115], v[40:43]
	ds_read2_b64 v[120:123], v136 offset1:4
	s_waitcnt lgkmcnt(3)
	v_mfma_f32_16x16x32_bf16 v[44:47], v[124:127], v[108:111], v[44:47]
	v_mfma_f32_16x16x32_bf16 v[40:43], v[124:127], v[116:119], v[40:43]
	ds_read2_b64 v[124:127], v136 offset0:8 offset1:12
	s_waitcnt lgkmcnt(3)
	v_mfma_f32_16x16x32_bf16 v[36:39], v[140:143], v[104:107], v[36:39]
	v_mfma_f32_16x16x32_bf16 v[32:35], v[140:143], v[112:115], v[32:35]
	ds_read2_b64 v[140:143], v137 offset0:32 offset1:36
	s_waitcnt lgkmcnt(3)
	v_mfma_f32_16x16x32_bf16 v[36:39], v[144:147], v[108:111], v[36:39]
	v_mfma_f32_16x16x32_bf16 v[32:35], v[144:147], v[116:119], v[32:35]
	ds_read2_b64 v[144:147], v137 offset0:40 offset1:44
	s_waitcnt lgkmcnt(3)
	v_mfma_f32_16x16x32_bf16 v[28:31], v[120:123], v[104:107], v[28:31]
	v_mfma_f32_16x16x32_bf16 v[24:27], v[120:123], v[112:115], v[24:27]
	ds_read2_b64 v[120:123], v138 offset0:64 offset1:68
	s_waitcnt lgkmcnt(3)
	v_mfma_f32_16x16x32_bf16 v[28:31], v[124:127], v[108:111], v[28:31]
	v_mfma_f32_16x16x32_bf16 v[24:27], v[124:127], v[116:119], v[24:27]
	ds_read2_b64 v[124:127], v138 offset0:72 offset1:76
	s_waitcnt lgkmcnt(3)
	v_mfma_f32_16x16x32_bf16 v[20:23], v[140:143], v[104:107], v[20:23]
	v_mfma_f32_16x16x32_bf16 v[16:19], v[140:143], v[112:115], v[16:19]
	ds_read2_b64 v[140:143], v139 offset0:96 offset1:100
	s_waitcnt lgkmcnt(3)
	v_mfma_f32_16x16x32_bf16 v[20:23], v[144:147], v[108:111], v[20:23]
	v_mfma_f32_16x16x32_bf16 v[16:19], v[144:147], v[116:119], v[16:19]
	ds_read2_b64 v[144:147], v139 offset0:104 offset1:108
	s_waitcnt lgkmcnt(3)
	v_mfma_f32_16x16x32_bf16 v[12:15], v[120:123], v[104:107], v[12:15]
	v_mfma_f32_16x16x32_bf16 v[8:11], v[120:123], v[112:115], v[8:11]
	s_waitcnt lgkmcnt(2)
	v_mfma_f32_16x16x32_bf16 v[12:15], v[124:127], v[108:111], v[12:15]
	v_mfma_f32_16x16x32_bf16 v[8:11], v[124:127], v[116:119], v[8:11]
	s_waitcnt lgkmcnt(1)
	v_mfma_f32_16x16x32_bf16 v[4:7], v[140:143], v[104:107], v[4:7]
	v_mfma_f32_16x16x32_bf16 v[0:3], v[140:143], v[112:115], v[0:3]
	s_waitcnt lgkmcnt(0)
	v_mfma_f32_16x16x32_bf16 v[4:7], v[144:147], v[108:111], v[4:7]
	v_mfma_f32_16x16x32_bf16 v[0:3], v[144:147], v[116:119], v[0:3]
	s_setprio 0
	s_waitcnt vmcnt(4)
	ds_write_b128 v223, v[80:83]
	ds_write_b128 v224, v[84:87]
	s_waitcnt lgkmcnt(0)
	s_barrier
	s_add_u32 s30, s30, 8
	s_addc_u32 s31, s31, 0
	s_add_i32 s25, s25, 64
	v_lshl_add_u64 v[180:181], v[180:181], 0, s[82:83]
	v_lshl_add_u64 v[182:183], v[182:183], 0, s[82:83]
	v_lshl_add_u64 v[184:185], v[184:185], 0, s[82:83]
	v_lshl_add_u64 v[186:187], v[186:187], 0, s[82:83]
	v_lshl_add_u64 v[188:189], v[188:189], 0, s[76:77]
	s_cmpk_eq_i32 s25, 0x1000
	v_lshl_add_u64 v[190:191], v[190:191], 0, s[76:77]
	s_waitcnt vmcnt(0)
	ds_write_b128 v219, v[88:91] offset:25600
	ds_write_b128 v220, v[92:95] offset:25600
	ds_write_b128 v221, v[96:99] offset:25600
	ds_write_b128 v222, v[100:103] offset:25600
	s_cbranch_scc1 .LBB0_193
	v_mov_b32_e32 v231, v132
	v_mov_b32_e32 v232, v131
	v_mov_b32_e32 v230, v129
	v_mov_b32_e32 v229, v130
	s_branch .LBB0_179

; __device__ __forceinline__ float lo2f(unsigned u) { return __uint_as_float(u << 16); }
; __device__ __forceinline__ float hi2f(unsigned u) { return __uint_as_float(u & 0xffff0000u); }
; __device__ __forceinline__ void seg_norm8(u16* ptr, bool active, int width, float inv_n, const float* g, float scale) {
;   uint4 v = make_uint4(0, 0, 0, 0);
;   if (active) v = *(const uint4*)ptr;
;   float x[8] = {lo2f(v.x), hi2f(v.x), lo2f(v.y), hi2f(v.y), lo2f(v.z), hi2f(v.z), lo2f(v.w), hi2f(v.w)};
;   float ss = 0.f;
; #pragma unroll
;   for (int i = 0; i < 8; ++i) ss += x[i] * x[i];
;   for (int o = 1; o < width; o <<= 1) ss += __shfl_xor(ss, o);
;   float rs = rsqrtf(ss * inv_n + 1e-6f) * scale;
;   if (active) {
;     float4 g0 = *(const float4*)g, g1 = *(const float4*)(g + 4);
;     uint4 o;
;     o.x = pack2(x[0] * rs * g0.x, x[1] * rs * g0.y);
;     o.y = pack2(x[2] * rs * g0.z, x[3] * rs * g0.w);
;     o.z = pack2(x[4] * rs * g1.x, x[5] * rs * g1.y);
;     o.w = pack2(x[6] * rs * g1.z, x[7] * rs * g1.w);
;     *(uint4*)ptr = o;
;   }
; }
; template <bool RWONLY>
; __device__ __forceinline__ void phase_prep(const Params p, int l, char* smem) {
;   char* ws = p.ws;
;   const int tid = ltid(), lane = tid & 63, w = tid >> 6;
;   u16* P = (u16*)(ws + OFF_P);
;   if (!RWONLY) {
;     const float* dqg = (const float*)p.in[I_DQKG] + l * 128;
;     const float* mqg = (const float*)p.in[I_MQKG] + l * 256;
;     const float* qlg = (const float*)p.in[I_QLATG] + l * 384;
;     const float* kvg = (const float*)p.in[I_KVLATG] + l * 256;
;     for (int s = lbid() * 4 + w; s < S_; s += gridDim.x * 4) {
;       u16* row = P + (size_t)s * NINP;
;       seg_norm8(row + O_DQ + lane * 8, true, 8, 1.f / 64, dqg + (lane * 8) % 64, 0.125f * LOG2E);
;       seg_norm8(row + O_DK + lane * 8, true, 8, 1.f / 64, dqg + 64 + (lane * 8) % 64, 1.f);
;       seg_norm8(row + O_MQ + lane * 8, true, 16, 1.f / 128, mqg + (lane * 8) % 128, 0.08838834764831845f * LOG2E);
;       seg_norm8(row + O_QL + (lane < 48 ? lane : 0) * 8, lane < 48, 64, 1.f / 384, qlg + (lane < 48 ? lane : 0) * 8, 1.f);
;       seg_norm8(row + O_KVL + (lane < 32 ? lane : 0) * 8, lane < 32, 64, 1.f / 256, kvg + (lane < 32 ? lane : 0) * 8, 1.f);
;     }
.LBB0_313:
	s_andn2_b64 vcc, exec, s[0:1]
	s_cbranch_vccnz .LBB0_532
	v_readlane_b32 s0, v244, 45
	s_cmp_gt_i32 s0, 0
	s_mov_b64 s[0:1], -1
	s_cbranch_scc0 .LBB0_497
	s_waitcnt vmcnt(4)
	v_mov_b32_e32 v8, v171
	s_mov_b32 s0, s73
	s_nop 0
	v_ashrrev_i32_e32 v160, 6, v8
	v_lshl_add_u32 v9, s0, 2, v160
	s_movk_i32 s0, 0x2000
	s_waitcnt vmcnt(3)
	v_and_b32_e32 v12, 63, v8
	v_cmp_gt_i32_e32 vcc, s0, v9
	s_and_saveexec_b64 s[2:3], vcc
	v_readlane_b32 s30, v247, 62
	v_readlane_b32 s52, v246, 13
	v_readlane_b32 s31, v247, 63
	v_readlane_b32 s53, v246, 14
	s_movk_i32 s54, 0x1fff
	s_mov_b64 s[56:57], 0x1a00
	v_readlane_b32 s55, v244, 42
	s_cbranch_execz .LBB0_326
	v_readlane_b32 s0, v244, 43
	v_readlane_b32 s1, v244, 44
	s_mov_b32 s24, s0
	s_lshl_b32 s0, s0, 8
	s_ashr_i32 s1, s0, 31
	v_readlane_b32 s36, v247, 12
	s_lshl_b64 s[0:1], s[0:1], 2
	v_readlane_b32 s38, v247, 14
	v_readlane_b32 s39, v247, 15
	s_add_u32 s20, s38, s0
	s_mul_i32 s22, s24, 0x180
	s_addc_u32 s21, s39, s1
	s_ashr_i32 s23, s22, 31
	s_lshl_b64 s[22:23], s[22:23], 2
	v_readlane_b32 s37, v247, 13
	v_readlane_b32 s40, v247, 16
	v_readlane_b32 s41, v247, 17
	v_readlane_b32 s42, v247, 18
	v_readlane_b32 s43, v247, 19
	s_add_u32 s22, s36, s22
	s_addc_u32 s23, s37, s23
	v_readlane_b32 s36, v247, 0
	v_readlane_b32 s37, v247, 1
	s_add_u32 s0, s36, s0
	s_addc_u32 s1, s37, s1
	s_lshl_b32 s24, s24, 7
	s_ashr_i32 s25, s24, 31
	s_lshl_b64 s[24:25], s[24:25], 2
	s_add_u32 s24, s12, s24
	v_lshlrev_b32_e32 v1, 5, v12
	s_addc_u32 s25, s13, s25
	v_and_b32_e32 v168, 0xe0, v1
	v_lshl_add_u64 v[10:11], s[24:25], 0, v[168:169]
	v_and_b32_e32 v168, 0x1e0, v1
	s_waitcnt lgkmcnt(0)
	v_lshl_add_u64 v[14:15], s[0:1], 0, v[168:169]
	v_cmp_lt_i32_e64 s[0:1], v204, v198
	v_readlane_b32 s38, v247, 2
	v_readlane_b32 s39, v247, 3
	v_cndmask_b32_e64 v1, v197, v204, s[0:1]
	v_cmp_lt_i32_e64 s[0:1], v203, v198
	v_lshlrev_b32_e32 v13, 2, v1
	v_lshlrev_b32_e32 v0, 3, v12
	v_cndmask_b32_e64 v1, v197, v203, s[0:1]
	v_cmp_lt_i32_e64 s[0:1], v202, v198
	v_cmp_gt_u32_e32 vcc, 48, v12
	v_lshlrev_b32_e32 v44, 2, v1
	v_cndmask_b32_e64 v1, v197, v202, s[0:1]
	v_cmp_lt_i32_e64 s[0:1], v201, v198
	v_cndmask_b32_e32 v2, 0, v0, vcc
	v_cmp_gt_u32_e64 s[38:39], 32, v12
	v_lshlrev_b32_e32 v45, 2, v1
	v_cndmask_b32_e64 v1, v197, v201, s[0:1]
	v_cmp_lt_i32_e64 s[0:1], v200, v198
	v_lshlrev_b32_e32 v168, 2, v2
	v_cndmask_b32_e64 v4, 0, v0, s[38:39]
	v_lshlrev_b32_e32 v46, 2, v1
	v_cndmask_b32_e64 v1, v197, v200, s[0:1]
	v_cmp_lt_i32_e64 s[0:1], v199, v198
	v_readlane_b32 s48, v247, 24
	v_readlane_b32 s50, v247, 26
	v_readlane_b32 s51, v247, 27
	s_waitcnt vmcnt(2)
	v_lshl_add_u64 v[16:17], s[22:23], 0, v[168:169]
	v_lshlrev_b32_e32 v168, 2, v4
	v_lshlrev_b32_e32 v47, 2, v1
	v_cndmask_b32_e64 v1, v197, v199, s[0:1]
	v_readlane_b32 s48, v244, 34
	s_movk_i32 s51, 0x3ff
	v_readlane_b32 s50, v244, 33
	v_lshl_add_u64 v[18:19], s[20:21], 0, v[168:169]
	v_lshlrev_b32_e32 v48, 2, v1
	s_mov_b64 s[20:21], 0
	v_lshlrev_b32_e32 v168, 1, v0
	s_waitcnt vmcnt(1)
	v_lshlrev_b32_e32 v20, 1, v2
	v_lshlrev_b32_e32 v22, 1, v4
	v_readlane_b32 s44, v247, 20
	v_readlane_b32 s45, v247, 21
	v_readlane_b32 s46, v247, 22
	v_readlane_b32 s47, v247, 23
	v_readlane_b32 s49, v247, 25
	v_readlane_b32 s40, v247, 4
	v_readlane_b32 s41, v247, 5
	v_readlane_b32 s42, v247, 6
	v_readlane_b32 s43, v247, 7
	s_cmpk_lg_u32 s72, 0x800
	s_cbranch_scc1 .LBB0_318
	v_readlane_b32 s0, v246, 6
	v_readlane_b32 s1, v246, 7
	s_nop 1
	v_mov_b64_e32 v[66:67], s[0:1]
	global_load_dwordx4 v[124:127], v[10:11], off
	global_load_dwordx4 v[128:131], v[10:11], off offset:16
	global_load_dwordx4 v[132:135], v[10:11], off offset:256
	global_load_dwordx4 v[136:139], v[10:11], off offset:272
	global_load_dwordx4 v[140:143], v[14:15], off
	global_load_dwordx4 v[144:147], v[14:15], off offset:16
	global_load_dwordx4 v[148:151], v[16:17], off
	global_load_dwordx4 v[152:155], v[16:17], off offset:16
	global_load_dwordx4 v[156:159], v[18:19], off
	global_load_dwordx4 v[164:167], v[18:19], off offset:16
	v_mov_b32_e32 v163, v9
	v_mad_i64_i32 v[108:109], s[0:1], v163, s88, v[66:67]
	v_mov_b32_e32 v111, v169
	v_mov_b32_e32 v110, v20
	v_lshl_add_u64 v[112:113], v[108:109], 0, v[110:111]
	v_mov_b32_e32 v110, v22
	v_lshl_add_u64 v[114:115], v[108:109], 0, v[110:111]
	v_mov_b32_e32 v110, v168
	v_lshl_add_u64 v[108:109], v[108:109], 0, v[110:111]
	s_mov_b64 s[0:1], 0x1a00
	v_lshl_add_u64 v[112:113], v[112:113], 0, s[0:1]
	s_mov_b64 s[0:1], 0x1d00
	v_lshl_add_u64 v[114:115], v[114:115], 0, s[0:1]
	s_mov_b64 s[0:1], 0x1000
	v_lshl_add_u64 v[110:111], v[108:109], 0, s[0:1]
	v_mov_b32_e32 v80, 0
	v_mov_b32_e32 v81, 0
	v_mov_b32_e32 v82, 0
	v_mov_b32_e32 v83, 0
	v_mov_b32_e32 v84, 0
	v_mov_b32_e32 v85, 0
	v_mov_b32_e32 v86, 0
	v_mov_b32_e32 v87, 0
	global_load_dwordx4 v[68:71], v[108:109], off offset:3584
	global_load_dwordx4 v[72:75], v[110:111], off offset:512
	global_load_dwordx4 v[76:79], v[110:111], off offset:3968
	s_and_saveexec_b64 s[22:23], vcc
	global_load_dwordx4 v[80:83], v[112:113], off
	s_mov_b64 exec, s[22:23]
	s_and_saveexec_b64 s[22:23], s[38:39]
	global_load_dwordx4 v[84:87], v[114:115], off
	s_mov_b64 exec, s[22:23]
	s_mul_i32 s0, s72, 1
	v_add_u32_e32 v163, s0, v9
	v_mad_i64_i32 v[116:117], s[0:1], v163, s88, v[66:67]
	v_mov_b32_e32 v119, v169
	v_mov_b32_e32 v118, v20
	v_lshl_add_u64 v[120:121], v[116:117], 0, v[118:119]
	v_mov_b32_e32 v118, v22
	v_lshl_add_u64 v[122:123], v[116:117], 0, v[118:119]
	v_mov_b32_e32 v118, v168
	v_lshl_add_u64 v[116:117], v[116:117], 0, v[118:119]
	s_mov_b64 s[0:1], 0x1a00
	v_lshl_add_u64 v[120:121], v[120:121], 0, s[0:1]
	s_mov_b64 s[0:1], 0x1d00
	v_lshl_add_u64 v[122:123], v[122:123], 0, s[0:1]
	s_mov_b64 s[0:1], 0x1000
	v_lshl_add_u64 v[118:119], v[116:117], 0, s[0:1]
	v_mov_b32_e32 v100, 0
	v_mov_b32_e32 v101, 0
	v_mov_b32_e32 v102, 0
	v_mov_b32_e32 v103, 0
	v_mov_b32_e32 v104, 0
	v_mov_b32_e32 v105, 0
	v_mov_b32_e32 v106, 0
	v_mov_b32_e32 v107, 0
	global_load_dwordx4 v[88:91], v[116:117], off offset:3584
	global_load_dwordx4 v[92:95], v[118:119], off offset:512
	global_load_dwordx4 v[96:99], v[118:119], off offset:3968
	s_and_saveexec_b64 s[22:23], vcc
	global_load_dwordx4 v[100:103], v[120:121], off
	s_mov_b64 exec, s[22:23]
	s_and_saveexec_b64 s[22:23], s[38:39]
	global_load_dwordx4 v[104:107], v[122:123], off
	s_mov_b64 exec, s[22:23]
	s_waitcnt vmcnt(5)
; __device__ __forceinline__ float lo2f(unsigned u) { return __uint_as_float(u << 16); }
; __device__ __forceinline__ float hi2f(unsigned u) { return __uint_as_float(u & 0xffff0000u); }
; __device__ __forceinline__ void seg_norm8(u16* ptr, bool active, int width, float inv_n, const float* g, float scale) {
;   uint4 v = make_uint4(0, 0, 0, 0);
;   if (active) v = *(const uint4*)ptr;
;   float x[8] = {lo2f(v.x), hi2f(v.x), lo2f(v.y), hi2f(v.y), lo2f(v.z), hi2f(v.z), lo2f(v.w), hi2f(v.w)};
;   float ss = 0.f;
; #pragma unroll
;   for (int i = 0; i < 8; ++i) ss += x[i] * x[i];
;   for (int o = 1; o < width; o <<= 1) ss += __shfl_xor(ss, o);
;   float rs = rsqrtf(ss * inv_n + 1e-6f) * scale;
	v_lshlrev_b32_e32 v172, 16, v68
	v_and_b32_e32 v173, 0xffff0000, v68
	v_lshlrev_b32_e32 v174, 16, v69
	v_and_b32_e32 v175, 0xffff0000, v69
	v_lshlrev_b32_e32 v176, 16, v70
	v_and_b32_e32 v177, 0xffff0000, v70
	v_lshlrev_b32_e32 v178, 16, v71
	v_and_b32_e32 v179, 0xffff0000, v71
	v_lshlrev_b32_e32 v180, 16, v72
	v_and_b32_e32 v181, 0xffff0000, v72
	v_lshlrev_b32_e32 v182, 16, v73
	v_and_b32_e32 v183, 0xffff0000, v73
	v_lshlrev_b32_e32 v184, 16, v74
	v_and_b32_e32 v185, 0xffff0000, v74
	v_lshlrev_b32_e32 v186, 16, v75
	v_and_b32_e32 v187, 0xffff0000, v75
	v_lshlrev_b32_e32 v188, 16, v76
	v_and_b32_e32 v189, 0xffff0000, v76
	v_lshlrev_b32_e32 v190, 16, v77
	v_and_b32_e32 v191, 0xffff0000, v77
	v_lshlrev_b32_e32 v214, 16, v78
	v_and_b32_e32 v215, 0xffff0000, v78
	v_lshlrev_b32_e32 v216, 16, v79
	v_and_b32_e32 v217, 0xffff0000, v79
	v_lshlrev_b32_e32 v218, 16, v80
	v_and_b32_e32 v219, 0xffff0000, v80
	v_lshlrev_b32_e32 v220, 16, v81
	v_and_b32_e32 v221, 0xffff0000, v81
	v_lshlrev_b32_e32 v222, 16, v82
	v_and_b32_e32 v223, 0xffff0000, v82
	v_lshlrev_b32_e32 v224, 16, v83
	v_and_b32_e32 v225, 0xffff0000, v83
	v_lshlrev_b32_e32 v226, 16, v84
	v_and_b32_e32 v227, 0xffff0000, v84
	v_lshlrev_b32_e32 v228, 16, v85
	v_and_b32_e32 v229, 0xffff0000, v85
	v_lshlrev_b32_e32 v230, 16, v86
	v_and_b32_e32 v231, 0xffff0000, v86
	v_lshlrev_b32_e32 v232, 16, v87
	v_and_b32_e32 v233, 0xffff0000, v87
	v_pk_mul_f32 v[234:235], v[172:173], v[172:173]
	v_pk_mul_f32 v[240:241], v[180:181], v[180:181]
	v_pk_mul_f32 v[242:243], v[188:189], v[188:189]
	v_pk_mul_f32 v[248:249], v[218:219], v[218:219]
	v_pk_mul_f32 v[250:251], v[226:227], v[226:227]
	v_pk_fma_f32 v[234:235], v[174:175], v[174:175], v[234:235]
	v_pk_fma_f32 v[240:241], v[182:183], v[182:183], v[240:241]
	v_pk_fma_f32 v[242:243], v[190:191], v[190:191], v[242:243]
	v_pk_fma_f32 v[248:249], v[220:221], v[220:221], v[248:249]
	v_pk_fma_f32 v[250:251], v[228:229], v[228:229], v[250:251]
	v_pk_fma_f32 v[234:235], v[176:177], v[176:177], v[234:235]
	v_pk_fma_f32 v[240:241], v[184:185], v[184:185], v[240:241]
	v_pk_fma_f32 v[242:243], v[214:215], v[214:215], v[242:243]
	v_pk_fma_f32 v[248:249], v[222:223], v[222:223], v[248:249]
	v_pk_fma_f32 v[250:251], v[230:231], v[230:231], v[250:251]
	v_pk_fma_f32 v[234:235], v[178:179], v[178:179], v[234:235]
	v_pk_fma_f32 v[240:241], v[186:187], v[186:187], v[240:241]
	v_pk_fma_f32 v[242:243], v[216:217], v[216:217], v[242:243]
	v_pk_fma_f32 v[248:249], v[224:225], v[224:225], v[248:249]
	v_pk_fma_f32 v[250:251], v[232:233], v[232:233], v[250:251]
	v_add_f32_e32 v234, v234, v235
	v_add_f32_e32 v240, v240, v241
	v_add_f32_e32 v242, v242, v243
	v_add_f32_e32 v248, v248, v249
	v_add_f32_e32 v250, v250, v251
	v_add_f32_dpp v234, v234, v234 quad_perm:[1,0,3,2] row_mask:0xf bank_mask:0xf bound_ctrl:1
	v_add_f32_dpp v240, v240, v240 quad_perm:[1,0,3,2] row_mask:0xf bank_mask:0xf bound_ctrl:1
	v_add_f32_dpp v242, v242, v242 quad_perm:[1,0,3,2] row_mask:0xf bank_mask:0xf bound_ctrl:1
	v_add_f32_dpp v248, v248, v248 quad_perm:[1,0,3,2] row_mask:0xf bank_mask:0xf bound_ctrl:1
	v_add_f32_dpp v250, v250, v250 quad_perm:[1,0,3,2] row_mask:0xf bank_mask:0xf bound_ctrl:1
	v_add_f32_dpp v234, v234, v234 quad_perm:[2,3,0,1] row_mask:0xf bank_mask:0xf bound_ctrl:1
	v_add_f32_dpp v240, v240, v240 quad_perm:[2,3,0,1] row_mask:0xf bank_mask:0xf bound_ctrl:1
	v_add_f32_dpp v242, v242, v242 quad_perm:[2,3,0,1] row_mask:0xf bank_mask:0xf bound_ctrl:1
	v_add_f32_dpp v248, v248, v248 quad_perm:[2,3,0,1] row_mask:0xf bank_mask:0xf bound_ctrl:1
	v_add_f32_dpp v250, v250, v250 quad_perm:[2,3,0,1] row_mask:0xf bank_mask:0xf bound_ctrl:1
	v_add_f32_dpp v234, v234, v234 row_half_mirror row_mask:0xf bank_mask:0xf bound_ctrl:1
	v_add_f32_dpp v240, v240, v240 row_half_mirror row_mask:0xf bank_mask:0xf bound_ctrl:1
	v_add_f32_dpp v242, v242, v242 row_half_mirror row_mask:0xf bank_mask:0xf bound_ctrl:1
	v_add_f32_dpp v248, v248, v248 row_half_mirror row_mask:0xf bank_mask:0xf bound_ctrl:1
	v_add_f32_dpp v250, v250, v250 row_half_mirror row_mask:0xf bank_mask:0xf bound_ctrl:1
	v_add_f32_dpp v242, v242, v242 row_mirror row_mask:0xf bank_mask:0xf bound_ctrl:1
	v_add_f32_dpp v248, v248, v248 row_mirror row_mask:0xf bank_mask:0xf bound_ctrl:1
	v_add_f32_dpp v250, v250, v250 row_mirror row_mask:0xf bank_mask:0xf bound_ctrl:1
	ds_bpermute_b32 v161, v47, v248
	ds_bpermute_b32 v162, v47, v250
	s_waitcnt lgkmcnt(0)
	v_add_f32_e32 v248, v248, v161
	v_add_f32_e32 v250, v250, v162
	ds_bpermute_b32 v161, v48, v248
	ds_bpermute_b32 v162, v48, v250
	s_waitcnt lgkmcnt(0)
; __device__ __forceinline__ void seg_norm8(u16* ptr, bool active, int width, float inv_n, const float* g, float scale) {
;     ...
;   float rs = rsqrtf(ss * inv_n + 1e-6f) * scale;
;   if (active) {
;     float4 g0 = *(const float4*)g, g1 = *(const float4*)(g + 4);
;     uint4 o;
;     o.x = pack2(x[0] * rs * g0.x, x[1] * rs * g0.y);
;     o.y = pack2(x[2] * rs * g0.z, x[3] * rs * g0.w);
;     o.z = pack2(x[4] * rs * g1.x, x[5] * rs * g1.y);
;     o.w = pack2(x[6] * rs * g1.z, x[7] * rs * g1.w);
;     *(uint4*)ptr = o;
;   }
; }
; template <bool RWONLY>
; __device__ __forceinline__ void phase_prep(const Params p, int l, char* smem) {
;   char* ws = p.ws;
;   const int tid = ltid(), lane = tid & 63, w = tid >> 6;
;   u16* P = (u16*)(ws + OFF_P);
;   if (!RWONLY) {
;     const float* dqg = (const float*)p.in[I_DQKG] + l * 128;
;     const float* mqg = (const float*)p.in[I_MQKG] + l * 256;
;     const float* qlg = (const float*)p.in[I_QLATG] + l * 384;
;     const float* kvg = (const float*)p.in[I_KVLATG] + l * 256;
;     for (int s = lbid() * 4 + w; s < S_; s += gridDim.x * 4) {
;       u16* row = P + (size_t)s * NINP;
;       seg_norm8(row + O_DQ + lane * 8, true, 8, 1.f / 64, dqg + (lane * 8) % 64, 0.125f * LOG2E);
;       seg_norm8(row + O_DK + lane * 8, true, 8, 1.f / 64, dqg + 64 + (lane * 8) % 64, 1.f);
;       seg_norm8(row + O_MQ + lane * 8, true, 16, 1.f / 128, mqg + (lane * 8) % 128, 0.08838834764831845f * LOG2E);
;       seg_norm8(row + O_QL + (lane < 48 ? lane : 0) * 8, lane < 48, 64, 1.f / 384, qlg + (lane < 48 ? lane : 0) * 8, 1.f);
;       seg_norm8(row + O_KVL + (lane < 32 ? lane : 0) * 8, lane < 32, 64, 1.f / 256, kvg + (lane < 32 ? lane : 0) * 8, 1.f);
;     }
	v_add_f32_e32 v248, v248, v161
	v_add_f32_e32 v250, v250, v162
	v_fmamk_f32 v234, v234, 0x3c800000, v170
	v_fmamk_f32 v240, v240, 0x3c800000, v170
	v_fmamk_f32 v242, v242, 0x3c000000, v170
	v_fmamk_f32 v248, v248, 0x3b2aaaab, v170
	v_fmamk_f32 v250, v250, 0x3b800000, v170
	v_rsq_f32_e32 v234, v234
	v_rsq_f32_e32 v240, v240
	v_rsq_f32_e32 v242, v242
	v_rsq_f32_e32 v248, v248
	v_rsq_f32_e32 v250, v250
	s_nop 0
	v_mul_f32_e32 v234, 0x3e38aa3b, v234
	v_mul_f32_e32 v242, 0x3e0293ee, v242
	v_pk_mul_f32 v[172:173], v[234:235], v[172:173] op_sel_hi:[0,1]
	v_pk_mul_f32 v[174:175], v[234:235], v[174:175] op_sel_hi:[0,1]
	v_pk_mul_f32 v[176:177], v[234:235], v[176:177] op_sel_hi:[0,1]
	v_pk_mul_f32 v[178:179], v[234:235], v[178:179] op_sel_hi:[0,1]
	v_pk_mul_f32 v[172:173], v[124:125], v[172:173]
	v_pk_mul_f32 v[174:175], v[126:127], v[174:175]
	v_pk_mul_f32 v[176:177], v[128:129], v[176:177]
	v_pk_mul_f32 v[178:179], v[130:131], v[178:179]
	v_cvt_pk_bf16_f32 v252, v172, v173
	v_cvt_pk_bf16_f32 v253, v174, v175
	v_cvt_pk_bf16_f32 v254, v176, v177
	v_cvt_pk_bf16_f32 v255, v178, v179
	global_store_dwordx4 v[108:109], v[252:255], off offset:3584
	v_pk_mul_f32 v[180:181], v[240:241], v[180:181] op_sel_hi:[0,1]
	v_pk_mul_f32 v[182:183], v[240:241], v[182:183] op_sel_hi:[0,1]
	v_pk_mul_f32 v[184:185], v[240:241], v[184:185] op_sel_hi:[0,1]
	v_pk_mul_f32 v[186:187], v[240:241], v[186:187] op_sel_hi:[0,1]
	v_pk_mul_f32 v[180:181], v[132:133], v[180:181]
	v_pk_mul_f32 v[182:183], v[134:135], v[182:183]
	v_pk_mul_f32 v[184:185], v[136:137], v[184:185]
	v_pk_mul_f32 v[186:187], v[138:139], v[186:187]
	v_cvt_pk_bf16_f32 v252, v180, v181
	v_cvt_pk_bf16_f32 v253, v182, v183
	v_cvt_pk_bf16_f32 v254, v184, v185
	v_cvt_pk_bf16_f32 v255, v186, v187
	global_store_dwordx4 v[110:111], v[252:255], off offset:512
	v_pk_mul_f32 v[188:189], v[242:243], v[188:189] op_sel_hi:[0,1]
	v_pk_mul_f32 v[190:191], v[242:243], v[190:191] op_sel_hi:[0,1]
	v_pk_mul_f32 v[214:215], v[242:243], v[214:215] op_sel_hi:[0,1]
	v_pk_mul_f32 v[216:217], v[242:243], v[216:217] op_sel_hi:[0,1]
	v_pk_mul_f32 v[188:189], v[140:141], v[188:189]
	v_pk_mul_f32 v[190:191], v[142:143], v[190:191]
	v_pk_mul_f32 v[214:215], v[144:145], v[214:215]
	v_pk_mul_f32 v[216:217], v[146:147], v[216:217]
	v_cvt_pk_bf16_f32 v252, v188, v189
	v_cvt_pk_bf16_f32 v253, v190, v191
	v_cvt_pk_bf16_f32 v254, v214, v215
	v_cvt_pk_bf16_f32 v255, v216, v217
	global_store_dwordx4 v[110:111], v[252:255], off offset:3968
	v_pk_mul_f32 v[218:219], v[248:249], v[218:219] op_sel_hi:[0,1]
	v_pk_mul_f32 v[220:221], v[248:249], v[220:221] op_sel_hi:[0,1]
	v_pk_mul_f32 v[222:223], v[248:249], v[222:223] op_sel_hi:[0,1]
	v_pk_mul_f32 v[224:225], v[248:249], v[224:225] op_sel_hi:[0,1]
	v_pk_mul_f32 v[218:219], v[148:149], v[218:219]
	v_pk_mul_f32 v[220:221], v[150:151], v[220:221]
	v_pk_mul_f32 v[222:223], v[152:153], v[222:223]
	v_pk_mul_f32 v[224:225], v[154:155], v[224:225]
	v_cvt_pk_bf16_f32 v252, v218, v219
	v_cvt_pk_bf16_f32 v253, v220, v221
	v_cvt_pk_bf16_f32 v254, v222, v223
	v_cvt_pk_bf16_f32 v255, v224, v225
	s_and_saveexec_b64 s[22:23], vcc
	global_store_dwordx4 v[112:113], v[252:255], off
	s_mov_b64 exec, s[22:23]
	v_pk_mul_f32 v[226:227], v[250:251], v[226:227] op_sel_hi:[0,1]
	v_pk_mul_f32 v[228:229], v[250:251], v[228:229] op_sel_hi:[0,1]
	v_pk_mul_f32 v[230:231], v[250:251], v[230:231] op_sel_hi:[0,1]
	v_pk_mul_f32 v[232:233], v[250:251], v[232:233] op_sel_hi:[0,1]
	v_pk_mul_f32 v[226:227], v[156:157], v[226:227]
	v_pk_mul_f32 v[228:229], v[158:159], v[228:229]
	v_pk_mul_f32 v[230:231], v[164:165], v[230:231]
	v_pk_mul_f32 v[232:233], v[166:167], v[232:233]
	v_cvt_pk_bf16_f32 v252, v226, v227
	v_cvt_pk_bf16_f32 v253, v228, v229
	v_cvt_pk_bf16_f32 v254, v230, v231
	v_cvt_pk_bf16_f32 v255, v232, v233
	s_and_saveexec_b64 s[22:23], s[38:39]
	global_store_dwordx4 v[114:115], v[252:255], off
	s_mov_b64 exec, s[22:23]
	s_mul_i32 s0, s72, 2
	v_add_u32_e32 v163, s0, v9
	v_mad_i64_i32 v[108:109], s[0:1], v163, s88, v[66:67]
	v_mov_b32_e32 v111, v169
	v_mov_b32_e32 v110, v20
	v_lshl_add_u64 v[112:113], v[108:109], 0, v[110:111]
	v_mov_b32_e32 v110, v22
	v_lshl_add_u64 v[114:115], v[108:109], 0, v[110:111]
	v_mov_b32_e32 v110, v168
	v_lshl_add_u64 v[108:109], v[108:109], 0, v[110:111]
	s_mov_b64 s[0:1], 0x1a00
	v_lshl_add_u64 v[112:113], v[112:113], 0, s[0:1]
	s_mov_b64 s[0:1], 0x1d00
	v_lshl_add_u64 v[114:115], v[114:115], 0, s[0:1]
	s_mov_b64 s[0:1], 0x1000
	v_lshl_add_u64 v[110:111], v[108:109], 0, s[0:1]
	v_mov_b32_e32 v80, 0
	v_mov_b32_e32 v81, 0
	v_mov_b32_e32 v82, 0
	v_mov_b32_e32 v83, 0
	v_mov_b32_e32 v84, 0
	v_mov_b32_e32 v85, 0
	v_mov_b32_e32 v86, 0
	v_mov_b32_e32 v87, 0
	global_load_dwordx4 v[68:71], v[108:109], off offset:3584
	global_load_dwordx4 v[72:75], v[110:111], off offset:512
	global_load_dwordx4 v[76:79], v[110:111], off offset:3968
	s_and_saveexec_b64 s[22:23], vcc
	global_load_dwordx4 v[80:83], v[112:113], off
	s_mov_b64 exec, s[22:23]
	s_and_saveexec_b64 s[22:23], s[38:39]
	global_load_dwordx4 v[84:87], v[114:115], off
	s_mov_b64 exec, s[22:23]
	s_waitcnt vmcnt(10)
; __device__ __forceinline__ float lo2f(unsigned u) { return __uint_as_float(u << 16); }
; __device__ __forceinline__ float hi2f(unsigned u) { return __uint_as_float(u & 0xffff0000u); }
; __device__ __forceinline__ void seg_norm8(u16* ptr, bool active, int width, float inv_n, const float* g, float scale) {
;   uint4 v = make_uint4(0, 0, 0, 0);
;   if (active) v = *(const uint4*)ptr;
;   float x[8] = {lo2f(v.x), hi2f(v.x), lo2f(v.y), hi2f(v.y), lo2f(v.z), hi2f(v.z), lo2f(v.w), hi2f(v.w)};
;   float ss = 0.f;
; #pragma unroll
;   for (int i = 0; i < 8; ++i) ss += x[i] * x[i];
;   for (int o = 1; o < width; o <<= 1) ss += __shfl_xor(ss, o);
;   float rs = rsqrtf(ss * inv_n + 1e-6f) * scale;
;   if (active) {
;     float4 g0 = *(const float4*)g, g1 = *(const float4*)(g + 4);
;     uint4 o;
;     o.x = pack2(x[0] * rs * g0.x, x[1] * rs * g0.y);
;     o.y = pack2(x[2] * rs * g0.z, x[3] * rs * g0.w);
;     o.z = pack2(x[4] * rs * g1.x, x[5] * rs * g1.y);
;     o.w = pack2(x[6] * rs * g1.z, x[7] * rs * g1.w);
;     *(uint4*)ptr = o;
;   }
; }
; template <bool RWONLY>
; __device__ __forceinline__ void phase_prep(const Params p, int l, char* smem) {
;     ...
;     for (int s = lbid() * 4 + w; s < S_; s += gridDim.x * 4) {
;       u16* row = P + (size_t)s * NINP;
;       seg_norm8(row + O_DQ + lane * 8, true, 8, 1.f / 64, dqg + (lane * 8) % 64, 0.125f * LOG2E);
;       seg_norm8(row + O_DK + lane * 8, true, 8, 1.f / 64, dqg + 64 + (lane * 8) % 64, 1.f);
;       seg_norm8(row + O_MQ + lane * 8, true, 16, 1.f / 128, mqg + (lane * 8) % 128, 0.08838834764831845f * LOG2E);
;       seg_norm8(row + O_QL + (lane < 48 ? lane : 0) * 8, lane < 48, 64, 1.f / 384, qlg + (lane < 48 ? lane : 0) * 8, 1.f);
;       seg_norm8(row + O_KVL + (lane < 32 ? lane : 0) * 8, lane < 32, 64, 1.f / 256, kvg + (lane < 32 ? lane : 0) * 8, 1.f);
;     }
	v_lshlrev_b32_e32 v172, 16, v88
	v_and_b32_e32 v173, 0xffff0000, v88
	v_lshlrev_b32_e32 v174, 16, v89
	v_and_b32_e32 v175, 0xffff0000, v89
	v_lshlrev_b32_e32 v176, 16, v90
	v_and_b32_e32 v177, 0xffff0000, v90
	v_lshlrev_b32_e32 v178, 16, v91
	v_and_b32_e32 v179, 0xffff0000, v91
	v_lshlrev_b32_e32 v180, 16, v92
	v_and_b32_e32 v181, 0xffff0000, v92
	v_lshlrev_b32_e32 v182, 16, v93
	v_and_b32_e32 v183, 0xffff0000, v93
	v_lshlrev_b32_e32 v184, 16, v94
	v_and_b32_e32 v185, 0xffff0000, v94
	v_lshlrev_b32_e32 v186, 16, v95
	v_and_b32_e32 v187, 0xffff0000, v95
	v_lshlrev_b32_e32 v188, 16, v96
	v_and_b32_e32 v189, 0xffff0000, v96
	v_lshlrev_b32_e32 v190, 16, v97
	v_and_b32_e32 v191, 0xffff0000, v97
	v_lshlrev_b32_e32 v214, 16, v98
	v_and_b32_e32 v215, 0xffff0000, v98
	v_lshlrev_b32_e32 v216, 16, v99
	v_and_b32_e32 v217, 0xffff0000, v99
	v_lshlrev_b32_e32 v218, 16, v100
	v_and_b32_e32 v219, 0xffff0000, v100
	v_lshlrev_b32_e32 v220, 16, v101
	v_and_b32_e32 v221, 0xffff0000, v101
	v_lshlrev_b32_e32 v222, 16, v102
	v_and_b32_e32 v223, 0xffff0000, v102
	v_lshlrev_b32_e32 v224, 16, v103
	v_and_b32_e32 v225, 0xffff0000, v103
	v_lshlrev_b32_e32 v226, 16, v104
	v_and_b32_e32 v227, 0xffff0000, v104
	v_lshlrev_b32_e32 v228, 16, v105
	v_and_b32_e32 v229, 0xffff0000, v105
	v_lshlrev_b32_e32 v230, 16, v106
	v_and_b32_e32 v231, 0xffff0000, v106
	v_lshlrev_b32_e32 v232, 16, v107
	v_and_b32_e32 v233, 0xffff0000, v107
	v_pk_mul_f32 v[234:235], v[172:173], v[172:173]
	v_pk_mul_f32 v[240:241], v[180:181], v[180:181]
	v_pk_mul_f32 v[242:243], v[188:189], v[188:189]
	v_pk_mul_f32 v[248:249], v[218:219], v[218:219]
	v_pk_mul_f32 v[250:251], v[226:227], v[226:227]
	v_pk_fma_f32 v[234:235], v[174:175], v[174:175], v[234:235]
	v_pk_fma_f32 v[240:241], v[182:183], v[182:183], v[240:241]
	v_pk_fma_f32 v[242:243], v[190:191], v[190:191], v[242:243]
	v_pk_fma_f32 v[248:249], v[220:221], v[220:221], v[248:249]
	v_pk_fma_f32 v[250:251], v[228:229], v[228:229], v[250:251]
	v_pk_fma_f32 v[234:235], v[176:177], v[176:177], v[234:235]
	v_pk_fma_f32 v[240:241], v[184:185], v[184:185], v[240:241]
	v_pk_fma_f32 v[242:243], v[214:215], v[214:215], v[242:243]
	v_pk_fma_f32 v[248:249], v[222:223], v[222:223], v[248:249]
	v_pk_fma_f32 v[250:251], v[230:231], v[230:231], v[250:251]
	v_pk_fma_f32 v[234:235], v[178:179], v[178:179], v[234:235]
	v_pk_fma_f32 v[240:241], v[186:187], v[186:187], v[240:241]
	v_pk_fma_f32 v[242:243], v[216:217], v[216:217], v[242:243]
	v_pk_fma_f32 v[248:249], v[224:225], v[224:225], v[248:249]
	v_pk_fma_f32 v[250:251], v[232:233], v[232:233], v[250:251]
	v_add_f32_e32 v234, v234, v235
	v_add_f32_e32 v240, v240, v241
	v_add_f32_e32 v242, v242, v243
	v_add_f32_e32 v248, v248, v249
	v_add_f32_e32 v250, v250, v251
	v_add_f32_dpp v234, v234, v234 quad_perm:[1,0,3,2] row_mask:0xf bank_mask:0xf bound_ctrl:1
	v_add_f32_dpp v240, v240, v240 quad_perm:[1,0,3,2] row_mask:0xf bank_mask:0xf bound_ctrl:1
	v_add_f32_dpp v242, v242, v242 quad_perm:[1,0,3,2] row_mask:0xf bank_mask:0xf bound_ctrl:1
	v_add_f32_dpp v248, v248, v248 quad_perm:[1,0,3,2] row_mask:0xf bank_mask:0xf bound_ctrl:1
	v_add_f32_dpp v250, v250, v250 quad_perm:[1,0,3,2] row_mask:0xf bank_mask:0xf bound_ctrl:1
	v_add_f32_dpp v234, v234, v234 quad_perm:[2,3,0,1] row_mask:0xf bank_mask:0xf bound_ctrl:1
	v_add_f32_dpp v240, v240, v240 quad_perm:[2,3,0,1] row_mask:0xf bank_mask:0xf bound_ctrl:1
	v_add_f32_dpp v242, v242, v242 quad_perm:[2,3,0,1] row_mask:0xf bank_mask:0xf bound_ctrl:1
	v_add_f32_dpp v248, v248, v248 quad_perm:[2,3,0,1] row_mask:0xf bank_mask:0xf bound_ctrl:1
	v_add_f32_dpp v250, v250, v250 quad_perm:[2,3,0,1] row_mask:0xf bank_mask:0xf bound_ctrl:1
	v_add_f32_dpp v234, v234, v234 row_half_mirror row_mask:0xf bank_mask:0xf bound_ctrl:1
	v_add_f32_dpp v240, v240, v240 row_half_mirror row_mask:0xf bank_mask:0xf bound_ctrl:1
	v_add_f32_dpp v242, v242, v242 row_half_mirror row_mask:0xf bank_mask:0xf bound_ctrl:1
	v_add_f32_dpp v248, v248, v248 row_half_mirror row_mask:0xf bank_mask:0xf bound_ctrl:1
	v_add_f32_dpp v250, v250, v250 row_half_mirror row_mask:0xf bank_mask:0xf bound_ctrl:1
	v_add_f32_dpp v242, v242, v242 row_mirror row_mask:0xf bank_mask:0xf bound_ctrl:1
	v_add_f32_dpp v248, v248, v248 row_mirror row_mask:0xf bank_mask:0xf bound_ctrl:1
	v_add_f32_dpp v250, v250, v250 row_mirror row_mask:0xf bank_mask:0xf bound_ctrl:1
	ds_bpermute_b32 v161, v47, v248
	ds_bpermute_b32 v162, v47, v250
	s_waitcnt lgkmcnt(0)
	v_add_f32_e32 v248, v248, v161
	v_add_f32_e32 v250, v250, v162
	ds_bpermute_b32 v161, v48, v248
	ds_bpermute_b32 v162, v48, v250
	s_waitcnt lgkmcnt(0)
; __device__ __forceinline__ float lo2f(unsigned u) { return __uint_as_float(u << 16); }
; __device__ __forceinline__ float hi2f(unsigned u) { return __uint_as_float(u & 0xffff0000u); }
; __device__ __forceinline__ void seg_norm8(u16* ptr, bool active, int width, float inv_n, const float* g, float scale) {
;   uint4 v = make_uint4(0, 0, 0, 0);
;   if (active) v = *(const uint4*)ptr;
;   float x[8] = {lo2f(v.x), hi2f(v.x), lo2f(v.y), hi2f(v.y), lo2f(v.z), hi2f(v.z), lo2f(v.w), hi2f(v.w)};
;   float ss = 0.f;
; #pragma unroll
;   for (int i = 0; i < 8; ++i) ss += x[i] * x[i];
;   for (int o = 1; o < width; o <<= 1) ss += __shfl_xor(ss, o);
;   float rs = rsqrtf(ss * inv_n + 1e-6f) * scale;
;   if (active) {
;     float4 g0 = *(const float4*)g, g1 = *(const float4*)(g + 4);
;     uint4 o;
;     o.x = pack2(x[0] * rs * g0.x, x[1] * rs * g0.y);
;     o.y = pack2(x[2] * rs * g0.z, x[3] * rs * g0.w);
;     o.z = pack2(x[4] * rs * g1.x, x[5] * rs * g1.y);
;     o.w = pack2(x[6] * rs * g1.z, x[7] * rs * g1.w);
;     *(uint4*)ptr = o;
;   }
; }
; template <bool RWONLY>
; __device__ __forceinline__ void phase_prep(const Params p, int l, char* smem) {
;     ...
;     for (int s = lbid() * 4 + w; s < S_; s += gridDim.x * 4) {
;       u16* row = P + (size_t)s * NINP;
;       seg_norm8(row + O_DQ + lane * 8, true, 8, 1.f / 64, dqg + (lane * 8) % 64, 0.125f * LOG2E);
;       seg_norm8(row + O_DK + lane * 8, true, 8, 1.f / 64, dqg + 64 + (lane * 8) % 64, 1.f);
;       seg_norm8(row + O_MQ + lane * 8, true, 16, 1.f / 128, mqg + (lane * 8) % 128, 0.08838834764831845f * LOG2E);
;       seg_norm8(row + O_QL + (lane < 48 ? lane : 0) * 8, lane < 48, 64, 1.f / 384, qlg + (lane < 48 ? lane : 0) * 8, 1.f);
;       seg_norm8(row + O_KVL + (lane < 32 ? lane : 0) * 8, lane < 32, 64, 1.f / 256, kvg + (lane < 32 ? lane : 0) * 8, 1.f);
;     }
	v_add_f32_e32 v248, v248, v161
	v_add_f32_e32 v250, v250, v162
	v_fmamk_f32 v234, v234, 0x3c800000, v170
	v_fmamk_f32 v240, v240, 0x3c800000, v170
	v_fmamk_f32 v242, v242, 0x3c000000, v170
	v_fmamk_f32 v248, v248, 0x3b2aaaab, v170
	v_fmamk_f32 v250, v250, 0x3b800000, v170
	v_rsq_f32_e32 v234, v234
	v_rsq_f32_e32 v240, v240
	v_rsq_f32_e32 v242, v242
	v_rsq_f32_e32 v248, v248
	v_rsq_f32_e32 v250, v250
	s_nop 0
	v_mul_f32_e32 v234, 0x3e38aa3b, v234
	v_mul_f32_e32 v242, 0x3e0293ee, v242
	v_pk_mul_f32 v[172:173], v[234:235], v[172:173] op_sel_hi:[0,1]
	v_pk_mul_f32 v[174:175], v[234:235], v[174:175] op_sel_hi:[0,1]
	v_pk_mul_f32 v[176:177], v[234:235], v[176:177] op_sel_hi:[0,1]
	v_pk_mul_f32 v[178:179], v[234:235], v[178:179] op_sel_hi:[0,1]
	v_pk_mul_f32 v[172:173], v[124:125], v[172:173]
	v_pk_mul_f32 v[174:175], v[126:127], v[174:175]
	v_pk_mul_f32 v[176:177], v[128:129], v[176:177]
	v_pk_mul_f32 v[178:179], v[130:131], v[178:179]
	v_cvt_pk_bf16_f32 v252, v172, v173
	v_cvt_pk_bf16_f32 v253, v174, v175
	v_cvt_pk_bf16_f32 v254, v176, v177
	v_cvt_pk_bf16_f32 v255, v178, v179
	global_store_dwordx4 v[116:117], v[252:255], off offset:3584
	v_pk_mul_f32 v[180:181], v[240:241], v[180:181] op_sel_hi:[0,1]
	v_pk_mul_f32 v[182:183], v[240:241], v[182:183] op_sel_hi:[0,1]
	v_pk_mul_f32 v[184:185], v[240:241], v[184:185] op_sel_hi:[0,1]
	v_pk_mul_f32 v[186:187], v[240:241], v[186:187] op_sel_hi:[0,1]
	v_pk_mul_f32 v[180:181], v[132:133], v[180:181]
	v_pk_mul_f32 v[182:183], v[134:135], v[182:183]
	v_pk_mul_f32 v[184:185], v[136:137], v[184:185]
	v_pk_mul_f32 v[186:187], v[138:139], v[186:187]
	v_cvt_pk_bf16_f32 v252, v180, v181
	v_cvt_pk_bf16_f32 v253, v182, v183
	v_cvt_pk_bf16_f32 v254, v184, v185
	v_cvt_pk_bf16_f32 v255, v186, v187
	global_store_dwordx4 v[118:119], v[252:255], off offset:512
	v_pk_mul_f32 v[188:189], v[242:243], v[188:189] op_sel_hi:[0,1]
	v_pk_mul_f32 v[190:191], v[242:243], v[190:191] op_sel_hi:[0,1]
	v_pk_mul_f32 v[214:215], v[242:243], v[214:215] op_sel_hi:[0,1]
	v_pk_mul_f32 v[216:217], v[242:243], v[216:217] op_sel_hi:[0,1]
	v_pk_mul_f32 v[188:189], v[140:141], v[188:189]
	v_pk_mul_f32 v[190:191], v[142:143], v[190:191]
	v_pk_mul_f32 v[214:215], v[144:145], v[214:215]
	v_pk_mul_f32 v[216:217], v[146:147], v[216:217]
	v_cvt_pk_bf16_f32 v252, v188, v189
	v_cvt_pk_bf16_f32 v253, v190, v191
	v_cvt_pk_bf16_f32 v254, v214, v215
	v_cvt_pk_bf16_f32 v255, v216, v217
	global_store_dwordx4 v[118:119], v[252:255], off offset:3968
	v_pk_mul_f32 v[218:219], v[248:249], v[218:219] op_sel_hi:[0,1]
	v_pk_mul_f32 v[220:221], v[248:249], v[220:221] op_sel_hi:[0,1]
	v_pk_mul_f32 v[222:223], v[248:249], v[222:223] op_sel_hi:[0,1]
	v_pk_mul_f32 v[224:225], v[248:249], v[224:225] op_sel_hi:[0,1]
	v_pk_mul_f32 v[218:219], v[148:149], v[218:219]
	v_pk_mul_f32 v[220:221], v[150:151], v[220:221]
	v_pk_mul_f32 v[222:223], v[152:153], v[222:223]
	v_pk_mul_f32 v[224:225], v[154:155], v[224:225]
	v_cvt_pk_bf16_f32 v252, v218, v219
	v_cvt_pk_bf16_f32 v253, v220, v221
	v_cvt_pk_bf16_f32 v254, v222, v223
	v_cvt_pk_bf16_f32 v255, v224, v225
	s_and_saveexec_b64 s[22:23], vcc
	global_store_dwordx4 v[120:121], v[252:255], off
	s_mov_b64 exec, s[22:23]
	v_pk_mul_f32 v[226:227], v[250:251], v[226:227] op_sel_hi:[0,1]
	v_pk_mul_f32 v[228:229], v[250:251], v[228:229] op_sel_hi:[0,1]
	v_pk_mul_f32 v[230:231], v[250:251], v[230:231] op_sel_hi:[0,1]
	v_pk_mul_f32 v[232:233], v[250:251], v[232:233] op_sel_hi:[0,1]
	v_pk_mul_f32 v[226:227], v[156:157], v[226:227]
	v_pk_mul_f32 v[228:229], v[158:159], v[228:229]
	v_pk_mul_f32 v[230:231], v[164:165], v[230:231]
	v_pk_mul_f32 v[232:233], v[166:167], v[232:233]
	v_cvt_pk_bf16_f32 v252, v226, v227
	v_cvt_pk_bf16_f32 v253, v228, v229
	v_cvt_pk_bf16_f32 v254, v230, v231
	v_cvt_pk_bf16_f32 v255, v232, v233
	s_and_saveexec_b64 s[22:23], s[38:39]
	global_store_dwordx4 v[122:123], v[252:255], off
	s_mov_b64 exec, s[22:23]
	s_mul_i32 s0, s72, 3
	v_add_u32_e32 v163, s0, v9
	v_mad_i64_i32 v[116:117], s[0:1], v163, s88, v[66:67]
	v_mov_b32_e32 v119, v169
	v_mov_b32_e32 v118, v20
	v_lshl_add_u64 v[120:121], v[116:117], 0, v[118:119]
	v_mov_b32_e32 v118, v22
	v_lshl_add_u64 v[122:123], v[116:117], 0, v[118:119]
	v_mov_b32_e32 v118, v168
	v_lshl_add_u64 v[116:117], v[116:117], 0, v[118:119]
	s_mov_b64 s[0:1], 0x1a00
	v_lshl_add_u64 v[120:121], v[120:121], 0, s[0:1]
	s_mov_b64 s[0:1], 0x1d00
	v_lshl_add_u64 v[122:123], v[122:123], 0, s[0:1]
	s_mov_b64 s[0:1], 0x1000
	v_lshl_add_u64 v[118:119], v[116:117], 0, s[0:1]
	v_mov_b32_e32 v100, 0
	v_mov_b32_e32 v101, 0
	v_mov_b32_e32 v102, 0
	v_mov_b32_e32 v103, 0
	v_mov_b32_e32 v104, 0
	v_mov_b32_e32 v105, 0
	v_mov_b32_e32 v106, 0
	v_mov_b32_e32 v107, 0
	global_load_dwordx4 v[88:91], v[116:117], off offset:3584
	global_load_dwordx4 v[92:95], v[118:119], off offset:512
	global_load_dwordx4 v[96:99], v[118:119], off offset:3968
	s_and_saveexec_b64 s[22:23], vcc
	global_load_dwordx4 v[100:103], v[120:121], off
	s_mov_b64 exec, s[22:23]
	s_and_saveexec_b64 s[22:23], s[38:39]
	global_load_dwordx4 v[104:107], v[122:123], off
	s_mov_b64 exec, s[22:23]
	s_waitcnt vmcnt(10)
; __device__ __forceinline__ float lo2f(unsigned u) { return __uint_as_float(u << 16); }
; __device__ __forceinline__ float hi2f(unsigned u) { return __uint_as_float(u & 0xffff0000u); }
; __device__ __forceinline__ void seg_norm8(u16* ptr, bool active, int width, float inv_n, const float* g, float scale) {
;   uint4 v = make_uint4(0, 0, 0, 0);
;   if (active) v = *(const uint4*)ptr;
;   float x[8] = {lo2f(v.x), hi2f(v.x), lo2f(v.y), hi2f(v.y), lo2f(v.z), hi2f(v.z), lo2f(v.w), hi2f(v.w)};
;   float ss = 0.f;
; #pragma unroll
;   for (int i = 0; i < 8; ++i) ss += x[i] * x[i];
;   for (int o = 1; o < width; o <<= 1) ss += __shfl_xor(ss, o);
;   float rs = rsqrtf(ss * inv_n + 1e-6f) * scale;
;   if (active) {
;     float4 g0 = *(const float4*)g, g1 = *(const float4*)(g + 4);
;     uint4 o;
;     o.x = pack2(x[0] * rs * g0.x, x[1] * rs * g0.y);
;     o.y = pack2(x[2] * rs * g0.z, x[3] * rs * g0.w);
;     o.z = pack2(x[4] * rs * g1.x, x[5] * rs * g1.y);
;     o.w = pack2(x[6] * rs * g1.z, x[7] * rs * g1.w);
;     *(uint4*)ptr = o;
;   }
; }
; template <bool RWONLY>
; __device__ __forceinline__ void phase_prep(const Params p, int l, char* smem) {
;     ...
;     for (int s = lbid() * 4 + w; s < S_; s += gridDim.x * 4) {
;       u16* row = P + (size_t)s * NINP;
;       seg_norm8(row + O_DQ + lane * 8, true, 8, 1.f / 64, dqg + (lane * 8) % 64, 0.125f * LOG2E);
;       seg_norm8(row + O_DK + lane * 8, true, 8, 1.f / 64, dqg + 64 + (lane * 8) % 64, 1.f);
;       seg_norm8(row + O_MQ + lane * 8, true, 16, 1.f / 128, mqg + (lane * 8) % 128, 0.08838834764831845f * LOG2E);
;       seg_norm8(row + O_QL + (lane < 48 ? lane : 0) * 8, lane < 48, 64, 1.f / 384, qlg + (lane < 48 ? lane : 0) * 8, 1.f);
;       seg_norm8(row + O_KVL + (lane < 32 ? lane : 0) * 8, lane < 32, 64, 1.f / 256, kvg + (lane < 32 ? lane : 0) * 8, 1.f);
;     }
	v_lshlrev_b32_e32 v172, 16, v68
	v_and_b32_e32 v173, 0xffff0000, v68
	v_lshlrev_b32_e32 v174, 16, v69
	v_and_b32_e32 v175, 0xffff0000, v69
	v_lshlrev_b32_e32 v176, 16, v70
	v_and_b32_e32 v177, 0xffff0000, v70
	v_lshlrev_b32_e32 v178, 16, v71
	v_and_b32_e32 v179, 0xffff0000, v71
	v_lshlrev_b32_e32 v180, 16, v72
	v_and_b32_e32 v181, 0xffff0000, v72
	v_lshlrev_b32_e32 v182, 16, v73
	v_and_b32_e32 v183, 0xffff0000, v73
	v_lshlrev_b32_e32 v184, 16, v74
	v_and_b32_e32 v185, 0xffff0000, v74
	v_lshlrev_b32_e32 v186, 16, v75
	v_and_b32_e32 v187, 0xffff0000, v75
	v_lshlrev_b32_e32 v188, 16, v76
	v_and_b32_e32 v189, 0xffff0000, v76
	v_lshlrev_b32_e32 v190, 16, v77
	v_and_b32_e32 v191, 0xffff0000, v77
	v_lshlrev_b32_e32 v214, 16, v78
	v_and_b32_e32 v215, 0xffff0000, v78
	v_lshlrev_b32_e32 v216, 16, v79
	v_and_b32_e32 v217, 0xffff0000, v79
	v_lshlrev_b32_e32 v218, 16, v80
	v_and_b32_e32 v219, 0xffff0000, v80
	v_lshlrev_b32_e32 v220, 16, v81
	v_and_b32_e32 v221, 0xffff0000, v81
	v_lshlrev_b32_e32 v222, 16, v82
	v_and_b32_e32 v223, 0xffff0000, v82
	v_lshlrev_b32_e32 v224, 16, v83
	v_and_b32_e32 v225, 0xffff0000, v83
	v_lshlrev_b32_e32 v226, 16, v84
	v_and_b32_e32 v227, 0xffff0000, v84
	v_lshlrev_b32_e32 v228, 16, v85
	v_and_b32_e32 v229, 0xffff0000, v85
	v_lshlrev_b32_e32 v230, 16, v86
	v_and_b32_e32 v231, 0xffff0000, v86
	v_lshlrev_b32_e32 v232, 16, v87
	v_and_b32_e32 v233, 0xffff0000, v87
	v_pk_mul_f32 v[234:235], v[172:173], v[172:173]
	v_pk_mul_f32 v[240:241], v[180:181], v[180:181]
	v_pk_mul_f32 v[242:243], v[188:189], v[188:189]
	v_pk_mul_f32 v[248:249], v[218:219], v[218:219]
	v_pk_mul_f32 v[250:251], v[226:227], v[226:227]
	v_pk_fma_f32 v[234:235], v[174:175], v[174:175], v[234:235]
	v_pk_fma_f32 v[240:241], v[182:183], v[182:183], v[240:241]
	v_pk_fma_f32 v[242:243], v[190:191], v[190:191], v[242:243]
	v_pk_fma_f32 v[248:249], v[220:221], v[220:221], v[248:249]
	v_pk_fma_f32 v[250:251], v[228:229], v[228:229], v[250:251]
	v_pk_fma_f32 v[234:235], v[176:177], v[176:177], v[234:235]
	v_pk_fma_f32 v[240:241], v[184:185], v[184:185], v[240:241]
	v_pk_fma_f32 v[242:243], v[214:215], v[214:215], v[242:243]
	v_pk_fma_f32 v[248:249], v[222:223], v[222:223], v[248:249]
	v_pk_fma_f32 v[250:251], v[230:231], v[230:231], v[250:251]
	v_pk_fma_f32 v[234:235], v[178:179], v[178:179], v[234:235]
	v_pk_fma_f32 v[240:241], v[186:187], v[186:187], v[240:241]
	v_pk_fma_f32 v[242:243], v[216:217], v[216:217], v[242:243]
	v_pk_fma_f32 v[248:249], v[224:225], v[224:225], v[248:249]
	v_pk_fma_f32 v[250:251], v[232:233], v[232:233], v[250:251]
	v_add_f32_e32 v234, v234, v235
	v_add_f32_e32 v240, v240, v241
	v_add_f32_e32 v242, v242, v243
	v_add_f32_e32 v248, v248, v249
	v_add_f32_e32 v250, v250, v251
	v_add_f32_dpp v234, v234, v234 quad_perm:[1,0,3,2] row_mask:0xf bank_mask:0xf bound_ctrl:1
	v_add_f32_dpp v240, v240, v240 quad_perm:[1,0,3,2] row_mask:0xf bank_mask:0xf bound_ctrl:1
	v_add_f32_dpp v242, v242, v242 quad_perm:[1,0,3,2] row_mask:0xf bank_mask:0xf bound_ctrl:1
	v_add_f32_dpp v248, v248, v248 quad_perm:[1,0,3,2] row_mask:0xf bank_mask:0xf bound_ctrl:1
	v_add_f32_dpp v250, v250, v250 quad_perm:[1,0,3,2] row_mask:0xf bank_mask:0xf bound_ctrl:1
	v_add_f32_dpp v234, v234, v234 quad_perm:[2,3,0,1] row_mask:0xf bank_mask:0xf bound_ctrl:1
	v_add_f32_dpp v240, v240, v240 quad_perm:[2,3,0,1] row_mask:0xf bank_mask:0xf bound_ctrl:1
	v_add_f32_dpp v242, v242, v242 quad_perm:[2,3,0,1] row_mask:0xf bank_mask:0xf bound_ctrl:1
	v_add_f32_dpp v248, v248, v248 quad_perm:[2,3,0,1] row_mask:0xf bank_mask:0xf bound_ctrl:1
	v_add_f32_dpp v250, v250, v250 quad_perm:[2,3,0,1] row_mask:0xf bank_mask:0xf bound_ctrl:1
	v_add_f32_dpp v234, v234, v234 row_half_mirror row_mask:0xf bank_mask:0xf bound_ctrl:1
	v_add_f32_dpp v240, v240, v240 row_half_mirror row_mask:0xf bank_mask:0xf bound_ctrl:1
	v_add_f32_dpp v242, v242, v242 row_half_mirror row_mask:0xf bank_mask:0xf bound_ctrl:1
	v_add_f32_dpp v248, v248, v248 row_half_mirror row_mask:0xf bank_mask:0xf bound_ctrl:1
	v_add_f32_dpp v250, v250, v250 row_half_mirror row_mask:0xf bank_mask:0xf bound_ctrl:1
	v_add_f32_dpp v242, v242, v242 row_mirror row_mask:0xf bank_mask:0xf bound_ctrl:1
	v_add_f32_dpp v248, v248, v248 row_mirror row_mask:0xf bank_mask:0xf bound_ctrl:1
	v_add_f32_dpp v250, v250, v250 row_mirror row_mask:0xf bank_mask:0xf bound_ctrl:1
	ds_bpermute_b32 v161, v47, v248
	ds_bpermute_b32 v162, v47, v250
	s_waitcnt lgkmcnt(0)
	v_add_f32_e32 v248, v248, v161
	v_add_f32_e32 v250, v250, v162
	ds_bpermute_b32 v161, v48, v248
	ds_bpermute_b32 v162, v48, v250
	s_waitcnt lgkmcnt(0)
; __device__ __forceinline__ float lo2f(unsigned u) { return __uint_as_float(u << 16); }
; __device__ __forceinline__ float hi2f(unsigned u) { return __uint_as_float(u & 0xffff0000u); }
; __device__ __forceinline__ void seg_norm8(u16* ptr, bool active, int width, float inv_n, const float* g, float scale) {
;   uint4 v = make_uint4(0, 0, 0, 0);
;   if (active) v = *(const uint4*)ptr;
;   float x[8] = {lo2f(v.x), hi2f(v.x), lo2f(v.y), hi2f(v.y), lo2f(v.z), hi2f(v.z), lo2f(v.w), hi2f(v.w)};
;   float ss = 0.f;
; #pragma unroll
;   for (int i = 0; i < 8; ++i) ss += x[i] * x[i];
;   for (int o = 1; o < width; o <<= 1) ss += __shfl_xor(ss, o);
;   float rs = rsqrtf(ss * inv_n + 1e-6f) * scale;
;   if (active) {
;     float4 g0 = *(const float4*)g, g1 = *(const float4*)(g + 4);
;     uint4 o;
;     o.x = pack2(x[0] * rs * g0.x, x[1] * rs * g0.y);
;     o.y = pack2(x[2] * rs * g0.z, x[3] * rs * g0.w);
;     o.z = pack2(x[4] * rs * g1.x, x[5] * rs * g1.y);
;     o.w = pack2(x[6] * rs * g1.z, x[7] * rs * g1.w);
;     *(uint4*)ptr = o;
;   }
; }
; template <bool RWONLY>
; __device__ __forceinline__ void phase_prep(const Params p, int l, char* smem) {
;     ...
;     for (int s = lbid() * 4 + w; s < S_; s += gridDim.x * 4) {
;       u16* row = P + (size_t)s * NINP;
;       seg_norm8(row + O_DQ + lane * 8, true, 8, 1.f / 64, dqg + (lane * 8) % 64, 0.125f * LOG2E);
;       seg_norm8(row + O_DK + lane * 8, true, 8, 1.f / 64, dqg + 64 + (lane * 8) % 64, 1.f);
;       seg_norm8(row + O_MQ + lane * 8, true, 16, 1.f / 128, mqg + (lane * 8) % 128, 0.08838834764831845f * LOG2E);
;       seg_norm8(row + O_QL + (lane < 48 ? lane : 0) * 8, lane < 48, 64, 1.f / 384, qlg + (lane < 48 ? lane : 0) * 8, 1.f);
;       seg_norm8(row + O_KVL + (lane < 32 ? lane : 0) * 8, lane < 32, 64, 1.f / 256, kvg + (lane < 32 ? lane : 0) * 8, 1.f);
;     }
	v_add_f32_e32 v248, v248, v161
	v_add_f32_e32 v250, v250, v162
	v_fmamk_f32 v234, v234, 0x3c800000, v170
	v_fmamk_f32 v240, v240, 0x3c800000, v170
	v_fmamk_f32 v242, v242, 0x3c000000, v170
	v_fmamk_f32 v248, v248, 0x3b2aaaab, v170
	v_fmamk_f32 v250, v250, 0x3b800000, v170
	v_rsq_f32_e32 v234, v234
	v_rsq_f32_e32 v240, v240
	v_rsq_f32_e32 v242, v242
	v_rsq_f32_e32 v248, v248
	v_rsq_f32_e32 v250, v250
	s_nop 0
	v_mul_f32_e32 v234, 0x3e38aa3b, v234
	v_mul_f32_e32 v242, 0x3e0293ee, v242
	v_pk_mul_f32 v[172:173], v[234:235], v[172:173] op_sel_hi:[0,1]
	v_pk_mul_f32 v[174:175], v[234:235], v[174:175] op_sel_hi:[0,1]
	v_pk_mul_f32 v[176:177], v[234:235], v[176:177] op_sel_hi:[0,1]
	v_pk_mul_f32 v[178:179], v[234:235], v[178:179] op_sel_hi:[0,1]
	v_pk_mul_f32 v[172:173], v[124:125], v[172:173]
	v_pk_mul_f32 v[174:175], v[126:127], v[174:175]
	v_pk_mul_f32 v[176:177], v[128:129], v[176:177]
	v_pk_mul_f32 v[178:179], v[130:131], v[178:179]
	v_cvt_pk_bf16_f32 v252, v172, v173
	v_cvt_pk_bf16_f32 v253, v174, v175
	v_cvt_pk_bf16_f32 v254, v176, v177
	v_cvt_pk_bf16_f32 v255, v178, v179
	global_store_dwordx4 v[108:109], v[252:255], off offset:3584
	v_pk_mul_f32 v[180:181], v[240:241], v[180:181] op_sel_hi:[0,1]
	v_pk_mul_f32 v[182:183], v[240:241], v[182:183] op_sel_hi:[0,1]
	v_pk_mul_f32 v[184:185], v[240:241], v[184:185] op_sel_hi:[0,1]
	v_pk_mul_f32 v[186:187], v[240:241], v[186:187] op_sel_hi:[0,1]
	v_pk_mul_f32 v[180:181], v[132:133], v[180:181]
	v_pk_mul_f32 v[182:183], v[134:135], v[182:183]
	v_pk_mul_f32 v[184:185], v[136:137], v[184:185]
	v_pk_mul_f32 v[186:187], v[138:139], v[186:187]
	v_cvt_pk_bf16_f32 v252, v180, v181
	v_cvt_pk_bf16_f32 v253, v182, v183
	v_cvt_pk_bf16_f32 v254, v184, v185
	v_cvt_pk_bf16_f32 v255, v186, v187
	global_store_dwordx4 v[110:111], v[252:255], off offset:512
	v_pk_mul_f32 v[188:189], v[242:243], v[188:189] op_sel_hi:[0,1]
	v_pk_mul_f32 v[190:191], v[242:243], v[190:191] op_sel_hi:[0,1]
	v_pk_mul_f32 v[214:215], v[242:243], v[214:215] op_sel_hi:[0,1]
	v_pk_mul_f32 v[216:217], v[242:243], v[216:217] op_sel_hi:[0,1]
	v_pk_mul_f32 v[188:189], v[140:141], v[188:189]
	v_pk_mul_f32 v[190:191], v[142:143], v[190:191]
	v_pk_mul_f32 v[214:215], v[144:145], v[214:215]
	v_pk_mul_f32 v[216:217], v[146:147], v[216:217]
	v_cvt_pk_bf16_f32 v252, v188, v189
	v_cvt_pk_bf16_f32 v253, v190, v191
	v_cvt_pk_bf16_f32 v254, v214, v215
	v_cvt_pk_bf16_f32 v255, v216, v217
	global_store_dwordx4 v[110:111], v[252:255], off offset:3968
	v_pk_mul_f32 v[218:219], v[248:249], v[218:219] op_sel_hi:[0,1]
	v_pk_mul_f32 v[220:221], v[248:249], v[220:221] op_sel_hi:[0,1]
	v_pk_mul_f32 v[222:223], v[248:249], v[222:223] op_sel_hi:[0,1]
	v_pk_mul_f32 v[224:225], v[248:249], v[224:225] op_sel_hi:[0,1]
	v_pk_mul_f32 v[218:219], v[148:149], v[218:219]
	v_pk_mul_f32 v[220:221], v[150:151], v[220:221]
	v_pk_mul_f32 v[222:223], v[152:153], v[222:223]
	v_pk_mul_f32 v[224:225], v[154:155], v[224:225]
	v_cvt_pk_bf16_f32 v252, v218, v219
	v_cvt_pk_bf16_f32 v253, v220, v221
	v_cvt_pk_bf16_f32 v254, v222, v223
	v_cvt_pk_bf16_f32 v255, v224, v225
	s_and_saveexec_b64 s[22:23], vcc
	global_store_dwordx4 v[112:113], v[252:255], off
	s_mov_b64 exec, s[22:23]
	v_pk_mul_f32 v[226:227], v[250:251], v[226:227] op_sel_hi:[0,1]
	v_pk_mul_f32 v[228:229], v[250:251], v[228:229] op_sel_hi:[0,1]
	v_pk_mul_f32 v[230:231], v[250:251], v[230:231] op_sel_hi:[0,1]
	v_pk_mul_f32 v[232:233], v[250:251], v[232:233] op_sel_hi:[0,1]
	v_pk_mul_f32 v[226:227], v[156:157], v[226:227]
	v_pk_mul_f32 v[228:229], v[158:159], v[228:229]
	v_pk_mul_f32 v[230:231], v[164:165], v[230:231]
	v_pk_mul_f32 v[232:233], v[166:167], v[232:233]
	v_cvt_pk_bf16_f32 v252, v226, v227
	v_cvt_pk_bf16_f32 v253, v228, v229
	v_cvt_pk_bf16_f32 v254, v230, v231
	v_cvt_pk_bf16_f32 v255, v232, v233
	s_and_saveexec_b64 s[22:23], s[38:39]
	global_store_dwordx4 v[114:115], v[252:255], off
	s_mov_b64 exec, s[22:23]
	s_waitcnt vmcnt(5)
	v_lshlrev_b32_e32 v172, 16, v88
	v_and_b32_e32 v173, 0xffff0000, v88
	v_lshlrev_b32_e32 v174, 16, v89
	v_and_b32_e32 v175, 0xffff0000, v89
	v_lshlrev_b32_e32 v176, 16, v90
	v_and_b32_e32 v177, 0xffff0000, v90
	v_lshlrev_b32_e32 v178, 16, v91
	v_and_b32_e32 v179, 0xffff0000, v91
	v_lshlrev_b32_e32 v180, 16, v92
	v_and_b32_e32 v181, 0xffff0000, v92
	v_lshlrev_b32_e32 v182, 16, v93
	v_and_b32_e32 v183, 0xffff0000, v93
	v_lshlrev_b32_e32 v184, 16, v94
	v_and_b32_e32 v185, 0xffff0000, v94
	v_lshlrev_b32_e32 v186, 16, v95
	v_and_b32_e32 v187, 0xffff0000, v95
	v_lshlrev_b32_e32 v188, 16, v96
	v_and_b32_e32 v189, 0xffff0000, v96
	v_lshlrev_b32_e32 v190, 16, v97
	v_and_b32_e32 v191, 0xffff0000, v97
	v_lshlrev_b32_e32 v214, 16, v98
	v_and_b32_e32 v215, 0xffff0000, v98
	v_lshlrev_b32_e32 v216, 16, v99
	v_and_b32_e32 v217, 0xffff0000, v99
	v_lshlrev_b32_e32 v218, 16, v100
	v_and_b32_e32 v219, 0xffff0000, v100
	v_lshlrev_b32_e32 v220, 16, v101
	v_and_b32_e32 v221, 0xffff0000, v101
	v_lshlrev_b32_e32 v222, 16, v102
	v_and_b32_e32 v223, 0xffff0000, v102
	v_lshlrev_b32_e32 v224, 16, v103
	v_and_b32_e32 v225, 0xffff0000, v103
	v_lshlrev_b32_e32 v226, 16, v104
	v_and_b32_e32 v227, 0xffff0000, v104
	v_lshlrev_b32_e32 v228, 16, v105
	v_and_b32_e32 v229, 0xffff0000, v105
	v_lshlrev_b32_e32 v230, 16, v106
	v_and_b32_e32 v231, 0xffff0000, v106
	v_lshlrev_b32_e32 v232, 16, v107
	v_and_b32_e32 v233, 0xffff0000, v107
	v_pk_mul_f32 v[234:235], v[172:173], v[172:173]
	v_pk_mul_f32 v[240:241], v[180:181], v[180:181]
	v_pk_mul_f32 v[242:243], v[188:189], v[188:189]
	v_pk_mul_f32 v[248:249], v[218:219], v[218:219]
	v_pk_mul_f32 v[250:251], v[226:227], v[226:227]
	v_pk_fma_f32 v[234:235], v[174:175], v[174:175], v[234:235]
; __device__ __forceinline__ float lo2f(unsigned u) { return __uint_as_float(u << 16); }
; __device__ __forceinline__ float hi2f(unsigned u) { return __uint_as_float(u & 0xffff0000u); }
; __device__ __forceinline__ void seg_norm8(u16* ptr, bool active, int width, float inv_n, const float* g, float scale) {
;   uint4 v = make_uint4(0, 0, 0, 0);
;   if (active) v = *(const uint4*)ptr;
;   float x[8] = {lo2f(v.x), hi2f(v.x), lo2f(v.y), hi2f(v.y), lo2f(v.z), hi2f(v.z), lo2f(v.w), hi2f(v.w)};
;   float ss = 0.f;
; #pragma unroll
;   for (int i = 0; i < 8; ++i) ss += x[i] * x[i];
;   for (int o = 1; o < width; o <<= 1) ss += __shfl_xor(ss, o);
;   float rs = rsqrtf(ss * inv_n + 1e-6f) * scale;
;   if (active) {
;     float4 g0 = *(const float4*)g, g1 = *(const float4*)(g + 4);
;     uint4 o;
;     o.x = pack2(x[0] * rs * g0.x, x[1] * rs * g0.y);
;     o.y = pack2(x[2] * rs * g0.z, x[3] * rs * g0.w);
;     o.z = pack2(x[4] * rs * g1.x, x[5] * rs * g1.y);
;     o.w = pack2(x[6] * rs * g1.z, x[7] * rs * g1.w);
;     *(uint4*)ptr = o;
;   }
; }
; template <bool RWONLY>
; __device__ __forceinline__ void phase_prep(const Params p, int l, char* smem) {
;     ...
;     for (int s = lbid() * 4 + w; s < S_; s += gridDim.x * 4) {
;       u16* row = P + (size_t)s * NINP;
;       seg_norm8(row + O_DQ + lane * 8, true, 8, 1.f / 64, dqg + (lane * 8) % 64, 0.125f * LOG2E);
;       seg_norm8(row + O_DK + lane * 8, true, 8, 1.f / 64, dqg + 64 + (lane * 8) % 64, 1.f);
;       seg_norm8(row + O_MQ + lane * 8, true, 16, 1.f / 128, mqg + (lane * 8) % 128, 0.08838834764831845f * LOG2E);
;       seg_norm8(row + O_QL + (lane < 48 ? lane : 0) * 8, lane < 48, 64, 1.f / 384, qlg + (lane < 48 ? lane : 0) * 8, 1.f);
;       seg_norm8(row + O_KVL + (lane < 32 ? lane : 0) * 8, lane < 32, 64, 1.f / 256, kvg + (lane < 32 ? lane : 0) * 8, 1.f);
;     }
	v_pk_fma_f32 v[240:241], v[182:183], v[182:183], v[240:241]
	v_pk_fma_f32 v[242:243], v[190:191], v[190:191], v[242:243]
	v_pk_fma_f32 v[248:249], v[220:221], v[220:221], v[248:249]
	v_pk_fma_f32 v[250:251], v[228:229], v[228:229], v[250:251]
	v_pk_fma_f32 v[234:235], v[176:177], v[176:177], v[234:235]
	v_pk_fma_f32 v[240:241], v[184:185], v[184:185], v[240:241]
	v_pk_fma_f32 v[242:243], v[214:215], v[214:215], v[242:243]
	v_pk_fma_f32 v[248:249], v[222:223], v[222:223], v[248:249]
	v_pk_fma_f32 v[250:251], v[230:231], v[230:231], v[250:251]
	v_pk_fma_f32 v[234:235], v[178:179], v[178:179], v[234:235]
	v_pk_fma_f32 v[240:241], v[186:187], v[186:187], v[240:241]
	v_pk_fma_f32 v[242:243], v[216:217], v[216:217], v[242:243]
	v_pk_fma_f32 v[248:249], v[224:225], v[224:225], v[248:249]
	v_pk_fma_f32 v[250:251], v[232:233], v[232:233], v[250:251]
	v_add_f32_e32 v234, v234, v235
	v_add_f32_e32 v240, v240, v241
	v_add_f32_e32 v242, v242, v243
	v_add_f32_e32 v248, v248, v249
	v_add_f32_e32 v250, v250, v251
	v_add_f32_dpp v234, v234, v234 quad_perm:[1,0,3,2] row_mask:0xf bank_mask:0xf bound_ctrl:1
	v_add_f32_dpp v240, v240, v240 quad_perm:[1,0,3,2] row_mask:0xf bank_mask:0xf bound_ctrl:1
	v_add_f32_dpp v242, v242, v242 quad_perm:[1,0,3,2] row_mask:0xf bank_mask:0xf bound_ctrl:1
	v_add_f32_dpp v248, v248, v248 quad_perm:[1,0,3,2] row_mask:0xf bank_mask:0xf bound_ctrl:1
	v_add_f32_dpp v250, v250, v250 quad_perm:[1,0,3,2] row_mask:0xf bank_mask:0xf bound_ctrl:1
	v_add_f32_dpp v234, v234, v234 quad_perm:[2,3,0,1] row_mask:0xf bank_mask:0xf bound_ctrl:1
	v_add_f32_dpp v240, v240, v240 quad_perm:[2,3,0,1] row_mask:0xf bank_mask:0xf bound_ctrl:1
	v_add_f32_dpp v242, v242, v242 quad_perm:[2,3,0,1] row_mask:0xf bank_mask:0xf bound_ctrl:1
	v_add_f32_dpp v248, v248, v248 quad_perm:[2,3,0,1] row_mask:0xf bank_mask:0xf bound_ctrl:1
	v_add_f32_dpp v250, v250, v250 quad_perm:[2,3,0,1] row_mask:0xf bank_mask:0xf bound_ctrl:1
	v_add_f32_dpp v234, v234, v234 row_half_mirror row_mask:0xf bank_mask:0xf bound_ctrl:1
	v_add_f32_dpp v240, v240, v240 row_half_mirror row_mask:0xf bank_mask:0xf bound_ctrl:1
	v_add_f32_dpp v242, v242, v242 row_half_mirror row_mask:0xf bank_mask:0xf bound_ctrl:1
	v_add_f32_dpp v248, v248, v248 row_half_mirror row_mask:0xf bank_mask:0xf bound_ctrl:1
	v_add_f32_dpp v250, v250, v250 row_half_mirror row_mask:0xf bank_mask:0xf bound_ctrl:1
	v_add_f32_dpp v242, v242, v242 row_mirror row_mask:0xf bank_mask:0xf bound_ctrl:1
	v_add_f32_dpp v248, v248, v248 row_mirror row_mask:0xf bank_mask:0xf bound_ctrl:1
	v_add_f32_dpp v250, v250, v250 row_mirror row_mask:0xf bank_mask:0xf bound_ctrl:1
	ds_bpermute_b32 v161, v47, v248
	ds_bpermute_b32 v162, v47, v250
	s_waitcnt lgkmcnt(0)
	v_add_f32_e32 v248, v248, v161
	v_add_f32_e32 v250, v250, v162
	ds_bpermute_b32 v161, v48, v248
	ds_bpermute_b32 v162, v48, v250
	s_waitcnt lgkmcnt(0)
	v_add_f32_e32 v248, v248, v161
	v_add_f32_e32 v250, v250, v162
	v_fmamk_f32 v234, v234, 0x3c800000, v170
	v_fmamk_f32 v240, v240, 0x3c800000, v170
	v_fmamk_f32 v242, v242, 0x3c000000, v170
	v_fmamk_f32 v248, v248, 0x3b2aaaab, v170
	v_fmamk_f32 v250, v250, 0x3b800000, v170
	v_rsq_f32_e32 v234, v234
	v_rsq_f32_e32 v240, v240
	v_rsq_f32_e32 v242, v242
	v_rsq_f32_e32 v248, v248
	v_rsq_f32_e32 v250, v250
	s_nop 0
	v_mul_f32_e32 v234, 0x3e38aa3b, v234
	v_mul_f32_e32 v242, 0x3e0293ee, v242
	v_pk_mul_f32 v[172:173], v[234:235], v[172:173] op_sel_hi:[0,1]
	v_pk_mul_f32 v[174:175], v[234:235], v[174:175] op_sel_hi:[0,1]
	v_pk_mul_f32 v[176:177], v[234:235], v[176:177] op_sel_hi:[0,1]
	v_pk_mul_f32 v[178:179], v[234:235], v[178:179] op_sel_hi:[0,1]
	v_pk_mul_f32 v[172:173], v[124:125], v[172:173]
	v_pk_mul_f32 v[174:175], v[126:127], v[174:175]
	v_pk_mul_f32 v[176:177], v[128:129], v[176:177]
	v_pk_mul_f32 v[178:179], v[130:131], v[178:179]
	v_cvt_pk_bf16_f32 v252, v172, v173
	v_cvt_pk_bf16_f32 v253, v174, v175
	v_cvt_pk_bf16_f32 v254, v176, v177
	v_cvt_pk_bf16_f32 v255, v178, v179
	global_store_dwordx4 v[116:117], v[252:255], off offset:3584
	v_pk_mul_f32 v[180:181], v[240:241], v[180:181] op_sel_hi:[0,1]
	v_pk_mul_f32 v[182:183], v[240:241], v[182:183] op_sel_hi:[0,1]
	v_pk_mul_f32 v[184:185], v[240:241], v[184:185] op_sel_hi:[0,1]
	v_pk_mul_f32 v[186:187], v[240:241], v[186:187] op_sel_hi:[0,1]
	v_pk_mul_f32 v[180:181], v[132:133], v[180:181]
	v_pk_mul_f32 v[182:183], v[134:135], v[182:183]
	v_pk_mul_f32 v[184:185], v[136:137], v[184:185]
	v_pk_mul_f32 v[186:187], v[138:139], v[186:187]
	v_cvt_pk_bf16_f32 v252, v180, v181
	v_cvt_pk_bf16_f32 v253, v182, v183
	v_cvt_pk_bf16_f32 v254, v184, v185
	v_cvt_pk_bf16_f32 v255, v186, v187
	global_store_dwordx4 v[118:119], v[252:255], off offset:512
	v_pk_mul_f32 v[188:189], v[242:243], v[188:189] op_sel_hi:[0,1]
	v_pk_mul_f32 v[190:191], v[242:243], v[190:191] op_sel_hi:[0,1]
	v_pk_mul_f32 v[214:215], v[242:243], v[214:215] op_sel_hi:[0,1]
	v_pk_mul_f32 v[216:217], v[242:243], v[216:217] op_sel_hi:[0,1]
	v_pk_mul_f32 v[188:189], v[140:141], v[188:189]
	v_pk_mul_f32 v[190:191], v[142:143], v[190:191]
	v_pk_mul_f32 v[214:215], v[144:145], v[214:215]
	v_pk_mul_f32 v[216:217], v[146:147], v[216:217]
	v_cvt_pk_bf16_f32 v252, v188, v189
	v_cvt_pk_bf16_f32 v253, v190, v191
	v_cvt_pk_bf16_f32 v254, v214, v215
	v_cvt_pk_bf16_f32 v255, v216, v217
	global_store_dwordx4 v[118:119], v[252:255], off offset:3968
	v_pk_mul_f32 v[218:219], v[248:249], v[218:219] op_sel_hi:[0,1]
	v_pk_mul_f32 v[220:221], v[248:249], v[220:221] op_sel_hi:[0,1]
	v_pk_mul_f32 v[222:223], v[248:249], v[222:223] op_sel_hi:[0,1]
	v_pk_mul_f32 v[224:225], v[248:249], v[224:225] op_sel_hi:[0,1]
	v_pk_mul_f32 v[218:219], v[148:149], v[218:219]
	v_pk_mul_f32 v[220:221], v[150:151], v[220:221]
	v_pk_mul_f32 v[222:223], v[152:153], v[222:223]
	v_pk_mul_f32 v[224:225], v[154:155], v[224:225]
	v_cvt_pk_bf16_f32 v252, v218, v219
	v_cvt_pk_bf16_f32 v253, v220, v221
	v_cvt_pk_bf16_f32 v254, v222, v223
	v_cvt_pk_bf16_f32 v255, v224, v225
	s_and_saveexec_b64 s[22:23], vcc
	global_store_dwordx4 v[120:121], v[252:255], off
	s_mov_b64 exec, s[22:23]
	v_pk_mul_f32 v[226:227], v[250:251], v[226:227] op_sel_hi:[0,1]
	v_pk_mul_f32 v[228:229], v[250:251], v[228:229] op_sel_hi:[0,1]
	v_pk_mul_f32 v[230:231], v[250:251], v[230:231] op_sel_hi:[0,1]
	v_pk_mul_f32 v[232:233], v[250:251], v[232:233] op_sel_hi:[0,1]
	v_pk_mul_f32 v[226:227], v[156:157], v[226:227]
	v_pk_mul_f32 v[228:229], v[158:159], v[228:229]
	v_pk_mul_f32 v[230:231], v[164:165], v[230:231]
	v_pk_mul_f32 v[232:233], v[166:167], v[232:233]
	v_cvt_pk_bf16_f32 v252, v226, v227
	v_cvt_pk_bf16_f32 v253, v228, v229
	v_cvt_pk_bf16_f32 v254, v230, v231
	v_cvt_pk_bf16_f32 v255, v232, v233
	s_and_saveexec_b64 s[22:23], s[38:39]
	global_store_dwordx4 v[122:123], v[252:255], off
	s_mov_b64 exec, s[22:23]
	s_branch .LBB0_326
.Ltramp_705:
	s_endpgm
.Ltramp_10:
	s_branch .LBB0_10
.LBB0_317:
	s_or_b64 exec, exec, s[22:23]
	v_add_u32_e32 v9, s72, v9
	v_cmp_lt_i32_e64 s[0:1], s54, v9
	s_or_b64 s[20:21], s[0:1], s[20:21]
	s_andn2_b64 exec, exec, s[20:21]
	s_cbranch_execz .LBB0_326
